# v70 + V tiles staged with natural key order inside each 16-key group so P fragments feed P.V MFMAs without permlane32 swaps (8 permlanes + 2 nops fewer per tile)
# speedup vs baseline: 1.0684x; 1.0053x over previous
; DI float bf2f(unsigned short h) { return __uint_as_float((unsigned)h << 16); }
; template <int DQK, int MODE, int LDQ, int LDK, int LDV> ...
;     ...
;     int kgo[NKP], vgo[2];
; #pragma unroll
;     for (int i = 0; i < NKP; ++i) { const int L = (wid + 8 * i) * 64 + lane, row = L / CPR, slot = L % CPR, cc = (slot & ~7) | ((slot & 7) ^ ((row >> 1) & 7)); kgo[i] = row * LDK + cc * 8; }
; #pragma unroll
;     for (int i = 0; i < 2; ++i) { const int L = (2 * wid + i) * 64 + lane, st = L >> 5, w5 = L & 31, kk = (st >> 2) * 8 + (w5 >> 2), c = (st & 3) * 32 + (w5 & 3) * 8;
;         const int k = (kk & ~0xC) | ((kk & 4) << 1) | ((kk & 8) >> 1); vgo[i] = k * LDV + c; }
;     ...
;     ATT_DMA_K(0); ATT_DMA_K(1); ATT_DMA_V(0, 0); ATT_DMA_K(2); ATT_DMA_V(1, 1);
;     bf16x8 qr[ND0];
;     { const bf16_t* Qw = Qb + (size_t)(wid * 32 + r32) * LDQ + hi * 8;
; #pragma unroll
;       for (int d0 = 0; d0 < ND0; ++d0) qr[d0] = *(const bf16x8*)(Qw + d0 * 16);
;       if constexpr (MODE == 0) {
;           float ss = 0.f;
; #pragma unroll
;           for (int d0 = 0; d0 < ND0; ++d0)
; #pragma unroll
;               for (int j = 0; j < 8; ++j) { const float f = bf2f((unsigned short)qr[d0][j]); ss += f * f; }
;           ss = swap_sum(ss);
;           const float rstd = rsqrtf(ss * (1.f / DQK) + EPS) * C;
; #pragma unroll
;           for (int d0 = 0; d0 < ND0; ++d0) { const float* g = gq + d0 * 16 + hi * 8;
;               { float f[8]; _Pragma("unroll") for (int j = 0; j < 8; ++j) f[j] = bf2f((unsigned short)qr[d0][j]) * rstd * g[j];
;                 u32x4 w = {cvtpk(f[0], f[1]), cvtpk(f[2], f[3]), cvtpk(f[4], f[5]), cvtpk(f[6], f[7])}; qr[d0] = __builtin_bit_cast(bf16x8, w); asm volatile("" ::: "memory"); } }
;       } }
;     const int qlo = q0 + wid * 32, qpos = qlo + r32;
;     const int tL = MODE == 0 ? 0 : (qlo >= 191 ? (qlo - 127) >> 6 : 0), tR = MODE == 0 ? NT : min(NT, (qlo + 222) >> 6);
;     float fL = 1.f, fR = 1.f; if constexpr (MODE != 0) { fL = __builtin_amdgcn_exp2f(bt[0]); fR = __builtin_amdgcn_exp2f(-bt[448]); }
;     ...
;     const int vbase = (int)(unsigned)(size_t)lds + V_OFF + v_rd_base(lane);
;     ...
;     constexpr int NDA = ND0 > 6 ? 6 : ND0;
;     ...
;     f32x16 pA, pB; bf16x8 pa0, pa1;
;     int v0 = 0, v1 = 1, v2 = 2;
;     ATT_TOP(NKP + 2);
;     { bf16x8 kf[NDA]; k_reads<DQK, 0, NDA>(kf, lds, 0, r32, hi); ATT_LGKM0(); qk_mma<0, NDA>(pA, kf, qr);
.LBB0_1915:
	s_or_b64 exec, exec, s[2:3]
	s_lshl_b64 s[0:1], s[40:41], 12
	s_add_u32 s0, s14, s0
	s_addc_u32 s1, s15, s1
	s_lshl_b32 s4, s86, 8
	s_add_u32 s44, s0, s4
	s_addc_u32 s45, s1, 0
	s_lshl_b64 s[2:3], s[42:43], 24
	s_add_u32 s0, s14, s2
	s_addc_u32 s1, s15, s3
	s_add_u32 s46, s0, s4
	s_addc_u32 s47, s1, 0
	s_add_u32 s48, s46, 0x800
	s_waitcnt lgkmcnt(0)
	s_barrier
	s_addc_u32 s49, s47, 0
	v_mbcnt_lo_u32_b32 v7, -1, 0
	v_mbcnt_hi_u32_b32 v7, -1, v7
	s_add_u32 s56, s46, 0xc00
	v_add_u32_e32 v0, s33, v7
	s_addc_u32 s57, s47, 0
	v_readfirstlane_b32 s0, v0
	s_ashr_i32 s4, s0, 31
	s_ashr_i32 s1, s0, 6
	v_mov_b32_e32 v1, s0
	v_bfi_b32 v1, s63, v1, v7
	s_lshr_b32 s4, s4, 29
	v_add_u32_e32 v3, s4, v1
	s_lshl_b32 s4, s1, 7
	v_ashrrev_i32_e32 v9, 3, v3
	v_and_b32_e32 v3, 0x1ffffff8, v3
	s_ashr_i32 s4, s4, 4
	v_bfe_u32 v4, v0, 2, 2
	v_lshrrev_b32_e32 v0, 2, v0
	v_sub_u32_e32 v1, v1, v3
	v_lshrrev_b32_e32 v3, 1, v9
	v_lshlrev_b32_e32 v18, 3, v7
	s_and_b32 s6, s4, -16
	v_and_b32_e32 v6, 4, v0
	s_lshr_b32 s4, s4, 0
	v_bitop3_b32 v1, v3, v1, 7 bitop3:0x6c
	v_and_b32_e32 v3, 32, v7
	v_and_b32_e32 v5, 24, v18
	s_and_b32 s7, s4, 8
	v_or3_b32 v0, v6, v4, s6
	v_or_b32_e32 v10, v3, v5
	v_or_b32_e32 v0, s7, v0
	v_lshl_or_b32 v96, v0, 11, v10
	v_lshlrev_b32_e32 v0, 11, v9
	v_lshl_add_u32 v0, v1, 3, v0
	v_ashrrev_i32_e32 v1, 31, v0
	v_lshlrev_b64 v[10:11], 1, v[0:1]
	v_lshl_add_u64 v[12:13], s[46:47], 0, v[10:11]
	s_mov_b64 s[4:5], 0x800
	v_lshl_add_u64 v[12:13], v[12:13], 0, s[4:5]
	s_lshl_b32 s4, s1, 10
	s_add_i32 s59, s4, 0
	s_mov_b32 m0, s59
	v_lshl_add_u64 v[10:11], s[48:49], 0, v[10:11]
	global_load_lds_dwordx4 v[12:13], off
	v_lshl_add_u64 v[12:13], v[10:11], 0, s[8:9]
	s_add_i32 m0, s59, 0x2000
	s_lshl_b32 s4, s1, 11
	v_ashrrev_i32_e32 v97, 31, v96
	global_load_lds_dwordx4 v[12:13], off
	s_add_i32 s22, s4, 0
	v_lshlrev_b64 v[12:13], 1, v[96:97]
	s_add_i32 s95, s22, 0x18000
	v_lshl_add_u64 v[14:15], s[46:47], 0, v[12:13]
	v_lshl_add_u64 v[16:17], v[14:15], 0, s[96:97]
	s_mov_b32 m0, s95
	s_mov_b64 s[4:5], 0xc80
	global_load_lds_dwordx4 v[16:17], off
	v_lshl_add_u64 v[14:15], v[14:15], 0, s[4:5]
	s_add_i32 m0, s22, 0x18400
	s_mov_b64 s[4:5], 0x80000
	global_load_lds_dwordx4 v[14:15], off
	s_add_i32 m0, s59, 0x4000
	s_add_u32 s52, s46, 0x40c00
	v_or_b32_e32 v98, 64, v96
	v_lshl_add_u64 v[10:11], v[10:11], 0, s[4:5]
	s_addc_u32 s53, s47, 0
	v_ashrrev_i32_e32 v99, 31, v98
	global_load_lds_dwordx4 v[10:11], off
	s_add_i32 m0, s22, 0x1c000
	v_lshl_add_u64 v[10:11], s[52:53], 0, v[12:13]
	v_and_b32_e32 v2, 31, v7
	global_load_lds_dwordx4 v[10:11], off
	v_lshl_add_u64 v[10:11], v[98:99], 1, s[52:53]
	s_add_i32 m0, s22, 0x1c400
	s_lshl_b32 s94, s1, 5
	global_load_lds_dwordx4 v[10:11], off
	v_or_b32_e32 v10, s94, v2
	v_ashrrev_i32_e32 v11, 31, v10
	v_bfe_u32 v8, v7, 5, 1
	v_lshlrev_b64 v[10:11], 12, v[10:11]
	v_lshl_add_u64 v[10:11], s[44:45], 0, v[10:11]
	v_lshlrev_b32_e32 v130, 4, v8
	v_lshl_add_u64 v[10:11], v[10:11], 0, v[130:131]
	global_load_dwordx4 v[92:95], v[10:11], off offset:1024
	global_load_dwordx4 v[88:91], v[10:11], off offset:1056
	global_load_dwordx4 v[84:87], v[10:11], off offset:1088
	global_load_dwordx4 v[80:83], v[10:11], off offset:1120
	s_add_i32 s4, s94, s89
	s_add_i32 s5, s4, 0xffffff81
	s_ashr_i32 s5, s5, 6
	s_cmpk_gt_i32 s4, 0xbe
	s_cselect_b32 s55, s5, 0
	s_add_i32 s88, 0, 0x24800
	v_and_b32_e32 v11, 0x70, v18
	v_mov_b32_e32 v9, s88
	v_mov_b32_e32 v10, s81
	v_lshl_add_u32 v114, v2, 7, 0
	v_bitop3_b32 v115, v130, v18, s64 bitop3:0x78
	v_bitop3_b32 v117, v130, v11, 64 bitop3:0x36
	ds_read_b32 v9, v9
	ds_read_b32 v10, v10
	s_waitcnt vmcnt(3)
	s_barrier
	v_add_u32_e32 v107, v114, v115
	v_bitop3_b32 v116, v130, v11, 32 bitop3:0x36
	v_add_u32_e32 v109, v114, v117
	v_bitop3_b32 v118, v130, v11, s65 bitop3:0x36
	v_add_u32_e32 v108, v114, v116
	ds_read_b128 v[12:15], v107
	ds_read_b128 v[16:19], v108
	v_add_u32_e32 v110, v114, v118
	ds_read_b128 v[20:23], v109
	ds_read_b128 v[24:27], v110
	v_or_b32_e32 v111, s4, v2
	s_addk_i32 s4, 0xde
	s_ashr_i32 s58, s4, 6
	s_waitcnt lgkmcnt(0)
	s_waitcnt vmcnt(0) lgkmcnt(0)
	v_mfma_f32_32x32x16_bf16 v[64:79], v[12:15], v[92:95], 0
	s_cmp_gt_i32 s55, 0
	s_cselect_b64 s[4:5], -1, 0
	s_cmp_lt_i32 s58, 1
	s_cselect_b64 s[22:23], -1, 0
	s_or_b64 s[4:5], s[22:23], s[4:5]
	s_and_b64 vcc, exec, s[4:5]
	v_mfma_f32_32x32x16_bf16 v[64:79], v[16:19], v[88:91], v[64:79]
	v_mfma_f32_32x32x16_bf16 v[64:79], v[20:23], v[84:87], v[64:79]
	v_mfma_f32_32x32x16_bf16 v[64:79], v[24:27], v[80:83], v[64:79]
	s_cbranch_vccnz .LBB0_1917
	v_lshlrev_b32_e32 v8, 2, v8
	v_sub_u32_e32 v8, v8, v111
	v_lshl_add_u32 v8, v8, 2, s88
	ds_read2_b32 v[12:13], v8 offset0:240 offset1:241
	ds_read2_b32 v[14:15], v8 offset0:242 offset1:243
	ds_read2_b32 v[16:17], v8 offset0:248 offset1:249
	ds_read2_b32 v[18:19], v8 offset0:250 offset1:251
	ds_read2_b32 v[20:21], v8 offset0:224 offset1:225
	ds_read2_b32 v[22:23], v8 offset0:226 offset1:227
	ds_read2_b32 v[24:25], v8 offset0:232 offset1:233
	ds_read2_b32 v[26:27], v8 offset0:234 offset1:235
	s_waitcnt lgkmcnt(4)
	v_pk_add_f32 v[78:79], v[78:79], v[18:19]
	v_pk_add_f32 v[76:77], v[76:77], v[16:17]
	v_pk_add_f32 v[74:75], v[74:75], v[14:15]
	v_pk_add_f32 v[72:73], v[72:73], v[12:13]
	s_waitcnt lgkmcnt(0)
	v_pk_add_f32 v[70:71], v[70:71], v[26:27]
	v_pk_add_f32 v[68:69], v[68:69], v[24:25]
	v_pk_add_f32 v[66:67], v[66:67], v[22:23]
	v_pk_add_f32 v[64:65], v[64:65], v[20:21]

; #define LAS __attribute__((address_space(3)))
; DI void expsum(f32x16& p, float& l_reg, bf16x8& pa0, bf16x8& pa1) {
; #pragma unroll
;     for (int r = 0; r < 16; ++r) p[r] = __builtin_amdgcn_exp2f(p[r]);
;     float ps = 0.f;
; #pragma unroll
;     for (int r = 0; r < 16; ++r) ps += p[r];
;     l_reg += ps; asm volatile("" : "+v"(l_reg));
;     ...
;     ATT_PK4(p, 0, pa0); ATT_PK4(p, 8, pa1);
;     ...
; }
; DI int v_rd_base(int lane) { return ((lane & 3) << 3) | (((lane >> 2) & 3) << 6) | (((lane >> 4) & 1) << 5) | (((lane >> 5) & 1) << 8); }
; template <int OFF> DI s16x4 tr_read(int vb) { s16x4 r; asm volatile("ds_read_b64_tr_b16 %0, %1 offset:%2" : "=&v"(r) : "v"(vb), "i"(OFF) : "memory"); return r; }
; template <int H> DI void v_reads(s16x4* vf, int vb) {
;     vf[0] = tr_read<v_rd_off(0, 2 * H, 0)>(vb); vf[1] = tr_read<v_rd_off(0, 2 * H, 1)>(vb); vf[2] = tr_read<v_rd_off(0, 2 * H + 1, 0)>(vb); vf[3] = tr_read<v_rd_off(0, 2 * H + 1, 1)>(vb);
;     vf[4] = tr_read<v_rd_off(1, 2 * H, 0)>(vb); vf[5] = tr_read<v_rd_off(1, 2 * H, 1)>(vb); vf[6] = tr_read<v_rd_off(1, 2 * H + 1, 0)>(vb); vf[7] = tr_read<v_rd_off(1, 2 * H + 1, 1)>(vb);
;     vf[8] = tr_read<v_rd_off(2, 2 * H, 0)>(vb); vf[9] = tr_read<v_rd_off(2, 2 * H, 1)>(vb); vf[10] = tr_read<v_rd_off(2, 2 * H + 1, 0)>(vb); vf[11] = tr_read<v_rd_off(2, 2 * H + 1, 1)>(vb);
;     vf[12] = tr_read<v_rd_off(3, 2 * H, 0)>(vb); vf[13] = tr_read<v_rd_off(3, 2 * H, 1)>(vb); vf[14] = tr_read<v_rd_off(3, 2 * H + 1, 0)>(vb); vf[15] = tr_read<v_rd_off(3, 2 * H + 1, 1)>(vb);
; }
; DI void pv_mma(f32x16* o, const s16x4* vf, bf16x8 pa0, bf16x8 pa1) {
;     ...
; #pragma unroll
;     for (int d0 = 0; d0 < 4; ++d0) {
;         o[d0] = __builtin_amdgcn_mfma_f32_32x32x16_bf16(pa0, ATT_PK(vf[4 * d0], vf[4 * d0 + 1]), o[d0], 0, 0, 0);
;         o[d0] = __builtin_amdgcn_mfma_f32_32x32x16_bf16(pa1, ATT_PK(vf[4 * d0 + 2], vf[4 * d0 + 3]), o[d0], 0, 0, 0); }
;     ...
; }
; template <int DQK, int D0A, int D0B> DI void k_reads(bf16x8* kf, const LAS unsigned char* Ks, int half, int r32, int hi) {
; #pragma unroll
;     for (int d0 = D0A; d0 < D0B; ++d0) kf[d0 - D0A] = *(const LAS bf16x8*)(Ks + half * (32 * DQK * 2) + kswz<DQK>(r32, (d0 * 16 + hi * 8) * 2));
; }
; template <int D0A, int D0B> DI void qk_mma(f32x16& p, const bf16x8* kf, const bf16x8* qr) {
; #pragma unroll
;     for (int d0 = D0A; d0 < D0B; ++d0) {
.Lhw_d0_b_n1922:
	ds_read_b128 v[122:125], v196 offset:4096
	ds_read_b128 v[132:135], v197 offset:4096
	s_lshl_b32 s2, s1, 14
	ds_read_b128 v[136:139], v198 offset:4096
	ds_read_b128 v[140:143], v199 offset:4096
	v_add_u32_e32 v121, s2, v106
	ds_read_b64_tr_b16 v[144:145], v121 offset:0
	ds_read_b64_tr_b16 v[146:147], v121 offset:0x800
	ds_read_b64_tr_b16 v[148:149], v121 offset:0x1000
	ds_read_b64_tr_b16 v[150:151], v121 offset:0x1800
	ds_read_b64_tr_b16 v[152:153], v121 offset:0x200
	ds_read_b64_tr_b16 v[154:155], v121 offset:0xa00
	ds_read_b64_tr_b16 v[156:157], v121 offset:0x1200
	ds_read_b64_tr_b16 v[158:159], v121 offset:0x1a00
	ds_read_b64_tr_b16 v[162:163], v121 offset:0x400
	ds_read_b64_tr_b16 v[164:165], v121 offset:0xc00
	ds_read_b64_tr_b16 v[166:167], v121 offset:0x1400
	ds_read_b64_tr_b16 v[168:169], v121 offset:0x1c00
	ds_read_b64_tr_b16 v[170:171], v121 offset:0x600
	ds_read_b64_tr_b16 v[172:173], v121 offset:0xe00
	ds_read_b64_tr_b16 v[174:175], v121 offset:0x1600
	ds_read_b64_tr_b16 v[176:177], v121 offset:0x1e00
	s_setprio 2
	v_exp_f32_e32 v64, v64
	v_exp_f32_e32 v65, v65
	v_exp_f32_e32 v66, v66
	v_exp_f32_e32 v67, v67
	v_exp_f32_e32 v68, v68
	v_exp_f32_e32 v69, v69
	v_add_f32_e32 v126, v65, v64
	v_exp_f32_e32 v70, v70
	v_add_f32_e32 v126, v66, v126
	v_exp_f32_e32 v71, v71
	v_add_f32_e32 v126, v67, v126
	v_exp_f32_e32 v72, v72
	v_add_f32_e32 v126, v68, v126
	v_exp_f32_e32 v73, v73
	v_add_f32_e32 v126, v69, v126
	v_exp_f32_e32 v74, v74
	v_add_f32_e32 v126, v70, v126
	v_exp_f32_e32 v75, v75
	v_add_f32_e32 v126, v71, v126
	v_exp_f32_e32 v76, v76
	v_add_f32_e32 v126, v72, v126
	v_exp_f32_e32 v77, v77
	v_add_f32_e32 v126, v73, v126
	v_exp_f32_e32 v78, v78
	v_add_f32_e32 v126, v74, v126
	v_exp_f32_e32 v79, v79
	v_add_f32_e32 v126, v75, v126
	v_add_f32_e32 v126, v76, v126
	v_add_f32_e32 v126, v77, v126
	v_add_f32_e32 v126, v78, v126
	v_add_f32_e32 v126, v79, v126
	v_add_f32_e32 v120, v126, v120
	v_cvt_pk_bf16_f32 v64, v64, v65
	v_cvt_pk_bf16_f32 v65, v66, v67
	v_cvt_pk_bf16_f32 v66, v68, v69
	v_cvt_pk_bf16_f32 v67, v70, v71
	v_cvt_pk_bf16_f32 v68, v72, v73
	v_cvt_pk_bf16_f32 v69, v74, v75
	v_cvt_pk_bf16_f32 v70, v76, v77
	v_cvt_pk_bf16_f32 v71, v78, v79
	s_waitcnt lgkmcnt(0)
	s_setprio 1
	v_mfma_f32_32x32x16_bf16 v[0:15], v[64:67], v[144:147], v[0:15]
	s_sub_i32 s3, s0, s98
	s_cmp_lt_u32 s3, s100
	v_mfma_f32_32x32x16_bf16 v[48:63], v[64:67], v[152:155], v[48:63]
	v_mfma_f32_32x32x16_bf16 v[32:47], v[64:67], v[162:165], v[32:47]
	v_mfma_f32_32x32x16_bf16 v[16:31], v[64:67], v[170:173], v[16:31]
	v_mfma_f32_32x32x16_bf16 v[0:15], v[68:71], v[148:151], v[0:15]
	v_mfma_f32_32x32x16_bf16 v[48:63], v[68:71], v[156:159], v[48:63]
	v_mfma_f32_32x32x16_bf16 v[32:47], v[68:71], v[166:169], v[32:47]
	v_mfma_f32_32x32x16_bf16 v[16:31], v[68:71], v[174:177], v[16:31]
	v_mfma_f32_32x32x16_bf16 v[64:79], v[122:125], v[92:95], 0
	v_mfma_f32_32x32x16_bf16 v[64:79], v[132:135], v[88:91], v[64:79]
	v_mfma_f32_32x32x16_bf16 v[64:79], v[136:139], v[84:87], v[64:79]
	v_mfma_f32_32x32x16_bf16 v[64:79], v[140:143], v[80:83], v[64:79]
	s_setprio 0
	s_cbranch_scc1 .Lhw_d0_b_dtd0bias1
.Lhw_d0_b_n1924:
	s_add_i32 s3, s22, 0xffffc000
	s_and_b32 s3, s3, 0x6000
	v_add_u32_e32 v196, s3, v107
	v_add_u32_e32 v197, s3, v108
	v_add_u32_e32 v198, s3, v109
	v_add_u32_e32 v199, s3, v110
	ds_read_b128 v[124:127], v196
	ds_read_b128 v[132:135], v197
	ds_read_b128 v[136:139], v198
	ds_read_b128 v[140:143], v199
	ds_read_b64_tr_b16 v[144:145], v121 offset:0x2000
	ds_read_b64_tr_b16 v[146:147], v121 offset:0x2800
	ds_read_b64_tr_b16 v[148:149], v121 offset:0x3000
	ds_read_b64_tr_b16 v[150:151], v121 offset:0x3800
	ds_read_b64_tr_b16 v[152:153], v121 offset:0x2200
	ds_read_b64_tr_b16 v[154:155], v121 offset:0x2a00
	ds_read_b64_tr_b16 v[156:157], v121 offset:0x3200
	ds_read_b64_tr_b16 v[158:159], v121 offset:0x3a00
	ds_read_b64_tr_b16 v[162:163], v121 offset:0x2400
	ds_read_b64_tr_b16 v[164:165], v121 offset:0x2c00
	ds_read_b64_tr_b16 v[166:167], v121 offset:0x3400
	ds_read_b64_tr_b16 v[168:169], v121 offset:0x3c00
	ds_read_b64_tr_b16 v[170:171], v121 offset:0x2600
	ds_read_b64_tr_b16 v[172:173], v121 offset:0x2e00
	ds_read_b64_tr_b16 v[174:175], v121 offset:0x3600
	ds_read_b64_tr_b16 v[176:177], v121 offset:0x3e00
	s_setprio 2
	v_exp_f32_e32 v64, v64
	v_exp_f32_e32 v65, v65
	v_exp_f32_e32 v66, v66
	v_exp_f32_e32 v67, v67
	v_exp_f32_e32 v68, v68
	v_exp_f32_e32 v69, v69
	v_add_f32_e32 v121, v65, v64
	v_exp_f32_e32 v70, v70
	v_add_f32_e32 v121, v66, v121
	v_exp_f32_e32 v71, v71
	v_add_f32_e32 v121, v67, v121
	v_exp_f32_e32 v72, v72
	v_add_f32_e32 v121, v68, v121
	v_exp_f32_e32 v73, v73
	v_add_f32_e32 v121, v69, v121
	v_exp_f32_e32 v74, v74
	v_add_f32_e32 v121, v70, v121
	v_exp_f32_e32 v75, v75
	v_add_f32_e32 v121, v71, v121
	v_exp_f32_e32 v76, v76
	v_add_f32_e32 v121, v72, v121
	v_exp_f32_e32 v77, v77
	v_add_f32_e32 v121, v73, v121
	v_exp_f32_e32 v78, v78
	v_add_f32_e32 v121, v74, v121
	v_exp_f32_e32 v79, v79
	v_add_f32_e32 v121, v75, v121
	v_add_f32_e32 v121, v76, v121
	v_add_f32_e32 v121, v77, v121
	v_add_f32_e32 v121, v78, v121
	v_add_f32_e32 v121, v79, v121
	v_add_f32_e32 v120, v120, v121
	v_cvt_pk_bf16_f32 v64, v64, v65
	v_cvt_pk_bf16_f32 v65, v66, v67
	v_cvt_pk_bf16_f32 v66, v68, v69
	v_cvt_pk_bf16_f32 v67, v70, v71
	v_cvt_pk_bf16_f32 v68, v72, v73
	v_cvt_pk_bf16_f32 v69, v74, v75
	v_cvt_pk_bf16_f32 v70, v76, v77
	v_cvt_pk_bf16_f32 v71, v78, v79
	s_waitcnt lgkmcnt(0)
	s_setprio 1
	s_waitcnt vmcnt(3)
	s_barrier
	v_mfma_f32_32x32x16_bf16 v[0:15], v[64:67], v[144:147], v[0:15]
	s_sub_i32 s74, s0, s55
	s_cmp_lt_u32 s74, s100
	v_mfma_f32_32x32x16_bf16 v[48:63], v[64:67], v[152:155], v[48:63]
	v_mfma_f32_32x32x16_bf16 v[32:47], v[64:67], v[162:165], v[32:47]
	v_mfma_f32_32x32x16_bf16 v[16:31], v[64:67], v[170:173], v[16:31]
	v_mfma_f32_32x32x16_bf16 v[0:15], v[68:71], v[148:151], v[0:15]
	v_mfma_f32_32x32x16_bf16 v[48:63], v[68:71], v[156:159], v[48:63]
	v_mfma_f32_32x32x16_bf16 v[32:47], v[68:71], v[166:169], v[32:47]
	v_mfma_f32_32x32x16_bf16 v[16:31], v[68:71], v[174:177], v[16:31]
	v_mfma_f32_32x32x16_bf16 v[64:79], v[124:127], v[92:95], 0
	v_mfma_f32_32x32x16_bf16 v[64:79], v[132:135], v[88:91], v[64:79]
	v_mfma_f32_32x32x16_bf16 v[64:79], v[136:139], v[84:87], v[64:79]
	v_mfma_f32_32x32x16_bf16 v[64:79], v[140:143], v[80:83], v[64:79]
	s_cbranch_scc1 .Lhw_d0_b_dtd0bias2

; #define LAS __attribute__((address_space(3)))
; DI void expsum(f32x16& p, float& l_reg, bf16x8& pa0, bf16x8& pa1) {
; #pragma unroll
;     for (int r = 0; r < 16; ++r) p[r] = __builtin_amdgcn_exp2f(p[r]);
;     float ps = 0.f;
; #pragma unroll
;     for (int r = 0; r < 16; ++r) ps += p[r];
;     l_reg += ps; asm volatile("" : "+v"(l_reg));
;     ...
;     ATT_PK4(p, 0, pa0); ATT_PK4(p, 8, pa1);
;     ...
; }
; DI int v_rd_base(int lane) { return ((lane & 3) << 3) | (((lane >> 2) & 3) << 6) | (((lane >> 4) & 1) << 5) | (((lane >> 5) & 1) << 8); }
; template <int OFF> DI s16x4 tr_read(int vb) { s16x4 r; asm volatile("ds_read_b64_tr_b16 %0, %1 offset:%2" : "=&v"(r) : "v"(vb), "i"(OFF) : "memory"); return r; }
; template <int H> DI void v_reads(s16x4* vf, int vb) {
;     vf[0] = tr_read<v_rd_off(0, 2 * H, 0)>(vb); vf[1] = tr_read<v_rd_off(0, 2 * H, 1)>(vb); vf[2] = tr_read<v_rd_off(0, 2 * H + 1, 0)>(vb); vf[3] = tr_read<v_rd_off(0, 2 * H + 1, 1)>(vb);
;     vf[4] = tr_read<v_rd_off(1, 2 * H, 0)>(vb); vf[5] = tr_read<v_rd_off(1, 2 * H, 1)>(vb); vf[6] = tr_read<v_rd_off(1, 2 * H + 1, 0)>(vb); vf[7] = tr_read<v_rd_off(1, 2 * H + 1, 1)>(vb);
;     vf[8] = tr_read<v_rd_off(2, 2 * H, 0)>(vb); vf[9] = tr_read<v_rd_off(2, 2 * H, 1)>(vb); vf[10] = tr_read<v_rd_off(2, 2 * H + 1, 0)>(vb); vf[11] = tr_read<v_rd_off(2, 2 * H + 1, 1)>(vb);
;     vf[12] = tr_read<v_rd_off(3, 2 * H, 0)>(vb); vf[13] = tr_read<v_rd_off(3, 2 * H, 1)>(vb); vf[14] = tr_read<v_rd_off(3, 2 * H + 1, 0)>(vb); vf[15] = tr_read<v_rd_off(3, 2 * H + 1, 1)>(vb);
; }
; DI void pv_mma(f32x16* o, const s16x4* vf, bf16x8 pa0, bf16x8 pa1) {
;     ...
; #pragma unroll
;     for (int d0 = 0; d0 < 4; ++d0) {
;         o[d0] = __builtin_amdgcn_mfma_f32_32x32x16_bf16(pa0, ATT_PK(vf[4 * d0], vf[4 * d0 + 1]), o[d0], 0, 0, 0);
;         o[d0] = __builtin_amdgcn_mfma_f32_32x32x16_bf16(pa1, ATT_PK(vf[4 * d0 + 2], vf[4 * d0 + 3]), o[d0], 0, 0, 0); }
;     ...
; }
; template <int DQK, int D0A, int D0B> DI void k_reads(bf16x8* kf, const LAS unsigned char* Ks, int half, int r32, int hi) {
; #pragma unroll
;     for (int d0 = D0A; d0 < D0B; ++d0) kf[d0 - D0A] = *(const LAS bf16x8*)(Ks + half * (32 * DQK * 2) + kswz<DQK>(r32, (d0 * 16 + hi * 8) * 2));
; }
; template <int D0A, int D0B> DI void qk_mma(f32x16& p, const bf16x8* kf, const bf16x8* qr) {
; #pragma unroll
;     for (int d0 = D0A; d0 < D0B; ++d0) {
.LBB0_1924:
	s_add_i32 s3, s22, 0xffffc000
	s_and_b32 s3, s3, 0x6000
	v_add_u32_e32 v196, s3, v107
	v_add_u32_e32 v197, s3, v108
	v_add_u32_e32 v198, s3, v109
	v_add_u32_e32 v199, s3, v110
	ds_read_b128 v[124:127], v196
	ds_read_b128 v[132:135], v197
	ds_read_b128 v[136:139], v198
	ds_read_b128 v[140:143], v199
	ds_read_b64_tr_b16 v[144:145], v121 offset:0x2000
	ds_read_b64_tr_b16 v[146:147], v121 offset:0x2800
	ds_read_b64_tr_b16 v[148:149], v121 offset:0x3000
	ds_read_b64_tr_b16 v[150:151], v121 offset:0x3800
	ds_read_b64_tr_b16 v[152:153], v121 offset:0x2200
	ds_read_b64_tr_b16 v[154:155], v121 offset:0x2a00
	ds_read_b64_tr_b16 v[156:157], v121 offset:0x3200
	ds_read_b64_tr_b16 v[158:159], v121 offset:0x3a00
	ds_read_b64_tr_b16 v[162:163], v121 offset:0x2400
	ds_read_b64_tr_b16 v[164:165], v121 offset:0x2c00
	ds_read_b64_tr_b16 v[166:167], v121 offset:0x3400
	ds_read_b64_tr_b16 v[168:169], v121 offset:0x3c00
	ds_read_b64_tr_b16 v[170:171], v121 offset:0x2600
	ds_read_b64_tr_b16 v[172:173], v121 offset:0x2e00
	ds_read_b64_tr_b16 v[174:175], v121 offset:0x3600
	ds_read_b64_tr_b16 v[176:177], v121 offset:0x3e00
	s_setprio 2
	v_exp_f32_e32 v64, v64
	v_exp_f32_e32 v65, v65
	v_exp_f32_e32 v66, v66
	v_exp_f32_e32 v67, v67
	v_exp_f32_e32 v68, v68
	v_exp_f32_e32 v69, v69
	v_add_f32_e32 v121, v65, v64
	v_exp_f32_e32 v70, v70
	v_add_f32_e32 v121, v66, v121
	v_exp_f32_e32 v71, v71
	v_add_f32_e32 v121, v67, v121
	v_exp_f32_e32 v72, v72
	v_add_f32_e32 v121, v68, v121
	v_exp_f32_e32 v73, v73
	v_add_f32_e32 v121, v69, v121
	v_exp_f32_e32 v74, v74
	v_add_f32_e32 v121, v70, v121
	v_exp_f32_e32 v75, v75
	v_add_f32_e32 v121, v71, v121
	v_exp_f32_e32 v76, v76
	v_add_f32_e32 v121, v72, v121
	v_exp_f32_e32 v77, v77
	v_add_f32_e32 v121, v73, v121
	v_exp_f32_e32 v78, v78
	v_add_f32_e32 v121, v74, v121
	v_exp_f32_e32 v79, v79
	v_add_f32_e32 v121, v75, v121
	v_add_f32_e32 v121, v76, v121
	v_add_f32_e32 v121, v77, v121
	v_add_f32_e32 v121, v78, v121
	v_add_f32_e32 v121, v79, v121
	v_add_f32_e32 v120, v120, v121
	v_cvt_pk_bf16_f32 v64, v64, v65
	v_cvt_pk_bf16_f32 v65, v66, v67
	v_cvt_pk_bf16_f32 v66, v68, v69
	v_cvt_pk_bf16_f32 v67, v70, v71
	v_cvt_pk_bf16_f32 v68, v72, v73
	v_cvt_pk_bf16_f32 v69, v74, v75
	v_cvt_pk_bf16_f32 v70, v76, v77
	v_cvt_pk_bf16_f32 v71, v78, v79
	s_waitcnt lgkmcnt(0)
	s_setprio 1
	v_mfma_f32_32x32x16_bf16 v[0:15], v[64:67], v[144:147], v[0:15]
	s_sub_i32 s74, s0, s55
	s_cmp_lt_u32 s74, s100
	v_mfma_f32_32x32x16_bf16 v[48:63], v[64:67], v[152:155], v[48:63]
	v_mfma_f32_32x32x16_bf16 v[32:47], v[64:67], v[162:165], v[32:47]
	v_mfma_f32_32x32x16_bf16 v[16:31], v[64:67], v[170:173], v[16:31]
	v_mfma_f32_32x32x16_bf16 v[0:15], v[68:71], v[148:151], v[0:15]
	v_mfma_f32_32x32x16_bf16 v[48:63], v[68:71], v[156:159], v[48:63]
	v_mfma_f32_32x32x16_bf16 v[32:47], v[68:71], v[166:169], v[32:47]
	v_mfma_f32_32x32x16_bf16 v[16:31], v[68:71], v[174:177], v[16:31]
	v_mfma_f32_32x32x16_bf16 v[64:79], v[124:127], v[92:95], 0
	v_mfma_f32_32x32x16_bf16 v[64:79], v[132:135], v[88:91], v[64:79]
	v_mfma_f32_32x32x16_bf16 v[64:79], v[136:139], v[84:87], v[64:79]
	v_mfma_f32_32x32x16_bf16 v[64:79], v[140:143], v[80:83], v[64:79]
	s_cbranch_scc1 .Ldt_d0_bias2

; #define LAS __attribute__((address_space(3)))
; DI void expsum(f32x16& p, float& l_reg, bf16x8& pa0, bf16x8& pa1) {
; #pragma unroll
;     for (int r = 0; r < 16; ++r) p[r] = __builtin_amdgcn_exp2f(p[r]);
;     float ps = 0.f;
; #pragma unroll
;     for (int r = 0; r < 16; ++r) ps += p[r];
;     l_reg += ps; asm volatile("" : "+v"(l_reg));
;     ...
;     ATT_PK4(p, 0, pa0); ATT_PK4(p, 8, pa1);
;     ...
; }
; DI int v_rd_base(int lane) { return ((lane & 3) << 3) | (((lane >> 2) & 3) << 6) | (((lane >> 4) & 1) << 5) | (((lane >> 5) & 1) << 8); }
; template <int OFF> DI s16x4 tr_read(int vb) { s16x4 r; asm volatile("ds_read_b64_tr_b16 %0, %1 offset:%2" : "=&v"(r) : "v"(vb), "i"(OFF) : "memory"); return r; }
; template <int H> DI void v_reads(s16x4* vf, int vb) {
;     vf[0] = tr_read<v_rd_off(0, 2 * H, 0)>(vb); vf[1] = tr_read<v_rd_off(0, 2 * H, 1)>(vb); vf[2] = tr_read<v_rd_off(0, 2 * H + 1, 0)>(vb); vf[3] = tr_read<v_rd_off(0, 2 * H + 1, 1)>(vb);
;     vf[4] = tr_read<v_rd_off(1, 2 * H, 0)>(vb); vf[5] = tr_read<v_rd_off(1, 2 * H, 1)>(vb); vf[6] = tr_read<v_rd_off(1, 2 * H + 1, 0)>(vb); vf[7] = tr_read<v_rd_off(1, 2 * H + 1, 1)>(vb);
;     vf[8] = tr_read<v_rd_off(2, 2 * H, 0)>(vb); vf[9] = tr_read<v_rd_off(2, 2 * H, 1)>(vb); vf[10] = tr_read<v_rd_off(2, 2 * H + 1, 0)>(vb); vf[11] = tr_read<v_rd_off(2, 2 * H + 1, 1)>(vb);
;     vf[12] = tr_read<v_rd_off(3, 2 * H, 0)>(vb); vf[13] = tr_read<v_rd_off(3, 2 * H, 1)>(vb); vf[14] = tr_read<v_rd_off(3, 2 * H + 1, 0)>(vb); vf[15] = tr_read<v_rd_off(3, 2 * H + 1, 1)>(vb);
; }
; DI void pv_mma(f32x16* o, const s16x4* vf, bf16x8 pa0, bf16x8 pa1) {
;     ...
; #pragma unroll
;     for (int d0 = 0; d0 < 4; ++d0) {
;         o[d0] = __builtin_amdgcn_mfma_f32_32x32x16_bf16(pa0, ATT_PK(vf[4 * d0], vf[4 * d0 + 1]), o[d0], 0, 0, 0);
;         o[d0] = __builtin_amdgcn_mfma_f32_32x32x16_bf16(pa1, ATT_PK(vf[4 * d0 + 2], vf[4 * d0 + 3]), o[d0], 0, 0, 0); }
;     ...
; }
; template <int DQK, int D0A, int D0B> DI void k_reads(bf16x8* kf, const LAS unsigned char* Ks, int half, int r32, int hi) {
; #pragma unroll
;     for (int d0 = D0A; d0 < D0B; ++d0) kf[d0 - D0A] = *(const LAS bf16x8*)(Ks + half * (32 * DQK * 2) + kswz<DQK>(r32, (d0 * 16 + hi * 8) * 2));
; }
; template <int D0A, int D0B> DI void qk_mma(f32x16& p, const bf16x8* kf, const bf16x8* qr) {
; #pragma unroll
;     for (int d0 = D0A; d0 < D0B; ++d0) {
.LBB0_1930:
	s_mov_b64 s[96:97], 0xc00
	ds_read_b128 v[98:101], v107 offset:12288
	ds_read_b128 v[102:105], v108 offset:12288
	ds_read_b128 v[114:117], v109 offset:12288
	ds_read_b128 v[122:125], v110 offset:12288
	v_lshl_add_u32 v96, s64, 14, v106
	ds_read_b64_tr_b16 v[132:133], v96 offset:0
	ds_read_b64_tr_b16 v[134:135], v96 offset:0x800
	ds_read_b64_tr_b16 v[136:137], v96 offset:0x1000
	ds_read_b64_tr_b16 v[138:139], v96 offset:0x1800
	ds_read_b64_tr_b16 v[140:141], v96 offset:0x200
	ds_read_b64_tr_b16 v[142:143], v96 offset:0xa00
	ds_read_b64_tr_b16 v[144:145], v96 offset:0x1200
	ds_read_b64_tr_b16 v[146:147], v96 offset:0x1a00
	ds_read_b64_tr_b16 v[148:149], v96 offset:0x400
	ds_read_b64_tr_b16 v[150:151], v96 offset:0xc00
	ds_read_b64_tr_b16 v[152:153], v96 offset:0x1400
	ds_read_b64_tr_b16 v[154:155], v96 offset:0x1c00
	ds_read_b64_tr_b16 v[156:157], v96 offset:0x600
	ds_read_b64_tr_b16 v[158:159], v96 offset:0xe00
	ds_read_b64_tr_b16 v[162:163], v96 offset:0x1600
	ds_read_b64_tr_b16 v[164:165], v96 offset:0x1e00
	s_setprio 2
	v_exp_f32_e32 v64, v64
	v_exp_f32_e32 v65, v65
	v_exp_f32_e32 v66, v66
	v_exp_f32_e32 v67, v67
	v_exp_f32_e32 v68, v68
	v_exp_f32_e32 v69, v69
	v_add_f32_e32 v97, v65, v64
	v_exp_f32_e32 v70, v70
	v_add_f32_e32 v97, v66, v97
	v_exp_f32_e32 v71, v71
	v_add_f32_e32 v97, v67, v97
	v_exp_f32_e32 v72, v72
	v_add_f32_e32 v97, v68, v97
	v_exp_f32_e32 v73, v73
	v_add_f32_e32 v97, v69, v97
	v_exp_f32_e32 v74, v74
	v_add_f32_e32 v97, v70, v97
	v_exp_f32_e32 v75, v75
	v_add_f32_e32 v97, v71, v97
	v_exp_f32_e32 v76, v76
	v_add_f32_e32 v97, v72, v97
	v_exp_f32_e32 v77, v77
	v_add_f32_e32 v97, v73, v97
	v_exp_f32_e32 v78, v78
	v_add_f32_e32 v97, v74, v97
	v_exp_f32_e32 v79, v79
	v_add_f32_e32 v97, v75, v97
	v_add_f32_e32 v97, v76, v97
	v_add_f32_e32 v97, v77, v97
	v_add_f32_e32 v97, v78, v97
	v_add_f32_e32 v97, v79, v97
	v_add_f32_e32 v97, v97, v120
	v_cvt_pk_bf16_f32 v64, v64, v65
	v_cvt_pk_bf16_f32 v65, v66, v67
	v_cvt_pk_bf16_f32 v66, v68, v69
	v_cvt_pk_bf16_f32 v67, v70, v71
	v_cvt_pk_bf16_f32 v68, v72, v73
	v_cvt_pk_bf16_f32 v69, v74, v75
	v_cvt_pk_bf16_f32 v70, v76, v77
	v_cvt_pk_bf16_f32 v71, v78, v79
	s_waitcnt lgkmcnt(0)
	s_setprio 1
	v_mfma_f32_32x32x16_bf16 v[0:15], v[64:67], v[132:135], v[0:15]
	s_cmp_gt_i32 s55, 61
	s_cselect_b64 s[0:1], -1, 0
	s_cmp_lt_i32 s58, 62
	s_cselect_b64 s[2:3], -1, 0
	s_or_b64 s[0:1], s[0:1], s[2:3]
	s_and_b64 vcc, exec, s[0:1]
	v_mfma_f32_32x32x16_bf16 v[48:63], v[64:67], v[140:143], v[48:63]
	v_mfma_f32_32x32x16_bf16 v[32:47], v[64:67], v[148:151], v[32:47]
	v_mfma_f32_32x32x16_bf16 v[16:31], v[64:67], v[156:159], v[16:31]
	v_mfma_f32_32x32x16_bf16 v[0:15], v[68:71], v[136:139], v[0:15]
	v_mfma_f32_32x32x16_bf16 v[48:63], v[68:71], v[144:147], v[48:63]
	v_mfma_f32_32x32x16_bf16 v[32:47], v[68:71], v[152:155], v[32:47]
	v_mfma_f32_32x32x16_bf16 v[16:31], v[68:71], v[162:165], v[16:31]
	s_waitcnt lgkmcnt(0)
	v_mfma_f32_32x32x16_bf16 v[64:79], v[98:101], v[92:95], 0
	v_mfma_f32_32x32x16_bf16 v[64:79], v[102:105], v[88:91], v[64:79]
	v_mfma_f32_32x32x16_bf16 v[64:79], v[114:117], v[84:87], v[64:79]
	v_mfma_f32_32x32x16_bf16 v[64:79], v[122:125], v[80:83], v[64:79]
	s_setprio 0
	s_cbranch_vccnz .LBB0_1932
	v_sub_u32_e32 v98, 0xf40, v111
	v_lshlrev_b32_e32 v98, 2, v98
	v_add3_u32 v98, s88, v98, v130
	v_add_u32_e32 v114, 0x400, v98
	v_add_u32_e32 v116, 0x408, v98
	v_add_u32_e32 v118, 0x420, v98
	v_add_u32_e32 v120, 0x428, v98
	v_add_u32_e32 v99, 0x440, v98
	v_add_u32_e32 v100, 0x448, v98
	v_add_u32_e32 v102, 0x460, v98
	v_add_u32_e32 v104, 0x468, v98
	ds_read2_b32 v[98:99], v99 offset1:1
	ds_read2_b32 v[100:101], v100 offset1:1
	ds_read2_b32 v[102:103], v102 offset1:1
	ds_read2_b32 v[104:105], v104 offset1:1
	ds_read2_b32 v[114:115], v114 offset1:1
	ds_read2_b32 v[116:117], v116 offset1:1
	ds_read2_b32 v[118:119], v118 offset1:1
	ds_read2_b32 v[120:121], v120 offset1:1
	s_waitcnt lgkmcnt(0)
	v_pk_add_f32 v[78:79], v[78:79], v[104:105]
	v_pk_add_f32 v[76:77], v[76:77], v[102:103]
	v_pk_add_f32 v[74:75], v[74:75], v[100:101]
	v_pk_add_f32 v[72:73], v[72:73], v[98:99]
	v_pk_add_f32 v[70:71], v[70:71], v[120:121]
	v_pk_add_f32 v[68:69], v[68:69], v[118:119]
	v_pk_add_f32 v[66:67], v[66:67], v[116:117]
	v_pk_add_f32 v[64:65], v[64:65], v[114:115]
.LBB0_1932:
	s_movk_i32 s64, 0x70
	ds_read_b128 v[98:101], v107 offset:16384
	ds_read_b128 v[102:105], v108 offset:16384
	ds_read_b128 v[114:117], v109 offset:16384
	ds_read_b128 v[118:121], v110 offset:16384
	ds_read_b64_tr_b16 v[122:123], v96 offset:0x2000
	ds_read_b64_tr_b16 v[124:125], v96 offset:0x2800
	ds_read_b64_tr_b16 v[132:133], v96 offset:0x3000
	ds_read_b64_tr_b16 v[134:135], v96 offset:0x3800
	ds_read_b64_tr_b16 v[136:137], v96 offset:0x2200
	ds_read_b64_tr_b16 v[138:139], v96 offset:0x2a00
	ds_read_b64_tr_b16 v[140:141], v96 offset:0x3200
	ds_read_b64_tr_b16 v[142:143], v96 offset:0x3a00
	ds_read_b64_tr_b16 v[144:145], v96 offset:0x2400
	ds_read_b64_tr_b16 v[146:147], v96 offset:0x2c00
	ds_read_b64_tr_b16 v[148:149], v96 offset:0x3400
	ds_read_b64_tr_b16 v[150:151], v96 offset:0x3c00
	ds_read_b64_tr_b16 v[152:153], v96 offset:0x2600
	ds_read_b64_tr_b16 v[154:155], v96 offset:0x2e00
	ds_read_b64_tr_b16 v[156:157], v96 offset:0x3600
	ds_read_b64_tr_b16 v[158:159], v96 offset:0x3e00
	s_nop 5
	s_setprio 2
	v_exp_f32_e32 v64, v64
	v_exp_f32_e32 v65, v65
	v_exp_f32_e32 v66, v66
	v_exp_f32_e32 v67, v67
	v_exp_f32_e32 v68, v68
	v_exp_f32_e32 v69, v69
	v_add_f32_e32 v96, v65, v64
	v_exp_f32_e32 v70, v70
	v_add_f32_e32 v96, v66, v96
	v_exp_f32_e32 v71, v71
	v_add_f32_e32 v96, v67, v96
	v_exp_f32_e32 v72, v72
	v_add_f32_e32 v96, v68, v96
	v_exp_f32_e32 v73, v73
	v_add_f32_e32 v96, v69, v96
	v_exp_f32_e32 v74, v74
	v_add_f32_e32 v96, v70, v96
	v_exp_f32_e32 v75, v75
	v_add_f32_e32 v96, v71, v96
	v_exp_f32_e32 v76, v76
	v_add_f32_e32 v96, v72, v96
	v_exp_f32_e32 v77, v77
	v_add_f32_e32 v96, v73, v96
	v_exp_f32_e32 v78, v78
	v_add_f32_e32 v96, v74, v96
	v_exp_f32_e32 v79, v79
	v_add_f32_e32 v96, v75, v96
	v_add_f32_e32 v96, v76, v96
	v_add_f32_e32 v96, v77, v96
	v_add_f32_e32 v96, v78, v96
	v_add_f32_e32 v96, v79, v96
	v_add_f32_e32 v96, v97, v96
	v_cvt_pk_bf16_f32 v64, v64, v65
	v_cvt_pk_bf16_f32 v65, v66, v67
	v_cvt_pk_bf16_f32 v66, v68, v69
	v_cvt_pk_bf16_f32 v67, v70, v71
	v_cvt_pk_bf16_f32 v68, v72, v73
	v_cvt_pk_bf16_f32 v69, v74, v75
	v_cvt_pk_bf16_f32 v70, v76, v77
	v_cvt_pk_bf16_f32 v71, v78, v79
	s_waitcnt lgkmcnt(0)
	s_setprio 1
	s_cmp_lt_u32 s33, 0x100
	s_cbranch_scc1 .Lstg_d0_m61_13
	s_waitcnt vmcnt(0)
	s_barrier

; #define LAS __attribute__((address_space(3)))
; DI void expsum(f32x16& p, float& l_reg, bf16x8& pa0, bf16x8& pa1) {
; #pragma unroll
;     for (int r = 0; r < 16; ++r) p[r] = __builtin_amdgcn_exp2f(p[r]);
;     float ps = 0.f;
; #pragma unroll
;     for (int r = 0; r < 16; ++r) ps += p[r];
;     l_reg += ps; asm volatile("" : "+v"(l_reg));
;     ...
;     ATT_PK4(p, 0, pa0); ATT_PK4(p, 8, pa1);
;     ...
; }
; DI int v_rd_base(int lane) { return ((lane & 3) << 3) | (((lane >> 2) & 3) << 6) | (((lane >> 4) & 1) << 5) | (((lane >> 5) & 1) << 8); }
; template <int OFF> DI s16x4 tr_read(int vb) { s16x4 r; asm volatile("ds_read_b64_tr_b16 %0, %1 offset:%2" : "=&v"(r) : "v"(vb), "i"(OFF) : "memory"); return r; }
; template <int H> DI void v_reads(s16x4* vf, int vb) {
;     vf[0] = tr_read<v_rd_off(0, 2 * H, 0)>(vb); vf[1] = tr_read<v_rd_off(0, 2 * H, 1)>(vb); vf[2] = tr_read<v_rd_off(0, 2 * H + 1, 0)>(vb); vf[3] = tr_read<v_rd_off(0, 2 * H + 1, 1)>(vb);
;     vf[4] = tr_read<v_rd_off(1, 2 * H, 0)>(vb); vf[5] = tr_read<v_rd_off(1, 2 * H, 1)>(vb); vf[6] = tr_read<v_rd_off(1, 2 * H + 1, 0)>(vb); vf[7] = tr_read<v_rd_off(1, 2 * H + 1, 1)>(vb);
;     vf[8] = tr_read<v_rd_off(2, 2 * H, 0)>(vb); vf[9] = tr_read<v_rd_off(2, 2 * H, 1)>(vb); vf[10] = tr_read<v_rd_off(2, 2 * H + 1, 0)>(vb); vf[11] = tr_read<v_rd_off(2, 2 * H + 1, 1)>(vb);
;     vf[12] = tr_read<v_rd_off(3, 2 * H, 0)>(vb); vf[13] = tr_read<v_rd_off(3, 2 * H, 1)>(vb); vf[14] = tr_read<v_rd_off(3, 2 * H + 1, 0)>(vb); vf[15] = tr_read<v_rd_off(3, 2 * H + 1, 1)>(vb);
; }
; DI void pv_mma(f32x16* o, const s16x4* vf, bf16x8 pa0, bf16x8 pa1) {
;     ...
; #pragma unroll
;     for (int d0 = 0; d0 < 4; ++d0) {
;         o[d0] = __builtin_amdgcn_mfma_f32_32x32x16_bf16(pa0, ATT_PK(vf[4 * d0], vf[4 * d0 + 1]), o[d0], 0, 0, 0);
;         o[d0] = __builtin_amdgcn_mfma_f32_32x32x16_bf16(pa1, ATT_PK(vf[4 * d0 + 2], vf[4 * d0 + 3]), o[d0], 0, 0, 0); }
;     ...
; }
; template <int DQK, int D0A, int D0B> DI void k_reads(bf16x8* kf, const LAS unsigned char* Ks, int half, int r32, int hi) {
; #pragma unroll
;     for (int d0 = D0A; d0 < D0B; ++d0) kf[d0 - D0A] = *(const LAS bf16x8*)(Ks + half * (32 * DQK * 2) + kswz<DQK>(r32, (d0 * 16 + hi * 8) * 2));
; }
; template <int D0A, int D0B> DI void qk_mma(f32x16& p, const bf16x8* kf, const bf16x8* qr) {
; #pragma unroll
;     for (int d0 = D0A; d0 < D0B; ++d0) {
.LBB0_1936:
	ds_read_b128 v[100:103], v107 offset:20480
	ds_read_b128 v[114:117], v108 offset:20480
	ds_read_b128 v[118:121], v109 offset:20480
	ds_read_b128 v[122:125], v110 offset:20480
	v_add_u32_e32 v98, 0x8000, v106
	ds_read_b64_tr_b16 v[132:133], v98 offset:0
	ds_read_b64_tr_b16 v[134:135], v98 offset:0x800
	ds_read_b64_tr_b16 v[136:137], v98 offset:0x1000
	ds_read_b64_tr_b16 v[138:139], v98 offset:0x1800
	ds_read_b64_tr_b16 v[140:141], v98 offset:0x200
	ds_read_b64_tr_b16 v[142:143], v98 offset:0xa00
	ds_read_b64_tr_b16 v[144:145], v98 offset:0x1200
	ds_read_b64_tr_b16 v[146:147], v98 offset:0x1a00
	ds_read_b64_tr_b16 v[148:149], v98 offset:0x400
	ds_read_b64_tr_b16 v[150:151], v98 offset:0xc00
	ds_read_b64_tr_b16 v[152:153], v98 offset:0x1400
	ds_read_b64_tr_b16 v[154:155], v98 offset:0x1c00
	ds_read_b64_tr_b16 v[156:157], v98 offset:0x600
	ds_read_b64_tr_b16 v[158:159], v98 offset:0xe00
	ds_read_b64_tr_b16 v[162:163], v98 offset:0x1600
	ds_read_b64_tr_b16 v[164:165], v98 offset:0x1e00
	s_setprio 2
	v_exp_f32_e32 v64, v64
	v_exp_f32_e32 v65, v65
	v_exp_f32_e32 v66, v66
	v_exp_f32_e32 v67, v67
	v_exp_f32_e32 v68, v68
	v_exp_f32_e32 v69, v69
	v_add_f32_e32 v99, v65, v64
	v_exp_f32_e32 v70, v70
	v_add_f32_e32 v99, v66, v99
	v_exp_f32_e32 v71, v71
	v_add_f32_e32 v99, v67, v99
	v_exp_f32_e32 v72, v72
	v_add_f32_e32 v99, v68, v99
	v_exp_f32_e32 v73, v73
	v_add_f32_e32 v99, v69, v99
	v_exp_f32_e32 v74, v74
	v_add_f32_e32 v99, v70, v99
	v_exp_f32_e32 v75, v75
	v_add_f32_e32 v99, v71, v99
	v_exp_f32_e32 v76, v76
	v_add_f32_e32 v99, v72, v99
	v_exp_f32_e32 v77, v77
	v_add_f32_e32 v99, v73, v99
	v_exp_f32_e32 v78, v78
	v_add_f32_e32 v99, v74, v99
	v_exp_f32_e32 v79, v79
	v_add_f32_e32 v99, v75, v99
	v_add_f32_e32 v99, v76, v99
	v_add_f32_e32 v99, v77, v99
	v_add_f32_e32 v99, v78, v99
	v_add_f32_e32 v99, v79, v99
	v_add_f32_e32 v96, v99, v96
	v_cvt_pk_bf16_f32 v64, v64, v65
	v_cvt_pk_bf16_f32 v65, v66, v67
	v_cvt_pk_bf16_f32 v66, v68, v69
	v_cvt_pk_bf16_f32 v67, v70, v71
	v_cvt_pk_bf16_f32 v68, v72, v73
	v_cvt_pk_bf16_f32 v69, v74, v75
	v_cvt_pk_bf16_f32 v70, v76, v77
	v_cvt_pk_bf16_f32 v71, v78, v79
	s_waitcnt lgkmcnt(0)
	s_setprio 1
	v_mfma_f32_32x32x16_bf16 v[0:15], v[64:67], v[132:135], v[0:15]
	s_and_b64 vcc, exec, s[2:3]
	v_mfma_f32_32x32x16_bf16 v[48:63], v[64:67], v[140:143], v[48:63]
	v_mfma_f32_32x32x16_bf16 v[32:47], v[64:67], v[148:151], v[32:47]
	v_mfma_f32_32x32x16_bf16 v[16:31], v[64:67], v[156:159], v[16:31]
	v_mfma_f32_32x32x16_bf16 v[0:15], v[68:71], v[136:139], v[0:15]
	v_mfma_f32_32x32x16_bf16 v[48:63], v[68:71], v[144:147], v[48:63]
	v_mfma_f32_32x32x16_bf16 v[32:47], v[68:71], v[152:155], v[32:47]
	v_mfma_f32_32x32x16_bf16 v[16:31], v[68:71], v[162:165], v[16:31]
	s_waitcnt lgkmcnt(0)
	v_mfma_f32_32x32x16_bf16 v[64:79], v[100:103], v[92:95], 0
	v_mfma_f32_32x32x16_bf16 v[64:79], v[114:117], v[88:91], v[64:79]
	v_mfma_f32_32x32x16_bf16 v[64:79], v[118:121], v[84:87], v[64:79]
	v_mfma_f32_32x32x16_bf16 v[64:79], v[122:125], v[80:83], v[64:79]
	s_setprio 0
	s_cbranch_vccnz .LBB0_1938
	v_add3_u32 v97, s88, v97, v130
	v_add_u32_e32 v118, 0x408, v97
	v_add_u32_e32 v120, 0x420, v97
	v_add_u32_e32 v122, 0x428, v97
	v_add_u32_e32 v100, 0x440, v97
	v_add_u32_e32 v102, 0x448, v97
	v_add_u32_e32 v104, 0x460, v97
	v_add_u32_e32 v99, 0x400, v97
	v_add_u32_e32 v97, 0x468, v97
	ds_read2_b32 v[100:101], v100 offset1:1
	ds_read2_b32 v[102:103], v102 offset1:1
	ds_read2_b32 v[104:105], v104 offset1:1
	ds_read2_b32 v[114:115], v97 offset1:1
	ds_read2_b32 v[116:117], v99 offset1:1
	ds_read2_b32 v[118:119], v118 offset1:1
	ds_read2_b32 v[120:121], v120 offset1:1
	ds_read2_b32 v[122:123], v122 offset1:1
	s_waitcnt lgkmcnt(0)
	v_pk_add_f32 v[78:79], v[78:79], v[114:115]
	v_pk_add_f32 v[76:77], v[76:77], v[104:105]
	v_pk_add_f32 v[74:75], v[74:75], v[102:103]
	v_pk_add_f32 v[72:73], v[72:73], v[100:101]
	v_pk_add_f32 v[70:71], v[70:71], v[122:123]
	v_pk_add_f32 v[68:69], v[68:69], v[120:121]
	v_pk_add_f32 v[66:67], v[66:67], v[118:119]
	v_pk_add_f32 v[64:65], v[64:65], v[116:117]
.LBB0_1938:
	ds_read_b128 v[100:103], v107 offset:24576
	ds_read_b128 v[114:117], v108 offset:24576
	ds_read_b128 v[118:121], v109 offset:24576
	ds_read_b128 v[122:125], v110 offset:24576
	ds_read_b64_tr_b16 v[132:133], v98 offset:0x2000
	ds_read_b64_tr_b16 v[134:135], v98 offset:0x2800
	ds_read_b64_tr_b16 v[136:137], v98 offset:0x3000
	ds_read_b64_tr_b16 v[138:139], v98 offset:0x3800
	ds_read_b64_tr_b16 v[140:141], v98 offset:0x2200
	ds_read_b64_tr_b16 v[142:143], v98 offset:0x2a00
	ds_read_b64_tr_b16 v[144:145], v98 offset:0x3200
	ds_read_b64_tr_b16 v[146:147], v98 offset:0x3a00
	ds_read_b64_tr_b16 v[148:149], v98 offset:0x2400
	ds_read_b64_tr_b16 v[150:151], v98 offset:0x2c00
	ds_read_b64_tr_b16 v[152:153], v98 offset:0x3400
	ds_read_b64_tr_b16 v[154:155], v98 offset:0x3c00
	ds_read_b64_tr_b16 v[156:157], v98 offset:0x2600
	ds_read_b64_tr_b16 v[158:159], v98 offset:0x2e00
	ds_read_b64_tr_b16 v[162:163], v98 offset:0x3600
	ds_read_b64_tr_b16 v[164:165], v98 offset:0x3e00
	s_nop 6
	s_setprio 2
	v_exp_f32_e32 v64, v64
	v_exp_f32_e32 v65, v65
	v_exp_f32_e32 v66, v66
	v_exp_f32_e32 v67, v67
	v_exp_f32_e32 v68, v68
	v_exp_f32_e32 v69, v69
	v_add_f32_e32 v97, v65, v64
	v_exp_f32_e32 v70, v70
	v_add_f32_e32 v97, v66, v97
	v_exp_f32_e32 v71, v71
	v_add_f32_e32 v97, v67, v97
	v_exp_f32_e32 v72, v72
	v_add_f32_e32 v97, v68, v97
	v_exp_f32_e32 v73, v73
	v_add_f32_e32 v97, v69, v97
	v_exp_f32_e32 v74, v74
	v_add_f32_e32 v97, v70, v97
	v_exp_f32_e32 v75, v75
	v_add_f32_e32 v97, v71, v97
	v_exp_f32_e32 v76, v76
	v_add_f32_e32 v97, v72, v97
	v_exp_f32_e32 v77, v77
	v_add_f32_e32 v97, v73, v97
	v_exp_f32_e32 v78, v78
	v_add_f32_e32 v97, v74, v97
	v_exp_f32_e32 v79, v79
	v_add_f32_e32 v97, v75, v97
	v_add_f32_e32 v97, v76, v97
	v_add_f32_e32 v97, v77, v97
	v_add_f32_e32 v97, v78, v97
	v_add_f32_e32 v97, v79, v97
	v_add_f32_e32 v96, v96, v97
	v_cvt_pk_bf16_f32 v64, v64, v65
	v_cvt_pk_bf16_f32 v65, v66, v67
	v_cvt_pk_bf16_f32 v66, v68, v69
	v_cvt_pk_bf16_f32 v67, v70, v71
	v_cvt_pk_bf16_f32 v68, v72, v73
	v_cvt_pk_bf16_f32 v69, v74, v75
	v_cvt_pk_bf16_f32 v70, v76, v77
	v_cvt_pk_bf16_f32 v71, v78, v79
	s_waitcnt lgkmcnt(0)
	s_setprio 1
	s_cmp_lt_u32 s33, 0x100
	s_cbranch_scc1 .Lstg_d0_m62_15
	s_waitcnt vmcnt(0)
	s_barrier

; #define LAS __attribute__((address_space(3)))
; DI void expsum(f32x16& p, float& l_reg, bf16x8& pa0, bf16x8& pa1) {
; #pragma unroll
;     for (int r = 0; r < 16; ++r) p[r] = __builtin_amdgcn_exp2f(p[r]);
;     float ps = 0.f;
; #pragma unroll
;     for (int r = 0; r < 16; ++r) ps += p[r];
;     l_reg += ps; asm volatile("" : "+v"(l_reg));
;     ...
;     ATT_PK4(p, 0, pa0); ATT_PK4(p, 8, pa1);
;     ...
; }
; DI int v_rd_base(int lane) { return ((lane & 3) << 3) | (((lane >> 2) & 3) << 6) | (((lane >> 4) & 1) << 5) | (((lane >> 5) & 1) << 8); }
; template <int OFF> DI s16x4 tr_read(int vb) { s16x4 r; asm volatile("ds_read_b64_tr_b16 %0, %1 offset:%2" : "=&v"(r) : "v"(vb), "i"(OFF) : "memory"); return r; }
; template <int H> DI void v_reads(s16x4* vf, int vb) {
;     vf[0] = tr_read<v_rd_off(0, 2 * H, 0)>(vb); vf[1] = tr_read<v_rd_off(0, 2 * H, 1)>(vb); vf[2] = tr_read<v_rd_off(0, 2 * H + 1, 0)>(vb); vf[3] = tr_read<v_rd_off(0, 2 * H + 1, 1)>(vb);
;     vf[4] = tr_read<v_rd_off(1, 2 * H, 0)>(vb); vf[5] = tr_read<v_rd_off(1, 2 * H, 1)>(vb); vf[6] = tr_read<v_rd_off(1, 2 * H + 1, 0)>(vb); vf[7] = tr_read<v_rd_off(1, 2 * H + 1, 1)>(vb);
;     vf[8] = tr_read<v_rd_off(2, 2 * H, 0)>(vb); vf[9] = tr_read<v_rd_off(2, 2 * H, 1)>(vb); vf[10] = tr_read<v_rd_off(2, 2 * H + 1, 0)>(vb); vf[11] = tr_read<v_rd_off(2, 2 * H + 1, 1)>(vb);
;     vf[12] = tr_read<v_rd_off(3, 2 * H, 0)>(vb); vf[13] = tr_read<v_rd_off(3, 2 * H, 1)>(vb); vf[14] = tr_read<v_rd_off(3, 2 * H + 1, 0)>(vb); vf[15] = tr_read<v_rd_off(3, 2 * H + 1, 1)>(vb);
; }
; DI void pv_mma(f32x16* o, const s16x4* vf, bf16x8 pa0, bf16x8 pa1) {
;     ...
; #pragma unroll
;     for (int d0 = 0; d0 < 4; ++d0) {
;         o[d0] = __builtin_amdgcn_mfma_f32_32x32x16_bf16(pa0, ATT_PK(vf[4 * d0], vf[4 * d0 + 1]), o[d0], 0, 0, 0);
;         o[d0] = __builtin_amdgcn_mfma_f32_32x32x16_bf16(pa1, ATT_PK(vf[4 * d0 + 2], vf[4 * d0 + 3]), o[d0], 0, 0, 0); }
;     ...
; }
; template <int DQK, int D0A, int D0B> DI void k_reads(bf16x8* kf, const LAS unsigned char* Ks, int half, int r32, int hi) {
; #pragma unroll
;     for (int d0 = D0A; d0 < D0B; ++d0) kf[d0 - D0A] = *(const LAS bf16x8*)(Ks + half * (32 * DQK * 2) + kswz<DQK>(r32, (d0 * 16 + hi * 8) * 2));
; }
; template <int D0A, int D0B> DI void qk_mma(f32x16& p, const bf16x8* kf, const bf16x8* qr) {
; #pragma unroll
;     for (int d0 = D0A; d0 < D0B; ++d0) {
.LBB0_1942:
	ds_read_b128 v[98:101], v107 offset:28672
	ds_read_b128 v[102:105], v108 offset:28672
	ds_read_b128 v[112:115], v109 offset:28672
	ds_read_b128 v[108:111], v110 offset:28672
	ds_read_b64_tr_b16 v[116:117], v106 offset:0
	ds_read_b64_tr_b16 v[118:119], v106 offset:0x800
	ds_read_b64_tr_b16 v[120:121], v106 offset:0x1000
	ds_read_b64_tr_b16 v[122:123], v106 offset:0x1800
	ds_read_b64_tr_b16 v[124:125], v106 offset:0x200
	ds_read_b64_tr_b16 v[126:127], v106 offset:0xa00
	ds_read_b64_tr_b16 v[132:133], v106 offset:0x1200
	ds_read_b64_tr_b16 v[134:135], v106 offset:0x1a00
	ds_read_b64_tr_b16 v[136:137], v106 offset:0x400
	ds_read_b64_tr_b16 v[138:139], v106 offset:0xc00
	ds_read_b64_tr_b16 v[140:141], v106 offset:0x1400
	ds_read_b64_tr_b16 v[142:143], v106 offset:0x1c00
	ds_read_b64_tr_b16 v[144:145], v106 offset:0x600
	ds_read_b64_tr_b16 v[146:147], v106 offset:0xe00
	ds_read_b64_tr_b16 v[148:149], v106 offset:0x1600
	ds_read_b64_tr_b16 v[150:151], v106 offset:0x1e00
	s_setprio 2
	v_exp_f32_e32 v64, v64
	v_exp_f32_e32 v65, v65
	v_exp_f32_e32 v66, v66
	v_exp_f32_e32 v67, v67
	v_exp_f32_e32 v68, v68
	v_exp_f32_e32 v69, v69
	v_add_f32_e32 v107, v65, v64
	v_exp_f32_e32 v70, v70
	v_add_f32_e32 v107, v66, v107
	v_exp_f32_e32 v71, v71
	v_add_f32_e32 v107, v67, v107
	v_exp_f32_e32 v72, v72
	v_add_f32_e32 v107, v68, v107
	v_exp_f32_e32 v73, v73
	v_add_f32_e32 v107, v69, v107
	v_exp_f32_e32 v74, v74
	v_add_f32_e32 v107, v70, v107
	v_exp_f32_e32 v75, v75
	v_add_f32_e32 v107, v71, v107
	v_exp_f32_e32 v76, v76
	v_add_f32_e32 v107, v72, v107
	v_exp_f32_e32 v77, v77
	v_add_f32_e32 v107, v73, v107
	v_exp_f32_e32 v78, v78
	v_add_f32_e32 v107, v74, v107
	v_exp_f32_e32 v79, v79
	v_add_f32_e32 v107, v75, v107
	v_add_f32_e32 v107, v76, v107
	v_add_f32_e32 v107, v77, v107
	v_add_f32_e32 v107, v78, v107
	v_add_f32_e32 v107, v79, v107
	v_add_f32_e32 v96, v107, v96
	v_cvt_pk_bf16_f32 v64, v64, v65
	v_cvt_pk_bf16_f32 v65, v66, v67
	v_cvt_pk_bf16_f32 v66, v68, v69
	v_cvt_pk_bf16_f32 v67, v70, v71
	v_cvt_pk_bf16_f32 v68, v72, v73
	v_cvt_pk_bf16_f32 v69, v74, v75
	v_cvt_pk_bf16_f32 v70, v76, v77
	v_cvt_pk_bf16_f32 v71, v78, v79
	s_waitcnt lgkmcnt(0)
	s_setprio 1
	v_mfma_f32_32x32x16_bf16 v[0:15], v[64:67], v[116:119], v[0:15]
	s_and_b64 vcc, exec, s[2:3]
	v_mfma_f32_32x32x16_bf16 v[48:63], v[64:67], v[124:127], v[48:63]
	v_mfma_f32_32x32x16_bf16 v[32:47], v[64:67], v[136:139], v[32:47]
	v_mfma_f32_32x32x16_bf16 v[16:31], v[64:67], v[144:147], v[16:31]
	v_mfma_f32_32x32x16_bf16 v[0:15], v[68:71], v[120:123], v[0:15]
	v_mfma_f32_32x32x16_bf16 v[48:63], v[68:71], v[132:135], v[48:63]
	v_mfma_f32_32x32x16_bf16 v[32:47], v[68:71], v[140:143], v[32:47]
	v_mfma_f32_32x32x16_bf16 v[16:31], v[68:71], v[148:151], v[16:31]
	s_waitcnt lgkmcnt(0)
	v_mfma_f32_32x32x16_bf16 v[64:79], v[98:101], v[92:95], 0
	v_mfma_f32_32x32x16_bf16 v[64:79], v[102:105], v[88:91], v[64:79]
	v_mfma_f32_32x32x16_bf16 v[64:79], v[112:115], v[84:87], v[64:79]
	v_mfma_f32_32x32x16_bf16 v[64:79], v[108:111], v[80:83], v[64:79]
	s_setprio 0
	s_cbranch_vccnz .LBB0_1944
	v_add3_u32 v80, s88, v97, v130
	v_add_u32_e32 v88, 0x400, v80
	v_add_u32_e32 v90, 0x408, v80
	v_add_u32_e32 v92, 0x420, v80
	v_add_u32_e32 v94, 0x428, v80
	v_add_u32_e32 v81, 0x440, v80
	v_add_u32_e32 v82, 0x448, v80
	v_add_u32_e32 v84, 0x460, v80
	v_add_u32_e32 v86, 0x468, v80
	ds_read2_b32 v[80:81], v81 offset1:1
	ds_read2_b32 v[82:83], v82 offset1:1
	ds_read2_b32 v[84:85], v84 offset1:1
	ds_read2_b32 v[86:87], v86 offset1:1
	ds_read2_b32 v[88:89], v88 offset1:1
	ds_read2_b32 v[90:91], v90 offset1:1
	ds_read2_b32 v[92:93], v92 offset1:1
	ds_read2_b32 v[94:95], v94 offset1:1
	s_waitcnt lgkmcnt(0)
	v_pk_add_f32 v[78:79], v[78:79], v[86:87]
	v_pk_add_f32 v[76:77], v[76:77], v[84:85]
	v_pk_add_f32 v[74:75], v[74:75], v[82:83]
	v_pk_add_f32 v[72:73], v[72:73], v[80:81]
	v_pk_add_f32 v[70:71], v[70:71], v[94:95]
	v_pk_add_f32 v[68:69], v[68:69], v[92:93]
	v_pk_add_f32 v[66:67], v[66:67], v[90:91]
	v_pk_add_f32 v[64:65], v[64:65], v[88:89]
.LBB0_1944:
	s_lshl_b32 s0, s54, 2
	s_add_i32 s0, s0, 0
	s_add_i32 s0, s0, 0x24000
	ds_read_b64_tr_b16 v[80:81], v106 offset:0x2000
	ds_read_b64_tr_b16 v[82:83], v106 offset:0x2800
	ds_read_b64_tr_b16 v[84:85], v106 offset:0x3000
	ds_read_b64_tr_b16 v[86:87], v106 offset:0x3800
	ds_read_b64_tr_b16 v[88:89], v106 offset:0x2200
	ds_read_b64_tr_b16 v[90:91], v106 offset:0x2a00
	ds_read_b64_tr_b16 v[92:93], v106 offset:0x3200
	ds_read_b64_tr_b16 v[94:95], v106 offset:0x3a00
	ds_read_b64_tr_b16 v[98:99], v106 offset:0x2400
	ds_read_b64_tr_b16 v[100:101], v106 offset:0x2c00
	ds_read_b64_tr_b16 v[102:103], v106 offset:0x3400
	ds_read_b64_tr_b16 v[104:105], v106 offset:0x3c00
	ds_read_b64_tr_b16 v[108:109], v106 offset:0x2600
	ds_read_b64_tr_b16 v[110:111], v106 offset:0x2e00
	ds_read_b64_tr_b16 v[112:113], v106 offset:0x3600
	ds_read_b64_tr_b16 v[114:115], v106 offset:0x3e00
	s_nop 7
	s_setprio 2
	v_exp_f32_e32 v97, v64
	v_exp_f32_e32 v65, v65
	v_exp_f32_e32 v106, v66
	v_exp_f32_e32 v67, v67
	v_exp_f32_e32 v68, v68
	v_exp_f32_e32 v69, v69
	v_add_f32_e32 v64, v65, v97
	v_exp_f32_e32 v70, v70
	v_add_f32_e32 v64, v106, v64
	v_exp_f32_e32 v71, v71
	v_add_f32_e32 v64, v67, v64
	v_exp_f32_e32 v72, v72
	v_add_f32_e32 v64, v68, v64
	v_exp_f32_e32 v73, v73
	v_add_f32_e32 v64, v69, v64
	v_exp_f32_e32 v74, v74
	v_add_f32_e32 v64, v70, v64
	v_exp_f32_e32 v75, v75
	v_add_f32_e32 v64, v71, v64
	v_exp_f32_e32 v76, v76
	v_add_f32_e32 v64, v72, v64
	v_exp_f32_e32 v77, v77
	v_add_f32_e32 v64, v73, v64
	v_exp_f32_e32 v78, v78
	v_add_f32_e32 v64, v74, v64
	v_exp_f32_e32 v79, v79
	v_add_f32_e32 v64, v75, v64
	v_add_f32_e32 v64, v76, v64
	v_add_f32_e32 v64, v77, v64
	v_add_f32_e32 v64, v78, v64
	v_add_f32_e32 v64, v79, v64
	v_add_f32_e32 v64, v96, v64
	v_cvt_pk_bf16_f32 v66, v97, v65
	v_cvt_pk_bf16_f32 v67, v106, v67
	v_cvt_pk_bf16_f32 v68, v68, v69
	v_cvt_pk_bf16_f32 v69, v70, v71
	v_cvt_pk_bf16_f32 v70, v72, v73
	v_cvt_pk_bf16_f32 v71, v74, v75
	v_cvt_pk_bf16_f32 v72, v76, v77
	v_cvt_pk_bf16_f32 v73, v78, v79
	s_waitcnt lgkmcnt(0)
; template <int TAG = 0> DI int fresh_tid(int wv) { int l; asm volatile("v_mbcnt_lo_u32_b32 %0, -1, 0\n\tv_mbcnt_hi_u32_b32 %0, -1, %0 ; site %1" : "=v"(l) : "n"(TAG)); return wv * 64 + l; }
; DI unsigned short f2bf(float x) { unsigned u = __float_as_uint(x); u += 0x7fffu + ((u >> 16) & 1u); return (unsigned short)(u >> 16); }
; DI int crow(int r, int hi) { return (r & 3) + 8 * (r >> 2) + 4 * hi; }
; DI float swap_sum(float v) { auto rr = __builtin_amdgcn_permlane32_swap(__float_as_uint(v), __float_as_uint(v), false, false); return __uint_as_float(rr[0]) + __uint_as_float(rr[1]); }
; DI void pv_mma(f32x16* o, const s16x4* vf, bf16x8 pa0, bf16x8 pa1) {
;     ...
; #pragma unroll
;     for (int d0 = 0; d0 < 4; ++d0) {
;         o[d0] = __builtin_amdgcn_mfma_f32_32x32x16_bf16(pa0, ATT_PK(vf[4 * d0], vf[4 * d0 + 1]), o[d0], 0, 0, 0);
;         o[d0] = __builtin_amdgcn_mfma_f32_32x32x16_bf16(pa1, ATT_PK(vf[4 * d0 + 2], vf[4 * d0 + 3]), o[d0], 0, 0, 0); }
;     ...
; }
; template <int DQK, int MODE, int LDQ, int LDK, int LDV> ...
;     ...
;     l_reg = swap_sum(l_reg);
;     { const int lane2 = fresh_tid<110 + MODE>(wv) & 63, r32 = lane2 & 31, hi = lane2 >> 5;
;     if (hi == 0) li_l[r32] = l_reg;
;     asm volatile("s_waitcnt lgkmcnt(0)" ::: "memory");
;     float s0v[MODE == 2 ? 16 : 1][4];
;     if constexpr (MODE == 2) {
; #pragma unroll
;         for (int r = 0; r < 16; ++r)
; #pragma unroll
;             for (int d0 = 0; d0 < 4; ++d0) s0v[r][d0] = S0[(size_t)(wid * 32 + crow(r, hi)) * 512 + d0 * 32 + r32];
;     }
; #pragma unroll
;     for (int r = 0; r < 16; ++r) { const int orow = wid * 32 + crow(r, hi); const float rl = __builtin_amdgcn_rcpf(li_l[crow(r, hi)]);
;         if constexpr (MODE == 0) {
; #pragma unroll
;             for (int d0 = 0; d0 < 4; ++d0) AOb[(size_t)orow * 1024 + d0 * 32 + r32] = f2bf(o[d0][r] * rl);
;         } else if constexpr (MODE == 1) {
; #pragma unroll
;             for (int d0 = 0; d0 < 4; ++d0) S0[(size_t)orow * 512 + d0 * 32 + r32] = o[d0][r] * rl;
	s_setprio 1
	v_mfma_f32_32x32x16_bf16 v[0:15], v[66:69], v[80:83], v[0:15]
	v_mfma_f32_32x32x16_bf16 v[48:63], v[66:69], v[88:91], v[48:63]
	v_mfma_f32_32x32x16_bf16 v[32:47], v[66:69], v[98:101], v[32:47]
	v_mfma_f32_32x32x16_bf16 v[16:31], v[66:69], v[108:111], v[16:31]
	v_mfma_f32_32x32x16_bf16 v[0:15], v[70:73], v[84:87], v[0:15]
	v_mfma_f32_32x32x16_bf16 v[48:63], v[70:73], v[92:95], v[48:63]
	v_mfma_f32_32x32x16_bf16 v[32:47], v[70:73], v[102:105], v[32:47]
	v_mfma_f32_32x32x16_bf16 v[16:31], v[70:73], v[112:115], v[16:31]
	s_setprio 0
	v_mbcnt_lo_u32_b32 v66, -1, 0
	v_mbcnt_hi_u32_b32 v66, -1, v66
	v_mov_b32_e32 v67, v64
	v_and_b32_e32 v65, 31, v66
	v_bfe_u32 v66, v66, 5, 1
	v_permlane32_swap_b32_e32 v64, v67
	v_cmp_eq_u32_e32 vcc, 0, v66
	s_and_saveexec_b64 s[2:3], vcc
	v_lshl_add_u32 v68, v65, 2, s0
	v_add_f32_e32 v64, v64, v67
	ds_write_b32 v68, v64
	s_or_b64 exec, exec, s[2:3]
	s_waitcnt lgkmcnt(0)
	v_lshl_add_u32 v68, v66, 4, s0
	ds_read_b128 v[70:73], v68
	ds_read_b128 v[74:77], v68 offset:32
	s_lshl_b64 s[58:59], s[40:41], 11
	v_readlane_b32 s1, v255, 2
	s_add_u32 s1, s1, s58
	v_readlane_b32 s2, v255, 0
	s_addc_u32 s2, s2, s59
	s_lshl_b32 s3, s87, 2
	s_waitcnt lgkmcnt(0)
	v_rcp_f32_e32 v69, v70
	s_add_u32 s54, s1, s3
	v_lshl_or_b32 v66, v66, 2, s94
	s_addc_u32 s55, s2, 0
	v_lshlrev_b32_e32 v130, 2, v65
	v_ashrrev_i32_e32 v67, 31, v66
	v_lshl_add_u64 v[64:65], s[54:55], 0, v[130:131]
	v_lshlrev_b64 v[78:79], 11, v[66:67]
	v_lshl_add_u64 v[78:79], v[64:65], 0, v[78:79]
	v_mul_f32_e32 v0, v0, v69
	global_store_dword v[78:79], v0, off
	v_mul_f32_e32 v0, v48, v69
	global_store_dword v[78:79], v0, off offset:128
	v_mul_f32_e32 v0, v32, v69
	global_store_dword v[78:79], v0, off offset:256
	v_mul_f32_e32 v0, v16, v69
	global_store_dword v[78:79], v0, off offset:384
	v_rcp_f32_e32 v0, v71
	v_or_b32_e32 v70, 1, v66
	v_ashrrev_i32_e32 v71, 31, v70
	v_lshlrev_b64 v[70:71], 11, v[70:71]
	v_lshl_add_u64 v[70:71], v[64:65], 0, v[70:71]
	v_mul_f32_e32 v1, v1, v0
	global_store_dword v[70:71], v1, off
	v_mul_f32_e32 v1, v49, v0
	global_store_dword v[70:71], v1, off offset:128
	v_mul_f32_e32 v1, v33, v0
	v_mul_f32_e32 v0, v17, v0
	v_rcp_f32_e32 v16, v72
	global_store_dword v[70:71], v0, off offset:384
	v_or_b32_e32 v0, 2, v66
	global_store_dword v[70:71], v1, off offset:256
	v_ashrrev_i32_e32 v1, 31, v0
	v_lshlrev_b64 v[0:1], 11, v[0:1]
	v_lshl_add_u64 v[0:1], v[64:65], 0, v[0:1]
	v_mul_f32_e32 v2, v2, v16
	global_store_dword v[0:1], v2, off
	v_mul_f32_e32 v2, v50, v16
	global_store_dword v[0:1], v2, off offset:128
	v_mul_f32_e32 v2, v34, v16
	global_store_dword v[0:1], v2, off offset:256
	v_mul_f32_e32 v2, v18, v16
	global_store_dword v[0:1], v2, off offset:384
	v_rcp_f32_e32 v2, v73
	v_or_b32_e32 v0, 3, v66
	v_ashrrev_i32_e32 v1, 31, v0
	v_lshlrev_b64 v[0:1], 11, v[0:1]
	v_lshl_add_u64 v[0:1], v[64:65], 0, v[0:1]
	v_mul_f32_e32 v3, v3, v2
	global_store_dword v[0:1], v3, off
	v_mul_f32_e32 v3, v51, v2
	global_store_dword v[0:1], v3, off offset:128
	v_mul_f32_e32 v3, v35, v2
	v_mul_f32_e32 v2, v19, v2
	global_store_dword v[0:1], v2, off offset:384
	v_rcp_f32_e32 v2, v74
	global_store_dword v[0:1], v3, off offset:256
	v_or_b32_e32 v0, 8, v66
	v_ashrrev_i32_e32 v1, 31, v0
	v_lshlrev_b64 v[0:1], 11, v[0:1]
	v_lshl_add_u64 v[0:1], v[64:65], 0, v[0:1]
	v_mul_f32_e32 v3, v4, v2
	global_store_dword v[0:1], v3, off
	v_mul_f32_e32 v3, v52, v2
	global_store_dword v[0:1], v3, off offset:128
	v_mul_f32_e32 v3, v36, v2
	v_mul_f32_e32 v2, v20, v2
	global_store_dword v[0:1], v2, off offset:384
	v_rcp_f32_e32 v2, v75
	global_store_dword v[0:1], v3, off offset:256
	v_or_b32_e32 v0, 9, v66
	v_ashrrev_i32_e32 v1, 31, v0
	v_lshlrev_b64 v[0:1], 11, v[0:1]
	v_lshl_add_u64 v[0:1], v[64:65], 0, v[0:1]
	v_mul_f32_e32 v3, v5, v2
	global_store_dword v[0:1], v3, off
	v_mul_f32_e32 v3, v53, v2
	global_store_dword v[0:1], v3, off offset:128
	v_mul_f32_e32 v3, v37, v2
	v_mul_f32_e32 v2, v21, v2
	global_store_dword v[0:1], v2, off offset:384
	v_rcp_f32_e32 v2, v76
	global_store_dword v[0:1], v3, off offset:256
	v_or_b32_e32 v0, 10, v66
	v_ashrrev_i32_e32 v1, 31, v0
	v_lshlrev_b64 v[0:1], 11, v[0:1]
	v_lshl_add_u64 v[0:1], v[64:65], 0, v[0:1]
	v_mul_f32_e32 v3, v6, v2
	global_store_dword v[0:1], v3, off
	v_mul_f32_e32 v3, v54, v2
	global_store_dword v[0:1], v3, off offset:128
	v_mul_f32_e32 v3, v38, v2
	v_mul_f32_e32 v2, v22, v2
	v_rcp_f32_e32 v6, v77
	global_store_dword v[0:1], v3, off offset:256
	global_store_dword v[0:1], v2, off offset:384
	v_or_b32_e32 v0, 11, v66
	v_ashrrev_i32_e32 v1, 31, v0
	v_lshlrev_b64 v[0:1], 11, v[0:1]
	v_lshl_add_u64 v[4:5], v[64:65], 0, v[0:1]
	v_mul_f32_e32 v0, v7, v6
	global_store_dword v[4:5], v0, off
	v_mul_f32_e32 v0, v55, v6
	global_store_dword v[4:5], v0, off offset:128
	v_mul_f32_e32 v0, v39, v6
	global_store_dword v[4:5], v0, off offset:256
	ds_read_b128 v[0:3], v68 offset:64
	v_mul_f32_e32 v6, v23, v6
	global_store_dword v[4:5], v6, off offset:384
	ds_read_b128 v[4:7], v68 offset:96
	v_or_b32_e32 v16, 16, v66
	s_waitcnt lgkmcnt(0)
; DI unsigned short f2bf(float x) { unsigned u = __float_as_uint(x); u += 0x7fffu + ((u >> 16) & 1u); return (unsigned short)(u >> 16); }
; DI int crow(int r, int hi) { return (r & 3) + 8 * (r >> 2) + 4 * hi; }
; template <int DQK, int MODE, int LDQ, int LDK, int LDV> ...
;     ...
;     for (int r = 0; r < 16; ++r) { const int orow = wid * 32 + crow(r, hi); const float rl = __builtin_amdgcn_rcpf(li_l[crow(r, hi)]);
;         if constexpr (MODE == 0) {
; #pragma unroll
;             for (int d0 = 0; d0 < 4; ++d0) AOb[(size_t)orow * 1024 + d0 * 32 + r32] = f2bf(o[d0][r] * rl);
;         } else if constexpr (MODE == 1) {
; #pragma unroll
;             for (int d0 = 0; d0 < 4; ++d0) S0[(size_t)orow * 512 + d0 * 32 + r32] = o[d0][r] * rl;
	v_rcp_f32_e32 v0, v0
	v_ashrrev_i32_e32 v17, 31, v16
	v_lshlrev_b64 v[16:17], 11, v[16:17]
	v_lshl_add_u64 v[16:17], v[64:65], 0, v[16:17]
	v_mul_f32_e32 v8, v8, v0
	global_store_dword v[16:17], v8, off
	v_mul_f32_e32 v8, v56, v0
	global_store_dword v[16:17], v8, off offset:128
	v_mul_f32_e32 v8, v40, v0
	global_store_dword v[16:17], v8, off offset:256
	v_mul_f32_e32 v0, v24, v0
	v_rcp_f32_e32 v8, v1
	global_store_dword v[16:17], v0, off offset:384
	v_or_b32_e32 v0, 17, v66
	v_ashrrev_i32_e32 v1, 31, v0
	v_lshlrev_b64 v[0:1], 11, v[0:1]
	v_lshl_add_u64 v[0:1], v[64:65], 0, v[0:1]
	v_mul_f32_e32 v9, v9, v8
	global_store_dword v[0:1], v9, off
	v_mul_f32_e32 v9, v57, v8
	global_store_dword v[0:1], v9, off offset:128
	v_mul_f32_e32 v9, v41, v8
	v_mul_f32_e32 v8, v25, v8
	v_rcp_f32_e32 v2, v2
	global_store_dword v[0:1], v9, off offset:256
	global_store_dword v[0:1], v8, off offset:384
	v_or_b32_e32 v0, 18, v66
	v_ashrrev_i32_e32 v1, 31, v0
	v_lshlrev_b64 v[0:1], 11, v[0:1]
	v_lshl_add_u64 v[0:1], v[64:65], 0, v[0:1]
	v_mul_f32_e32 v8, v10, v2
	global_store_dword v[0:1], v8, off
	v_mul_f32_e32 v8, v58, v2
	global_store_dword v[0:1], v8, off offset:128
	v_mul_f32_e32 v8, v42, v2
	v_mul_f32_e32 v2, v26, v2
	global_store_dword v[0:1], v2, off offset:384
	v_rcp_f32_e32 v2, v3
	global_store_dword v[0:1], v8, off offset:256
	v_or_b32_e32 v0, 19, v66
	v_ashrrev_i32_e32 v1, 31, v0
	v_lshlrev_b64 v[0:1], 11, v[0:1]
	v_lshl_add_u64 v[0:1], v[64:65], 0, v[0:1]
	v_mul_f32_e32 v3, v11, v2
	global_store_dword v[0:1], v3, off
	v_mul_f32_e32 v3, v59, v2
	global_store_dword v[0:1], v3, off offset:128
	v_mul_f32_e32 v3, v43, v2
	v_mul_f32_e32 v2, v27, v2
	global_store_dword v[0:1], v2, off offset:384
	v_rcp_f32_e32 v2, v4
	global_store_dword v[0:1], v3, off offset:256
	v_or_b32_e32 v0, 24, v66
	v_ashrrev_i32_e32 v1, 31, v0
	v_lshlrev_b64 v[0:1], 11, v[0:1]
	v_lshl_add_u64 v[0:1], v[64:65], 0, v[0:1]
	v_mul_f32_e32 v3, v12, v2
	global_store_dword v[0:1], v3, off
	v_mul_f32_e32 v3, v60, v2
	global_store_dword v[0:1], v3, off offset:128
	v_mul_f32_e32 v3, v44, v2
	v_mul_f32_e32 v2, v28, v2
	global_store_dword v[0:1], v2, off offset:384
	v_rcp_f32_e32 v2, v5
	global_store_dword v[0:1], v3, off offset:256
	v_or_b32_e32 v0, 25, v66
	v_ashrrev_i32_e32 v1, 31, v0
	v_lshlrev_b64 v[0:1], 11, v[0:1]
	v_lshl_add_u64 v[0:1], v[64:65], 0, v[0:1]
	v_mul_f32_e32 v3, v13, v2
	global_store_dword v[0:1], v3, off
	v_mul_f32_e32 v3, v61, v2
	global_store_dword v[0:1], v3, off offset:128
	v_mul_f32_e32 v3, v45, v2
	v_mul_f32_e32 v2, v29, v2
	global_store_dword v[0:1], v2, off offset:384
	v_rcp_f32_e32 v2, v6
	global_store_dword v[0:1], v3, off offset:256
	v_or_b32_e32 v0, 26, v66
	v_ashrrev_i32_e32 v1, 31, v0
	v_lshlrev_b64 v[0:1], 11, v[0:1]
	v_lshl_add_u64 v[0:1], v[64:65], 0, v[0:1]
	v_mul_f32_e32 v3, v14, v2
	global_store_dword v[0:1], v3, off
	v_mul_f32_e32 v3, v62, v2
	global_store_dword v[0:1], v3, off offset:128
	v_mul_f32_e32 v3, v46, v2
	v_mul_f32_e32 v2, v30, v2
	global_store_dword v[0:1], v2, off offset:384
	v_rcp_f32_e32 v2, v7
	global_store_dword v[0:1], v3, off offset:256
	v_or_b32_e32 v0, 27, v66
	v_ashrrev_i32_e32 v1, 31, v0
	v_lshlrev_b64 v[0:1], 11, v[0:1]
	v_lshl_add_u64 v[0:1], v[64:65], 0, v[0:1]
	v_mul_f32_e32 v3, v15, v2
	global_store_dword v[0:1], v3, off
	v_mul_f32_e32 v3, v63, v2
	global_store_dword v[0:1], v3, off offset:128
	v_mul_f32_e32 v3, v47, v2
	v_mul_f32_e32 v2, v31, v2
	global_store_dword v[0:1], v3, off offset:256
	global_store_dword v[0:1], v2, off offset:384
	s_waitcnt vmcnt(0)
	s_barrier
; DI float bf2f(unsigned short h) { return __uint_as_float((unsigned)h << 16); }
; template <int DQK, int MODE, int LDQ, int LDK, int LDV> ...
;     ...
;     int kgo[NKP], vgo[2];
; #pragma unroll
;     for (int i = 0; i < NKP; ++i) { const int L = (wid + 8 * i) * 64 + lane, row = L / CPR, slot = L % CPR, cc = (slot & ~7) | ((slot & 7) ^ ((row >> 1) & 7)); kgo[i] = row * LDK + cc * 8; }
; #pragma unroll
;     for (int i = 0; i < 2; ++i) { const int L = (2 * wid + i) * 64 + lane, st = L >> 5, w5 = L & 31, kk = (st >> 2) * 8 + (w5 >> 2), c = (st & 3) * 32 + (w5 & 3) * 8;
;         const int k = (kk & ~0xC) | ((kk & 4) << 1) | ((kk & 8) >> 1); vgo[i] = k * LDV + c; }
;     ...
;     ATT_DMA_K(0); ATT_DMA_K(1); ATT_DMA_V(0, 0); ATT_DMA_K(2); ATT_DMA_V(1, 1);
;     bf16x8 qr[ND0];
;     { const bf16_t* Qw = Qb + (size_t)(wid * 32 + r32) * LDQ + hi * 8;
; #pragma unroll
;       for (int d0 = 0; d0 < ND0; ++d0) qr[d0] = *(const bf16x8*)(Qw + d0 * 16);
;       if constexpr (MODE == 0) {
;           float ss = 0.f;
; #pragma unroll
;           for (int d0 = 0; d0 < ND0; ++d0)
; #pragma unroll
;               for (int j = 0; j < 8; ++j) { const float f = bf2f((unsigned short)qr[d0][j]); ss += f * f; }
;           ss = swap_sum(ss);
;           const float rstd = rsqrtf(ss * (1.f / DQK) + EPS) * C;
; #pragma unroll
;           for (int d0 = 0; d0 < ND0; ++d0) { const float* g = gq + d0 * 16 + hi * 8;
;               { float f[8]; _Pragma("unroll") for (int j = 0; j < 8; ++j) f[j] = bf2f((unsigned short)qr[d0][j]) * rstd * g[j];
;                 u32x4 w = {cvtpk(f[0], f[1]), cvtpk(f[2], f[3]), cvtpk(f[4], f[5]), cvtpk(f[6], f[7])}; qr[d0] = __builtin_bit_cast(bf16x8, w); asm volatile("" ::: "memory"); } }
;       } }
;     const int qlo = q0 + wid * 32, qpos = qlo + r32;
;     const int tL = MODE == 0 ? 0 : (qlo >= 191 ? (qlo - 127) >> 6 : 0), tR = MODE == 0 ? NT : min(NT, (qlo + 222) >> 6);
;     float fL = 1.f, fR = 1.f; if constexpr (MODE != 0) { fL = __builtin_amdgcn_exp2f(bt[0]); fR = __builtin_amdgcn_exp2f(-bt[448]); }
;     ...
;     const int vbase = (int)(unsigned)(size_t)lds + V_OFF + v_rd_base(lane);
;     ...
;     constexpr int NDA = ND0 > 6 ? 6 : ND0;
;     ...
;     f32x16 pA, pB; bf16x8 pa0, pa1;
;     int v0 = 0, v1 = 1, v2 = 2;
;     ATT_TOP(NKP + 2);
;     { bf16x8 kf[NDA]; k_reads<DQK, 0, NDA>(kf, lds, 0, r32, hi); ATT_LGKM0(); qk_mma<0, NDA>(pA, kf, qr);
	v_mbcnt_lo_u32_b32 v7, -1, 0
	v_mbcnt_hi_u32_b32 v7, -1, v7
	s_mov_b64 s[4:5], 0x880
	v_add_u32_e32 v0, s33, v7
	v_bfe_u32 v4, v0, 2, 2
	v_readfirstlane_b32 s0, v0
	s_ashr_i32 s2, s0, 31
	s_ashr_i32 s1, s0, 6
	v_mov_b32_e32 v1, s0
	v_bfi_b32 v1, s63, v1, v7
	s_lshr_b32 s2, s2, 29
	v_add_u32_e32 v3, s2, v1
	s_lshl_b32 s2, s1, 7
	v_ashrrev_i32_e32 v9, 3, v3
	v_and_b32_e32 v3, 0x1ffffff8, v3
	s_ashr_i32 s3, s2, 4
	v_lshrrev_b32_e32 v0, 2, v0
	v_sub_u32_e32 v1, v1, v3
	v_lshrrev_b32_e32 v3, 1, v9
	v_lshlrev_b32_e32 v18, 3, v7
	s_and_b32 s2, s3, -16
	v_and_b32_e32 v6, 4, v0
	s_lshr_b32 s3, s3, 0
	v_bitop3_b32 v1, v3, v1, 7 bitop3:0x6c
	v_and_b32_e32 v3, 32, v7
	v_and_b32_e32 v5, 24, v18
	s_and_b32 s3, s3, 8
	v_or3_b32 v0, v6, v4, s2
	v_or_b32_e32 v10, v3, v5
	v_or_b32_e32 v0, s3, v0
	v_lshl_or_b32 v96, v0, 11, v10
	v_lshlrev_b32_e32 v0, 11, v9
	v_lshl_add_u32 v0, v1, 3, v0
	v_ashrrev_i32_e32 v1, 31, v0
	v_lshlrev_b64 v[10:11], 1, v[0:1]
	v_lshl_add_u64 v[12:13], s[46:47], 0, v[10:11]
	v_lshl_add_u64 v[12:13], v[12:13], 0, s[4:5]
	s_lshl_b32 s4, s1, 10
	s_add_i32 s94, s4, 0
	s_mov_b32 m0, s94
	v_lshl_add_u64 v[10:11], s[48:49], 0, v[10:11]
	s_mov_b64 s[4:5], 0x40080
	global_load_lds_dwordx4 v[12:13], off
	v_lshl_add_u64 v[12:13], v[10:11], 0, s[4:5]
	s_add_i32 m0, s94, 0x2000
	s_lshl_b32 s4, s1, 11
	v_ashrrev_i32_e32 v97, 31, v96
	global_load_lds_dwordx4 v[12:13], off
	s_add_i32 s6, s4, 0
	v_lshlrev_b64 v[12:13], 1, v[96:97]
	s_add_i32 s48, s6, 0x18000
	v_lshl_add_u64 v[14:15], s[46:47], 0, v[12:13]
	v_lshl_add_u64 v[16:17], v[14:15], 0, s[96:97]
	s_mov_b32 m0, s48
	s_mov_b64 s[4:5], 0xc80
	global_load_lds_dwordx4 v[16:17], off
	v_lshl_add_u64 v[14:15], v[14:15], 0, s[4:5]
	s_add_i32 m0, s6, 0x18400
	s_mov_b64 s[4:5], 0x80080
	v_or_b32_e32 v98, 64, v96
	global_load_lds_dwordx4 v[14:15], off
	v_lshl_add_u64 v[10:11], v[10:11], 0, s[4:5]
	s_add_i32 m0, s94, 0x4000
	v_ashrrev_i32_e32 v99, 31, v98
	global_load_lds_dwordx4 v[10:11], off
	s_add_i32 m0, s6, 0x1c000
	v_lshl_add_u64 v[10:11], s[52:53], 0, v[12:13]
	v_and_b32_e32 v2, 31, v7
	global_load_lds_dwordx4 v[10:11], off
	v_lshl_add_u64 v[10:11], v[98:99], 1, s[52:53]
	s_add_i32 m0, s6, 0x1c400
	s_lshl_b32 s46, s1, 5
	global_load_lds_dwordx4 v[10:11], off
	v_or_b32_e32 v10, s46, v2
	v_ashrrev_i32_e32 v11, 31, v10
	v_bfe_u32 v8, v7, 5, 1
	v_lshlrev_b64 v[10:11], 12, v[10:11]
	v_lshl_add_u64 v[10:11], s[44:45], 0, v[10:11]
	v_lshlrev_b32_e32 v130, 4, v8
	v_lshl_add_u64 v[10:11], v[10:11], 0, v[130:131]
	global_load_dwordx4 v[92:95], v[10:11], off offset:1152
	global_load_dwordx4 v[88:91], v[10:11], off offset:1184
	global_load_dwordx4 v[84:87], v[10:11], off offset:1216
	global_load_dwordx4 v[80:83], v[10:11], off offset:1248
	v_and_b32_e32 v11, 0x70, v18
	v_mov_b32_e32 v9, s88
	v_mov_b32_e32 v10, s81
	v_lshl_add_u32 v114, v2, 7, 0
	v_bitop3_b32 v115, v130, v18, s64 bitop3:0x78
	v_bitop3_b32 v117, v130, v11, 64 bitop3:0x36
	s_add_i32 s4, s46, s89
	ds_read_b32 v9, v9
	ds_read_b32 v10, v10
	s_waitcnt vmcnt(3)
	s_barrier
	v_add_u32_e32 v107, v114, v115
	v_bitop3_b32 v116, v130, v11, 32 bitop3:0x36
	v_add_u32_e32 v109, v114, v117
	v_bitop3_b32 v118, v130, v11, s65 bitop3:0x36
	s_add_i32 s5, s4, 0xffffff81
	v_add_u32_e32 v108, v114, v116
	ds_read_b128 v[12:15], v107
	ds_read_b128 v[16:19], v108
	v_add_u32_e32 v110, v114, v118
	ds_read_b128 v[20:23], v109
	ds_read_b128 v[24:27], v110
	s_ashr_i32 s5, s5, 6
	s_cmpk_gt_i32 s4, 0xbe
	v_or_b32_e32 v111, s4, v2
	s_cselect_b32 s47, s5, 0
	s_addk_i32 s4, 0xde
	s_ashr_i32 s45, s4, 6
	s_waitcnt lgkmcnt(0)
	s_waitcnt vmcnt(0) lgkmcnt(0)
	v_mfma_f32_32x32x16_bf16 v[64:79], v[12:15], v[92:95], 0
	s_cmp_gt_i32 s47, 0
	s_cselect_b64 s[4:5], -1, 0
	s_cmp_lt_i32 s45, 1
	s_cselect_b64 s[6:7], -1, 0
	s_or_b64 s[4:5], s[6:7], s[4:5]
	s_and_b64 vcc, exec, s[4:5]
	v_mfma_f32_32x32x16_bf16 v[64:79], v[16:19], v[88:91], v[64:79]
	v_mfma_f32_32x32x16_bf16 v[64:79], v[20:23], v[84:87], v[64:79]
	v_mfma_f32_32x32x16_bf16 v[64:79], v[24:27], v[80:83], v[64:79]
	s_cbranch_vccnz .LBB0_1948
	v_lshlrev_b32_e32 v8, 2, v8
	v_sub_u32_e32 v8, v8, v111
	v_lshl_add_u32 v8, v8, 2, s88
	ds_read2_b32 v[12:13], v8 offset0:240 offset1:241
	ds_read2_b32 v[14:15], v8 offset0:242 offset1:243
	ds_read2_b32 v[16:17], v8 offset0:248 offset1:249
	ds_read2_b32 v[18:19], v8 offset0:250 offset1:251
	ds_read2_b32 v[20:21], v8 offset0:224 offset1:225
	ds_read2_b32 v[22:23], v8 offset0:226 offset1:227
	ds_read2_b32 v[24:25], v8 offset0:232 offset1:233
	ds_read2_b32 v[26:27], v8 offset0:234 offset1:235
	s_waitcnt lgkmcnt(4)
	v_pk_add_f32 v[78:79], v[78:79], v[18:19]
	v_pk_add_f32 v[76:77], v[76:77], v[16:17]
	v_pk_add_f32 v[74:75], v[74:75], v[14:15]
	v_pk_add_f32 v[72:73], v[72:73], v[12:13]
	s_waitcnt lgkmcnt(0)
	v_pk_add_f32 v[70:71], v[70:71], v[26:27]
	v_pk_add_f32 v[68:69], v[68:69], v[24:25]
	v_pk_add_f32 v[66:67], v[66:67], v[22:23]
	v_pk_add_f32 v[64:65], v[64:65], v[20:21]

; #define LAS __attribute__((address_space(3)))
; DI void expsum(f32x16& p, float& l_reg, bf16x8& pa0, bf16x8& pa1) {
; #pragma unroll
;     for (int r = 0; r < 16; ++r) p[r] = __builtin_amdgcn_exp2f(p[r]);
;     float ps = 0.f;
; #pragma unroll
;     for (int r = 0; r < 16; ++r) ps += p[r];
;     l_reg += ps; asm volatile("" : "+v"(l_reg));
;     ...
;     ATT_PK4(p, 0, pa0); ATT_PK4(p, 8, pa1);
;     ...
; }
; DI int v_rd_base(int lane) { return ((lane & 3) << 3) | (((lane >> 2) & 3) << 6) | (((lane >> 4) & 1) << 5) | (((lane >> 5) & 1) << 8); }
; template <int OFF> DI s16x4 tr_read(int vb) { s16x4 r; asm volatile("ds_read_b64_tr_b16 %0, %1 offset:%2" : "=&v"(r) : "v"(vb), "i"(OFF) : "memory"); return r; }
; template <int H> DI void v_reads(s16x4* vf, int vb) {
;     vf[0] = tr_read<v_rd_off(0, 2 * H, 0)>(vb); vf[1] = tr_read<v_rd_off(0, 2 * H, 1)>(vb); vf[2] = tr_read<v_rd_off(0, 2 * H + 1, 0)>(vb); vf[3] = tr_read<v_rd_off(0, 2 * H + 1, 1)>(vb);
;     vf[4] = tr_read<v_rd_off(1, 2 * H, 0)>(vb); vf[5] = tr_read<v_rd_off(1, 2 * H, 1)>(vb); vf[6] = tr_read<v_rd_off(1, 2 * H + 1, 0)>(vb); vf[7] = tr_read<v_rd_off(1, 2 * H + 1, 1)>(vb);
;     vf[8] = tr_read<v_rd_off(2, 2 * H, 0)>(vb); vf[9] = tr_read<v_rd_off(2, 2 * H, 1)>(vb); vf[10] = tr_read<v_rd_off(2, 2 * H + 1, 0)>(vb); vf[11] = tr_read<v_rd_off(2, 2 * H + 1, 1)>(vb);
;     vf[12] = tr_read<v_rd_off(3, 2 * H, 0)>(vb); vf[13] = tr_read<v_rd_off(3, 2 * H, 1)>(vb); vf[14] = tr_read<v_rd_off(3, 2 * H + 1, 0)>(vb); vf[15] = tr_read<v_rd_off(3, 2 * H + 1, 1)>(vb);
; }
; DI void pv_mma(f32x16* o, const s16x4* vf, bf16x8 pa0, bf16x8 pa1) {
;     ...
; #pragma unroll
;     for (int d0 = 0; d0 < 4; ++d0) {
;         o[d0] = __builtin_amdgcn_mfma_f32_32x32x16_bf16(pa0, ATT_PK(vf[4 * d0], vf[4 * d0 + 1]), o[d0], 0, 0, 0);
;         o[d0] = __builtin_amdgcn_mfma_f32_32x32x16_bf16(pa1, ATT_PK(vf[4 * d0 + 2], vf[4 * d0 + 3]), o[d0], 0, 0, 0); }
;     ...
; }
; template <int DQK, int D0A, int D0B> DI void k_reads(bf16x8* kf, const LAS unsigned char* Ks, int half, int r32, int hi) {
; #pragma unroll
;     for (int d0 = D0A; d0 < D0B; ++d0) kf[d0 - D0A] = *(const LAS bf16x8*)(Ks + half * (32 * DQK * 2) + kswz<DQK>(r32, (d0 * 16 + hi * 8) * 2));
; }
; template <int D0A, int D0B> DI void qk_mma(f32x16& p, const bf16x8* kf, const bf16x8* qr) {
; #pragma unroll
;     for (int d0 = D0A; d0 < D0B; ++d0) {
.Lhw_d1_b_n1953:
	ds_read_b128 v[122:125], v196 offset:4096
	ds_read_b128 v[132:135], v197 offset:4096
	s_lshl_b32 s2, s23, 14
	ds_read_b128 v[136:139], v198 offset:4096
	ds_read_b128 v[140:143], v199 offset:4096
	v_add_u32_e32 v121, s2, v106
	ds_read_b64_tr_b16 v[144:145], v121 offset:0
	ds_read_b64_tr_b16 v[146:147], v121 offset:0x800
	ds_read_b64_tr_b16 v[148:149], v121 offset:0x1000
	ds_read_b64_tr_b16 v[150:151], v121 offset:0x1800
	ds_read_b64_tr_b16 v[152:153], v121 offset:0x200
	ds_read_b64_tr_b16 v[154:155], v121 offset:0xa00
	ds_read_b64_tr_b16 v[156:157], v121 offset:0x1200
	ds_read_b64_tr_b16 v[158:159], v121 offset:0x1a00
	ds_read_b64_tr_b16 v[162:163], v121 offset:0x400
	ds_read_b64_tr_b16 v[164:165], v121 offset:0xc00
	ds_read_b64_tr_b16 v[166:167], v121 offset:0x1400
	ds_read_b64_tr_b16 v[168:169], v121 offset:0x1c00
	ds_read_b64_tr_b16 v[170:171], v121 offset:0x600
	ds_read_b64_tr_b16 v[172:173], v121 offset:0xe00
	ds_read_b64_tr_b16 v[174:175], v121 offset:0x1600
	ds_read_b64_tr_b16 v[176:177], v121 offset:0x1e00
	s_setprio 2
	v_exp_f32_e32 v64, v64
	v_exp_f32_e32 v65, v65
	v_exp_f32_e32 v66, v66
	v_exp_f32_e32 v67, v67
	v_exp_f32_e32 v68, v68
	v_exp_f32_e32 v69, v69
	v_add_f32_e32 v126, v65, v64
	v_exp_f32_e32 v70, v70
	v_add_f32_e32 v126, v66, v126
	v_exp_f32_e32 v71, v71
	v_add_f32_e32 v126, v67, v126
	v_exp_f32_e32 v72, v72
	v_add_f32_e32 v126, v68, v126
	v_exp_f32_e32 v73, v73
	v_add_f32_e32 v126, v69, v126
	v_exp_f32_e32 v74, v74
	v_add_f32_e32 v126, v70, v126
	v_exp_f32_e32 v75, v75
	v_add_f32_e32 v126, v71, v126
	v_exp_f32_e32 v76, v76
	v_add_f32_e32 v126, v72, v126
	v_exp_f32_e32 v77, v77
	v_add_f32_e32 v126, v73, v126
	v_exp_f32_e32 v78, v78
	v_add_f32_e32 v126, v74, v126
	v_exp_f32_e32 v79, v79
	v_add_f32_e32 v126, v75, v126
	v_add_f32_e32 v126, v76, v126
	v_add_f32_e32 v126, v77, v126
	v_add_f32_e32 v126, v78, v126
	v_add_f32_e32 v126, v79, v126
	v_add_f32_e32 v120, v126, v120
	v_cvt_pk_bf16_f32 v64, v64, v65
	v_cvt_pk_bf16_f32 v65, v66, v67
	v_cvt_pk_bf16_f32 v66, v68, v69
	v_cvt_pk_bf16_f32 v67, v70, v71
	v_cvt_pk_bf16_f32 v68, v72, v73
	v_cvt_pk_bf16_f32 v69, v74, v75
	v_cvt_pk_bf16_f32 v70, v76, v77
	v_cvt_pk_bf16_f32 v71, v78, v79
	s_waitcnt lgkmcnt(0)
	s_setprio 1
	v_mfma_f32_32x32x16_bf16 v[0:15], v[64:67], v[144:147], v[0:15]
	s_sub_i32 s3, s0, s98
	s_cmp_lt_u32 s3, s100
	v_mfma_f32_32x32x16_bf16 v[48:63], v[64:67], v[152:155], v[48:63]
	v_mfma_f32_32x32x16_bf16 v[16:31], v[64:67], v[162:165], v[16:31]
	v_mfma_f32_32x32x16_bf16 v[32:47], v[64:67], v[170:173], v[32:47]
	v_mfma_f32_32x32x16_bf16 v[0:15], v[68:71], v[148:151], v[0:15]
	v_mfma_f32_32x32x16_bf16 v[48:63], v[68:71], v[156:159], v[48:63]
	v_mfma_f32_32x32x16_bf16 v[16:31], v[68:71], v[166:169], v[16:31]
	v_mfma_f32_32x32x16_bf16 v[32:47], v[68:71], v[174:177], v[32:47]
	v_mfma_f32_32x32x16_bf16 v[64:79], v[122:125], v[92:95], 0
	v_mfma_f32_32x32x16_bf16 v[64:79], v[132:135], v[88:91], v[64:79]
	v_mfma_f32_32x32x16_bf16 v[64:79], v[136:139], v[84:87], v[64:79]
	v_mfma_f32_32x32x16_bf16 v[64:79], v[140:143], v[80:83], v[64:79]
	s_setprio 0
	s_cbranch_scc1 .Lhw_d1_b_dtd1bias1
.Lhw_d1_b_n1955:
	s_add_i32 s3, s22, 0xffffc000
	s_and_b32 s3, s3, 0x6000
	v_add_u32_e32 v196, s3, v107
	v_add_u32_e32 v197, s3, v108
	v_add_u32_e32 v198, s3, v109
	v_add_u32_e32 v199, s3, v110
	ds_read_b128 v[124:127], v196
	ds_read_b128 v[132:135], v197
	ds_read_b128 v[136:139], v198
	ds_read_b128 v[140:143], v199
	ds_read_b64_tr_b16 v[144:145], v121 offset:0x2000
	ds_read_b64_tr_b16 v[146:147], v121 offset:0x2800
	ds_read_b64_tr_b16 v[148:149], v121 offset:0x3000
	ds_read_b64_tr_b16 v[150:151], v121 offset:0x3800
	ds_read_b64_tr_b16 v[152:153], v121 offset:0x2200
	ds_read_b64_tr_b16 v[154:155], v121 offset:0x2a00
	ds_read_b64_tr_b16 v[156:157], v121 offset:0x3200
	ds_read_b64_tr_b16 v[158:159], v121 offset:0x3a00
	ds_read_b64_tr_b16 v[162:163], v121 offset:0x2400
	ds_read_b64_tr_b16 v[164:165], v121 offset:0x2c00
	ds_read_b64_tr_b16 v[166:167], v121 offset:0x3400
	ds_read_b64_tr_b16 v[168:169], v121 offset:0x3c00
	ds_read_b64_tr_b16 v[170:171], v121 offset:0x2600
	ds_read_b64_tr_b16 v[172:173], v121 offset:0x2e00
	ds_read_b64_tr_b16 v[174:175], v121 offset:0x3600
	ds_read_b64_tr_b16 v[176:177], v121 offset:0x3e00
	s_setprio 2
	v_exp_f32_e32 v64, v64
	v_exp_f32_e32 v65, v65
	v_exp_f32_e32 v66, v66
	v_exp_f32_e32 v67, v67
	v_exp_f32_e32 v68, v68
	v_exp_f32_e32 v69, v69
	v_add_f32_e32 v121, v65, v64
	v_exp_f32_e32 v70, v70
	v_add_f32_e32 v121, v66, v121
	v_exp_f32_e32 v71, v71
	v_add_f32_e32 v121, v67, v121
	v_exp_f32_e32 v72, v72
	v_add_f32_e32 v121, v68, v121
	v_exp_f32_e32 v73, v73
	v_add_f32_e32 v121, v69, v121
	v_exp_f32_e32 v74, v74
	v_add_f32_e32 v121, v70, v121
	v_exp_f32_e32 v75, v75
	v_add_f32_e32 v121, v71, v121
	v_exp_f32_e32 v76, v76
	v_add_f32_e32 v121, v72, v121
	v_exp_f32_e32 v77, v77
	v_add_f32_e32 v121, v73, v121
	v_exp_f32_e32 v78, v78
	v_add_f32_e32 v121, v74, v121
	v_exp_f32_e32 v79, v79
	v_add_f32_e32 v121, v75, v121
	v_add_f32_e32 v121, v76, v121
	v_add_f32_e32 v121, v77, v121
	v_add_f32_e32 v121, v78, v121
	v_add_f32_e32 v121, v79, v121
	v_add_f32_e32 v120, v120, v121
	v_cvt_pk_bf16_f32 v64, v64, v65
	v_cvt_pk_bf16_f32 v65, v66, v67
	v_cvt_pk_bf16_f32 v66, v68, v69
	v_cvt_pk_bf16_f32 v67, v70, v71
	v_cvt_pk_bf16_f32 v68, v72, v73
	v_cvt_pk_bf16_f32 v69, v74, v75
	v_cvt_pk_bf16_f32 v70, v76, v77
	v_cvt_pk_bf16_f32 v71, v78, v79
	s_waitcnt lgkmcnt(0)
	s_setprio 1
	s_waitcnt vmcnt(3)
	s_barrier
	v_mfma_f32_32x32x16_bf16 v[0:15], v[64:67], v[144:147], v[0:15]
	s_sub_i32 s74, s0, s47
	s_cmp_lt_u32 s74, s100
	v_mfma_f32_32x32x16_bf16 v[48:63], v[64:67], v[152:155], v[48:63]
	v_mfma_f32_32x32x16_bf16 v[16:31], v[64:67], v[162:165], v[16:31]
	v_mfma_f32_32x32x16_bf16 v[32:47], v[64:67], v[170:173], v[32:47]
	v_mfma_f32_32x32x16_bf16 v[0:15], v[68:71], v[148:151], v[0:15]
	v_mfma_f32_32x32x16_bf16 v[48:63], v[68:71], v[156:159], v[48:63]
	v_mfma_f32_32x32x16_bf16 v[16:31], v[68:71], v[166:169], v[16:31]
	v_mfma_f32_32x32x16_bf16 v[32:47], v[68:71], v[174:177], v[32:47]
	v_mfma_f32_32x32x16_bf16 v[64:79], v[124:127], v[92:95], 0
	v_mfma_f32_32x32x16_bf16 v[64:79], v[132:135], v[88:91], v[64:79]
	v_mfma_f32_32x32x16_bf16 v[64:79], v[136:139], v[84:87], v[64:79]
	v_mfma_f32_32x32x16_bf16 v[64:79], v[140:143], v[80:83], v[64:79]
	s_cbranch_scc1 .Lhw_d1_b_dtd1bias2

; #define LAS __attribute__((address_space(3)))
; DI void expsum(f32x16& p, float& l_reg, bf16x8& pa0, bf16x8& pa1) {
; #pragma unroll
;     for (int r = 0; r < 16; ++r) p[r] = __builtin_amdgcn_exp2f(p[r]);
;     float ps = 0.f;
; #pragma unroll
;     for (int r = 0; r < 16; ++r) ps += p[r];
;     l_reg += ps; asm volatile("" : "+v"(l_reg));
;     ...
;     ATT_PK4(p, 0, pa0); ATT_PK4(p, 8, pa1);
;     ...
; }
; DI int v_rd_base(int lane) { return ((lane & 3) << 3) | (((lane >> 2) & 3) << 6) | (((lane >> 4) & 1) << 5) | (((lane >> 5) & 1) << 8); }
; template <int OFF> DI s16x4 tr_read(int vb) { s16x4 r; asm volatile("ds_read_b64_tr_b16 %0, %1 offset:%2" : "=&v"(r) : "v"(vb), "i"(OFF) : "memory"); return r; }
; template <int H> DI void v_reads(s16x4* vf, int vb) {
;     vf[0] = tr_read<v_rd_off(0, 2 * H, 0)>(vb); vf[1] = tr_read<v_rd_off(0, 2 * H, 1)>(vb); vf[2] = tr_read<v_rd_off(0, 2 * H + 1, 0)>(vb); vf[3] = tr_read<v_rd_off(0, 2 * H + 1, 1)>(vb);
;     vf[4] = tr_read<v_rd_off(1, 2 * H, 0)>(vb); vf[5] = tr_read<v_rd_off(1, 2 * H, 1)>(vb); vf[6] = tr_read<v_rd_off(1, 2 * H + 1, 0)>(vb); vf[7] = tr_read<v_rd_off(1, 2 * H + 1, 1)>(vb);
;     vf[8] = tr_read<v_rd_off(2, 2 * H, 0)>(vb); vf[9] = tr_read<v_rd_off(2, 2 * H, 1)>(vb); vf[10] = tr_read<v_rd_off(2, 2 * H + 1, 0)>(vb); vf[11] = tr_read<v_rd_off(2, 2 * H + 1, 1)>(vb);
;     vf[12] = tr_read<v_rd_off(3, 2 * H, 0)>(vb); vf[13] = tr_read<v_rd_off(3, 2 * H, 1)>(vb); vf[14] = tr_read<v_rd_off(3, 2 * H + 1, 0)>(vb); vf[15] = tr_read<v_rd_off(3, 2 * H + 1, 1)>(vb);
; }
; DI void pv_mma(f32x16* o, const s16x4* vf, bf16x8 pa0, bf16x8 pa1) {
;     ...
; #pragma unroll
;     for (int d0 = 0; d0 < 4; ++d0) {
;         o[d0] = __builtin_amdgcn_mfma_f32_32x32x16_bf16(pa0, ATT_PK(vf[4 * d0], vf[4 * d0 + 1]), o[d0], 0, 0, 0);
;         o[d0] = __builtin_amdgcn_mfma_f32_32x32x16_bf16(pa1, ATT_PK(vf[4 * d0 + 2], vf[4 * d0 + 3]), o[d0], 0, 0, 0); }
;     ...
; }
; template <int DQK, int D0A, int D0B> DI void k_reads(bf16x8* kf, const LAS unsigned char* Ks, int half, int r32, int hi) {
; #pragma unroll
;     for (int d0 = D0A; d0 < D0B; ++d0) kf[d0 - D0A] = *(const LAS bf16x8*)(Ks + half * (32 * DQK * 2) + kswz<DQK>(r32, (d0 * 16 + hi * 8) * 2));
; }
; template <int D0A, int D0B> DI void qk_mma(f32x16& p, const bf16x8* kf, const bf16x8* qr) {
; #pragma unroll
;     for (int d0 = D0A; d0 < D0B; ++d0) {
.LBB0_1955:
	s_add_i32 s3, s22, 0xffffc000
	s_and_b32 s3, s3, 0x6000
	v_add_u32_e32 v196, s3, v107
	v_add_u32_e32 v197, s3, v108
	v_add_u32_e32 v198, s3, v109
	v_add_u32_e32 v199, s3, v110
	ds_read_b128 v[124:127], v196
	ds_read_b128 v[132:135], v197
	ds_read_b128 v[136:139], v198
	ds_read_b128 v[140:143], v199
	ds_read_b64_tr_b16 v[144:145], v121 offset:0x2000
	ds_read_b64_tr_b16 v[146:147], v121 offset:0x2800
	ds_read_b64_tr_b16 v[148:149], v121 offset:0x3000
	ds_read_b64_tr_b16 v[150:151], v121 offset:0x3800
	ds_read_b64_tr_b16 v[152:153], v121 offset:0x2200
	ds_read_b64_tr_b16 v[154:155], v121 offset:0x2a00
	ds_read_b64_tr_b16 v[156:157], v121 offset:0x3200
	ds_read_b64_tr_b16 v[158:159], v121 offset:0x3a00
	ds_read_b64_tr_b16 v[162:163], v121 offset:0x2400
	ds_read_b64_tr_b16 v[164:165], v121 offset:0x2c00
	ds_read_b64_tr_b16 v[166:167], v121 offset:0x3400
	ds_read_b64_tr_b16 v[168:169], v121 offset:0x3c00
	ds_read_b64_tr_b16 v[170:171], v121 offset:0x2600
	ds_read_b64_tr_b16 v[172:173], v121 offset:0x2e00
	ds_read_b64_tr_b16 v[174:175], v121 offset:0x3600
	ds_read_b64_tr_b16 v[176:177], v121 offset:0x3e00
	s_setprio 2
	v_exp_f32_e32 v64, v64
	v_exp_f32_e32 v65, v65
	v_exp_f32_e32 v66, v66
	v_exp_f32_e32 v67, v67
	v_exp_f32_e32 v68, v68
	v_exp_f32_e32 v69, v69
	v_add_f32_e32 v121, v65, v64
	v_exp_f32_e32 v70, v70
	v_add_f32_e32 v121, v66, v121
	v_exp_f32_e32 v71, v71
	v_add_f32_e32 v121, v67, v121
	v_exp_f32_e32 v72, v72
	v_add_f32_e32 v121, v68, v121
	v_exp_f32_e32 v73, v73
	v_add_f32_e32 v121, v69, v121
	v_exp_f32_e32 v74, v74
	v_add_f32_e32 v121, v70, v121
	v_exp_f32_e32 v75, v75
	v_add_f32_e32 v121, v71, v121
	v_exp_f32_e32 v76, v76
	v_add_f32_e32 v121, v72, v121
	v_exp_f32_e32 v77, v77
	v_add_f32_e32 v121, v73, v121
	v_exp_f32_e32 v78, v78
	v_add_f32_e32 v121, v74, v121
	v_exp_f32_e32 v79, v79
	v_add_f32_e32 v121, v75, v121
	v_add_f32_e32 v121, v76, v121
	v_add_f32_e32 v121, v77, v121
	v_add_f32_e32 v121, v78, v121
	v_add_f32_e32 v121, v79, v121
	v_add_f32_e32 v120, v120, v121
	v_cvt_pk_bf16_f32 v64, v64, v65
	v_cvt_pk_bf16_f32 v65, v66, v67
	v_cvt_pk_bf16_f32 v66, v68, v69
	v_cvt_pk_bf16_f32 v67, v70, v71
	v_cvt_pk_bf16_f32 v68, v72, v73
	v_cvt_pk_bf16_f32 v69, v74, v75
	v_cvt_pk_bf16_f32 v70, v76, v77
	v_cvt_pk_bf16_f32 v71, v78, v79
	s_waitcnt lgkmcnt(0)
	s_setprio 1
	v_mfma_f32_32x32x16_bf16 v[0:15], v[64:67], v[144:147], v[0:15]
	s_sub_i32 s74, s0, s47
	s_cmp_lt_u32 s74, s100
	v_mfma_f32_32x32x16_bf16 v[48:63], v[64:67], v[152:155], v[48:63]
	v_mfma_f32_32x32x16_bf16 v[16:31], v[64:67], v[162:165], v[16:31]
	v_mfma_f32_32x32x16_bf16 v[32:47], v[64:67], v[170:173], v[32:47]
	v_mfma_f32_32x32x16_bf16 v[0:15], v[68:71], v[148:151], v[0:15]
	v_mfma_f32_32x32x16_bf16 v[48:63], v[68:71], v[156:159], v[48:63]
	v_mfma_f32_32x32x16_bf16 v[16:31], v[68:71], v[166:169], v[16:31]
	v_mfma_f32_32x32x16_bf16 v[32:47], v[68:71], v[174:177], v[32:47]
	v_mfma_f32_32x32x16_bf16 v[64:79], v[124:127], v[92:95], 0
	v_mfma_f32_32x32x16_bf16 v[64:79], v[132:135], v[88:91], v[64:79]
	v_mfma_f32_32x32x16_bf16 v[64:79], v[136:139], v[84:87], v[64:79]
	v_mfma_f32_32x32x16_bf16 v[64:79], v[140:143], v[80:83], v[64:79]
	s_cbranch_scc1 .Ldt_d1_bias2

; #define LAS __attribute__((address_space(3)))
; DI void expsum(f32x16& p, float& l_reg, bf16x8& pa0, bf16x8& pa1) {
; #pragma unroll
;     for (int r = 0; r < 16; ++r) p[r] = __builtin_amdgcn_exp2f(p[r]);
;     float ps = 0.f;
; #pragma unroll
;     for (int r = 0; r < 16; ++r) ps += p[r];
;     l_reg += ps; asm volatile("" : "+v"(l_reg));
;     ...
;     ATT_PK4(p, 0, pa0); ATT_PK4(p, 8, pa1);
;     ...
; }
; DI int v_rd_base(int lane) { return ((lane & 3) << 3) | (((lane >> 2) & 3) << 6) | (((lane >> 4) & 1) << 5) | (((lane >> 5) & 1) << 8); }
; template <int OFF> DI s16x4 tr_read(int vb) { s16x4 r; asm volatile("ds_read_b64_tr_b16 %0, %1 offset:%2" : "=&v"(r) : "v"(vb), "i"(OFF) : "memory"); return r; }
; template <int H> DI void v_reads(s16x4* vf, int vb) {
;     vf[0] = tr_read<v_rd_off(0, 2 * H, 0)>(vb); vf[1] = tr_read<v_rd_off(0, 2 * H, 1)>(vb); vf[2] = tr_read<v_rd_off(0, 2 * H + 1, 0)>(vb); vf[3] = tr_read<v_rd_off(0, 2 * H + 1, 1)>(vb);
;     vf[4] = tr_read<v_rd_off(1, 2 * H, 0)>(vb); vf[5] = tr_read<v_rd_off(1, 2 * H, 1)>(vb); vf[6] = tr_read<v_rd_off(1, 2 * H + 1, 0)>(vb); vf[7] = tr_read<v_rd_off(1, 2 * H + 1, 1)>(vb);
;     vf[8] = tr_read<v_rd_off(2, 2 * H, 0)>(vb); vf[9] = tr_read<v_rd_off(2, 2 * H, 1)>(vb); vf[10] = tr_read<v_rd_off(2, 2 * H + 1, 0)>(vb); vf[11] = tr_read<v_rd_off(2, 2 * H + 1, 1)>(vb);
;     vf[12] = tr_read<v_rd_off(3, 2 * H, 0)>(vb); vf[13] = tr_read<v_rd_off(3, 2 * H, 1)>(vb); vf[14] = tr_read<v_rd_off(3, 2 * H + 1, 0)>(vb); vf[15] = tr_read<v_rd_off(3, 2 * H + 1, 1)>(vb);
; }
; DI void pv_mma(f32x16* o, const s16x4* vf, bf16x8 pa0, bf16x8 pa1) {
;     ...
; #pragma unroll
;     for (int d0 = 0; d0 < 4; ++d0) {
;         o[d0] = __builtin_amdgcn_mfma_f32_32x32x16_bf16(pa0, ATT_PK(vf[4 * d0], vf[4 * d0 + 1]), o[d0], 0, 0, 0);
;         o[d0] = __builtin_amdgcn_mfma_f32_32x32x16_bf16(pa1, ATT_PK(vf[4 * d0 + 2], vf[4 * d0 + 3]), o[d0], 0, 0, 0); }
;     ...
; }
; template <int DQK, int D0A, int D0B> DI void k_reads(bf16x8* kf, const LAS unsigned char* Ks, int half, int r32, int hi) {
; #pragma unroll
;     for (int d0 = D0A; d0 < D0B; ++d0) kf[d0 - D0A] = *(const LAS bf16x8*)(Ks + half * (32 * DQK * 2) + kswz<DQK>(r32, (d0 * 16 + hi * 8) * 2));
; }
; template <int D0A, int D0B> DI void qk_mma(f32x16& p, const bf16x8* kf, const bf16x8* qr) {
; #pragma unroll
;     for (int d0 = D0A; d0 < D0B; ++d0) {
.LBB0_1961:
	ds_read_b128 v[98:101], v107 offset:12288
	ds_read_b128 v[102:105], v108 offset:12288
	ds_read_b128 v[114:117], v109 offset:12288
	ds_read_b128 v[122:125], v110 offset:12288
	v_lshl_add_u32 v96, s49, 14, v106
	ds_read_b64_tr_b16 v[132:133], v96 offset:0
	ds_read_b64_tr_b16 v[134:135], v96 offset:0x800
	ds_read_b64_tr_b16 v[136:137], v96 offset:0x1000
	ds_read_b64_tr_b16 v[138:139], v96 offset:0x1800
	ds_read_b64_tr_b16 v[140:141], v96 offset:0x200
	ds_read_b64_tr_b16 v[142:143], v96 offset:0xa00
	ds_read_b64_tr_b16 v[144:145], v96 offset:0x1200
	ds_read_b64_tr_b16 v[146:147], v96 offset:0x1a00
	ds_read_b64_tr_b16 v[148:149], v96 offset:0x400
	ds_read_b64_tr_b16 v[150:151], v96 offset:0xc00
	ds_read_b64_tr_b16 v[152:153], v96 offset:0x1400
	ds_read_b64_tr_b16 v[154:155], v96 offset:0x1c00
	ds_read_b64_tr_b16 v[156:157], v96 offset:0x600
	ds_read_b64_tr_b16 v[158:159], v96 offset:0xe00
	ds_read_b64_tr_b16 v[162:163], v96 offset:0x1600
	ds_read_b64_tr_b16 v[164:165], v96 offset:0x1e00
	s_setprio 2
	v_exp_f32_e32 v64, v64
	v_exp_f32_e32 v65, v65
	v_exp_f32_e32 v66, v66
	v_exp_f32_e32 v67, v67
	v_exp_f32_e32 v68, v68
	v_exp_f32_e32 v69, v69
	v_add_f32_e32 v97, v65, v64
	v_exp_f32_e32 v70, v70
	v_add_f32_e32 v97, v66, v97
	v_exp_f32_e32 v71, v71
	v_add_f32_e32 v97, v67, v97
	v_exp_f32_e32 v72, v72
	v_add_f32_e32 v97, v68, v97
	v_exp_f32_e32 v73, v73
	v_add_f32_e32 v97, v69, v97
	v_exp_f32_e32 v74, v74
	v_add_f32_e32 v97, v70, v97
	v_exp_f32_e32 v75, v75
	v_add_f32_e32 v97, v71, v97
	v_exp_f32_e32 v76, v76
	v_add_f32_e32 v97, v72, v97
	v_exp_f32_e32 v77, v77
	v_add_f32_e32 v97, v73, v97
	v_exp_f32_e32 v78, v78
	v_add_f32_e32 v97, v74, v97
	v_exp_f32_e32 v79, v79
	v_add_f32_e32 v97, v75, v97
	v_add_f32_e32 v97, v76, v97
	v_add_f32_e32 v97, v77, v97
	v_add_f32_e32 v97, v78, v97
	v_add_f32_e32 v97, v79, v97
	v_add_f32_e32 v97, v97, v120
	v_cvt_pk_bf16_f32 v64, v64, v65
	v_cvt_pk_bf16_f32 v65, v66, v67
	v_cvt_pk_bf16_f32 v66, v68, v69
	v_cvt_pk_bf16_f32 v67, v70, v71
	v_cvt_pk_bf16_f32 v68, v72, v73
	v_cvt_pk_bf16_f32 v69, v74, v75
	v_cvt_pk_bf16_f32 v70, v76, v77
	v_cvt_pk_bf16_f32 v71, v78, v79
	s_waitcnt lgkmcnt(0)
	s_setprio 1
	v_mfma_f32_32x32x16_bf16 v[0:15], v[64:67], v[132:135], v[0:15]
	s_cmp_gt_i32 s47, 61
	s_cselect_b64 s[0:1], -1, 0
	s_cmp_lt_i32 s45, 62
	s_cselect_b64 s[2:3], -1, 0
	s_or_b64 s[0:1], s[0:1], s[2:3]
	s_and_b64 vcc, exec, s[0:1]
	v_mfma_f32_32x32x16_bf16 v[48:63], v[64:67], v[140:143], v[48:63]
	v_mfma_f32_32x32x16_bf16 v[16:31], v[64:67], v[148:151], v[16:31]
	v_mfma_f32_32x32x16_bf16 v[32:47], v[64:67], v[156:159], v[32:47]
	v_mfma_f32_32x32x16_bf16 v[0:15], v[68:71], v[136:139], v[0:15]
	v_mfma_f32_32x32x16_bf16 v[48:63], v[68:71], v[144:147], v[48:63]
	v_mfma_f32_32x32x16_bf16 v[16:31], v[68:71], v[152:155], v[16:31]
	v_mfma_f32_32x32x16_bf16 v[32:47], v[68:71], v[162:165], v[32:47]
	s_waitcnt lgkmcnt(0)
	v_mfma_f32_32x32x16_bf16 v[64:79], v[98:101], v[92:95], 0
	v_mfma_f32_32x32x16_bf16 v[64:79], v[102:105], v[88:91], v[64:79]
	v_mfma_f32_32x32x16_bf16 v[64:79], v[114:117], v[84:87], v[64:79]
	v_mfma_f32_32x32x16_bf16 v[64:79], v[122:125], v[80:83], v[64:79]
	s_setprio 0
	s_cbranch_vccnz .LBB0_1963
	v_sub_u32_e32 v98, 0xf40, v111
	v_lshlrev_b32_e32 v98, 2, v98
	v_add3_u32 v98, s88, v98, v130
	v_add_u32_e32 v114, 0x400, v98
	v_add_u32_e32 v116, 0x408, v98
	v_add_u32_e32 v118, 0x420, v98
	v_add_u32_e32 v120, 0x428, v98
	v_add_u32_e32 v99, 0x440, v98
	v_add_u32_e32 v100, 0x448, v98
	v_add_u32_e32 v102, 0x460, v98
	v_add_u32_e32 v104, 0x468, v98
	ds_read2_b32 v[98:99], v99 offset1:1
	ds_read2_b32 v[100:101], v100 offset1:1
	ds_read2_b32 v[102:103], v102 offset1:1
	ds_read2_b32 v[104:105], v104 offset1:1
	ds_read2_b32 v[114:115], v114 offset1:1
	ds_read2_b32 v[116:117], v116 offset1:1
	ds_read2_b32 v[118:119], v118 offset1:1
	ds_read2_b32 v[120:121], v120 offset1:1
	s_waitcnt lgkmcnt(0)
	v_pk_add_f32 v[78:79], v[78:79], v[104:105]
	v_pk_add_f32 v[76:77], v[76:77], v[102:103]
	v_pk_add_f32 v[74:75], v[74:75], v[100:101]
	v_pk_add_f32 v[72:73], v[72:73], v[98:99]
	v_pk_add_f32 v[70:71], v[70:71], v[120:121]
	v_pk_add_f32 v[68:69], v[68:69], v[118:119]
	v_pk_add_f32 v[66:67], v[66:67], v[116:117]
	v_pk_add_f32 v[64:65], v[64:65], v[114:115]
.LBB0_1963:
	ds_read_b128 v[98:101], v107 offset:16384
	ds_read_b128 v[102:105], v108 offset:16384
	ds_read_b128 v[114:117], v109 offset:16384
	ds_read_b128 v[118:121], v110 offset:16384
	ds_read_b64_tr_b16 v[122:123], v96 offset:0x2000
	ds_read_b64_tr_b16 v[124:125], v96 offset:0x2800
	ds_read_b64_tr_b16 v[132:133], v96 offset:0x3000
	ds_read_b64_tr_b16 v[134:135], v96 offset:0x3800
	ds_read_b64_tr_b16 v[136:137], v96 offset:0x2200
	ds_read_b64_tr_b16 v[138:139], v96 offset:0x2a00
	ds_read_b64_tr_b16 v[140:141], v96 offset:0x3200
	ds_read_b64_tr_b16 v[142:143], v96 offset:0x3a00
	ds_read_b64_tr_b16 v[144:145], v96 offset:0x2400
	ds_read_b64_tr_b16 v[146:147], v96 offset:0x2c00
	ds_read_b64_tr_b16 v[148:149], v96 offset:0x3400
	ds_read_b64_tr_b16 v[150:151], v96 offset:0x3c00
	ds_read_b64_tr_b16 v[152:153], v96 offset:0x2600
	ds_read_b64_tr_b16 v[154:155], v96 offset:0x2e00
	ds_read_b64_tr_b16 v[156:157], v96 offset:0x3600
	ds_read_b64_tr_b16 v[158:159], v96 offset:0x3e00
	s_nop 6
	s_setprio 2
	v_exp_f32_e32 v64, v64
	v_exp_f32_e32 v65, v65
	v_exp_f32_e32 v66, v66
	v_exp_f32_e32 v67, v67
	v_exp_f32_e32 v68, v68
	v_exp_f32_e32 v69, v69
	v_add_f32_e32 v96, v65, v64
	v_exp_f32_e32 v70, v70
	v_add_f32_e32 v96, v66, v96
	v_exp_f32_e32 v71, v71
	v_add_f32_e32 v96, v67, v96
	v_exp_f32_e32 v72, v72
	v_add_f32_e32 v96, v68, v96
	v_exp_f32_e32 v73, v73
	v_add_f32_e32 v96, v69, v96
	v_exp_f32_e32 v74, v74
	v_add_f32_e32 v96, v70, v96
	v_exp_f32_e32 v75, v75
	v_add_f32_e32 v96, v71, v96
	v_exp_f32_e32 v76, v76
	v_add_f32_e32 v96, v72, v96
	v_exp_f32_e32 v77, v77
	v_add_f32_e32 v96, v73, v96
	v_exp_f32_e32 v78, v78
	v_add_f32_e32 v96, v74, v96
	v_exp_f32_e32 v79, v79
	v_add_f32_e32 v96, v75, v96
	v_add_f32_e32 v96, v76, v96
	v_add_f32_e32 v96, v77, v96
	v_add_f32_e32 v96, v78, v96
	v_add_f32_e32 v96, v79, v96
	v_add_f32_e32 v96, v97, v96
	v_cvt_pk_bf16_f32 v64, v64, v65
	v_cvt_pk_bf16_f32 v65, v66, v67
	v_cvt_pk_bf16_f32 v66, v68, v69
	v_cvt_pk_bf16_f32 v67, v70, v71
	v_cvt_pk_bf16_f32 v68, v72, v73
	v_cvt_pk_bf16_f32 v69, v74, v75
	v_cvt_pk_bf16_f32 v70, v76, v77
	v_cvt_pk_bf16_f32 v71, v78, v79
	s_waitcnt lgkmcnt(0)
	s_setprio 1
	s_cmp_lt_u32 s33, 0x100
	s_cbranch_scc1 .Lstg_d1_m61_21
	s_waitcnt vmcnt(0)
	s_barrier

; #define LAS __attribute__((address_space(3)))
; DI void expsum(f32x16& p, float& l_reg, bf16x8& pa0, bf16x8& pa1) {
; #pragma unroll
;     for (int r = 0; r < 16; ++r) p[r] = __builtin_amdgcn_exp2f(p[r]);
;     float ps = 0.f;
; #pragma unroll
;     for (int r = 0; r < 16; ++r) ps += p[r];
;     l_reg += ps; asm volatile("" : "+v"(l_reg));
;     ...
;     ATT_PK4(p, 0, pa0); ATT_PK4(p, 8, pa1);
;     ...
; }
; DI int v_rd_base(int lane) { return ((lane & 3) << 3) | (((lane >> 2) & 3) << 6) | (((lane >> 4) & 1) << 5) | (((lane >> 5) & 1) << 8); }
; template <int OFF> DI s16x4 tr_read(int vb) { s16x4 r; asm volatile("ds_read_b64_tr_b16 %0, %1 offset:%2" : "=&v"(r) : "v"(vb), "i"(OFF) : "memory"); return r; }
; template <int H> DI void v_reads(s16x4* vf, int vb) {
;     vf[0] = tr_read<v_rd_off(0, 2 * H, 0)>(vb); vf[1] = tr_read<v_rd_off(0, 2 * H, 1)>(vb); vf[2] = tr_read<v_rd_off(0, 2 * H + 1, 0)>(vb); vf[3] = tr_read<v_rd_off(0, 2 * H + 1, 1)>(vb);
;     vf[4] = tr_read<v_rd_off(1, 2 * H, 0)>(vb); vf[5] = tr_read<v_rd_off(1, 2 * H, 1)>(vb); vf[6] = tr_read<v_rd_off(1, 2 * H + 1, 0)>(vb); vf[7] = tr_read<v_rd_off(1, 2 * H + 1, 1)>(vb);
;     vf[8] = tr_read<v_rd_off(2, 2 * H, 0)>(vb); vf[9] = tr_read<v_rd_off(2, 2 * H, 1)>(vb); vf[10] = tr_read<v_rd_off(2, 2 * H + 1, 0)>(vb); vf[11] = tr_read<v_rd_off(2, 2 * H + 1, 1)>(vb);
;     vf[12] = tr_read<v_rd_off(3, 2 * H, 0)>(vb); vf[13] = tr_read<v_rd_off(3, 2 * H, 1)>(vb); vf[14] = tr_read<v_rd_off(3, 2 * H + 1, 0)>(vb); vf[15] = tr_read<v_rd_off(3, 2 * H + 1, 1)>(vb);
; }
; DI void pv_mma(f32x16* o, const s16x4* vf, bf16x8 pa0, bf16x8 pa1) {
;     ...
; #pragma unroll
;     for (int d0 = 0; d0 < 4; ++d0) {
;         o[d0] = __builtin_amdgcn_mfma_f32_32x32x16_bf16(pa0, ATT_PK(vf[4 * d0], vf[4 * d0 + 1]), o[d0], 0, 0, 0);
;         o[d0] = __builtin_amdgcn_mfma_f32_32x32x16_bf16(pa1, ATT_PK(vf[4 * d0 + 2], vf[4 * d0 + 3]), o[d0], 0, 0, 0); }
;     ...
; }
; template <int DQK, int D0A, int D0B> DI void k_reads(bf16x8* kf, const LAS unsigned char* Ks, int half, int r32, int hi) {
; #pragma unroll
;     for (int d0 = D0A; d0 < D0B; ++d0) kf[d0 - D0A] = *(const LAS bf16x8*)(Ks + half * (32 * DQK * 2) + kswz<DQK>(r32, (d0 * 16 + hi * 8) * 2));
; }
; template <int D0A, int D0B> DI void qk_mma(f32x16& p, const bf16x8* kf, const bf16x8* qr) {
; #pragma unroll
;     for (int d0 = D0A; d0 < D0B; ++d0) {
.LBB0_1967:
	ds_read_b128 v[100:103], v107 offset:20480
	ds_read_b128 v[114:117], v108 offset:20480
	ds_read_b128 v[118:121], v109 offset:20480
	ds_read_b128 v[122:125], v110 offset:20480
	v_add_u32_e32 v98, 0x8000, v106
	ds_read_b64_tr_b16 v[132:133], v98 offset:0
	ds_read_b64_tr_b16 v[134:135], v98 offset:0x800
	ds_read_b64_tr_b16 v[136:137], v98 offset:0x1000
	ds_read_b64_tr_b16 v[138:139], v98 offset:0x1800
	ds_read_b64_tr_b16 v[140:141], v98 offset:0x200
	ds_read_b64_tr_b16 v[142:143], v98 offset:0xa00
	ds_read_b64_tr_b16 v[144:145], v98 offset:0x1200
	ds_read_b64_tr_b16 v[146:147], v98 offset:0x1a00
	ds_read_b64_tr_b16 v[148:149], v98 offset:0x400
	ds_read_b64_tr_b16 v[150:151], v98 offset:0xc00
	ds_read_b64_tr_b16 v[152:153], v98 offset:0x1400
	ds_read_b64_tr_b16 v[154:155], v98 offset:0x1c00
	ds_read_b64_tr_b16 v[156:157], v98 offset:0x600
	ds_read_b64_tr_b16 v[158:159], v98 offset:0xe00
	ds_read_b64_tr_b16 v[162:163], v98 offset:0x1600
	ds_read_b64_tr_b16 v[164:165], v98 offset:0x1e00
	s_setprio 2
	v_exp_f32_e32 v64, v64
	v_exp_f32_e32 v65, v65
	v_exp_f32_e32 v66, v66
	v_exp_f32_e32 v67, v67
	v_exp_f32_e32 v68, v68
	v_exp_f32_e32 v69, v69
	v_add_f32_e32 v99, v65, v64
	v_exp_f32_e32 v70, v70
	v_add_f32_e32 v99, v66, v99
	v_exp_f32_e32 v71, v71
	v_add_f32_e32 v99, v67, v99
	v_exp_f32_e32 v72, v72
	v_add_f32_e32 v99, v68, v99
	v_exp_f32_e32 v73, v73
	v_add_f32_e32 v99, v69, v99
	v_exp_f32_e32 v74, v74
	v_add_f32_e32 v99, v70, v99
	v_exp_f32_e32 v75, v75
	v_add_f32_e32 v99, v71, v99
	v_exp_f32_e32 v76, v76
	v_add_f32_e32 v99, v72, v99
	v_exp_f32_e32 v77, v77
	v_add_f32_e32 v99, v73, v99
	v_exp_f32_e32 v78, v78
	v_add_f32_e32 v99, v74, v99
	v_exp_f32_e32 v79, v79
	v_add_f32_e32 v99, v75, v99
	v_add_f32_e32 v99, v76, v99
	v_add_f32_e32 v99, v77, v99
	v_add_f32_e32 v99, v78, v99
	v_add_f32_e32 v99, v79, v99
	v_add_f32_e32 v96, v99, v96
	v_cvt_pk_bf16_f32 v64, v64, v65
	v_cvt_pk_bf16_f32 v65, v66, v67
	v_cvt_pk_bf16_f32 v66, v68, v69
	v_cvt_pk_bf16_f32 v67, v70, v71
	v_cvt_pk_bf16_f32 v68, v72, v73
	v_cvt_pk_bf16_f32 v69, v74, v75
	v_cvt_pk_bf16_f32 v70, v76, v77
	v_cvt_pk_bf16_f32 v71, v78, v79
	s_waitcnt lgkmcnt(0)
	s_setprio 1
	v_mfma_f32_32x32x16_bf16 v[0:15], v[64:67], v[132:135], v[0:15]
	s_and_b64 vcc, exec, s[2:3]
	v_mfma_f32_32x32x16_bf16 v[48:63], v[64:67], v[140:143], v[48:63]
	v_mfma_f32_32x32x16_bf16 v[16:31], v[64:67], v[148:151], v[16:31]
	v_mfma_f32_32x32x16_bf16 v[32:47], v[64:67], v[156:159], v[32:47]
	v_mfma_f32_32x32x16_bf16 v[0:15], v[68:71], v[136:139], v[0:15]
	v_mfma_f32_32x32x16_bf16 v[48:63], v[68:71], v[144:147], v[48:63]
	v_mfma_f32_32x32x16_bf16 v[16:31], v[68:71], v[152:155], v[16:31]
	v_mfma_f32_32x32x16_bf16 v[32:47], v[68:71], v[162:165], v[32:47]
	s_waitcnt lgkmcnt(0)
	v_mfma_f32_32x32x16_bf16 v[64:79], v[100:103], v[92:95], 0
	v_mfma_f32_32x32x16_bf16 v[64:79], v[114:117], v[88:91], v[64:79]
	v_mfma_f32_32x32x16_bf16 v[64:79], v[118:121], v[84:87], v[64:79]
	v_mfma_f32_32x32x16_bf16 v[64:79], v[122:125], v[80:83], v[64:79]
	s_setprio 0
	s_cbranch_vccnz .LBB0_1969
	v_add3_u32 v97, s88, v97, v130
	v_add_u32_e32 v118, 0x408, v97
	v_add_u32_e32 v120, 0x420, v97
	v_add_u32_e32 v122, 0x428, v97
	v_add_u32_e32 v100, 0x440, v97
	v_add_u32_e32 v102, 0x448, v97
	v_add_u32_e32 v104, 0x460, v97
	v_add_u32_e32 v99, 0x400, v97
	v_add_u32_e32 v97, 0x468, v97
	ds_read2_b32 v[100:101], v100 offset1:1
	ds_read2_b32 v[102:103], v102 offset1:1
	ds_read2_b32 v[104:105], v104 offset1:1
	ds_read2_b32 v[114:115], v97 offset1:1
	ds_read2_b32 v[116:117], v99 offset1:1
	ds_read2_b32 v[118:119], v118 offset1:1
	ds_read2_b32 v[120:121], v120 offset1:1
	ds_read2_b32 v[122:123], v122 offset1:1
	s_waitcnt lgkmcnt(0)
	v_pk_add_f32 v[78:79], v[78:79], v[114:115]
	v_pk_add_f32 v[76:77], v[76:77], v[104:105]
	v_pk_add_f32 v[74:75], v[74:75], v[102:103]
	v_pk_add_f32 v[72:73], v[72:73], v[100:101]
	v_pk_add_f32 v[70:71], v[70:71], v[122:123]
	v_pk_add_f32 v[68:69], v[68:69], v[120:121]
	v_pk_add_f32 v[66:67], v[66:67], v[118:119]
	v_pk_add_f32 v[64:65], v[64:65], v[116:117]

; #define LAS __attribute__((address_space(3)))
; DI void expsum(f32x16& p, float& l_reg, bf16x8& pa0, bf16x8& pa1) {
; #pragma unroll
;     for (int r = 0; r < 16; ++r) p[r] = __builtin_amdgcn_exp2f(p[r]);
;     float ps = 0.f;
; #pragma unroll
;     for (int r = 0; r < 16; ++r) ps += p[r];
;     l_reg += ps; asm volatile("" : "+v"(l_reg));
;     ...
;     ATT_PK4(p, 0, pa0); ATT_PK4(p, 8, pa1);
;     ...
; }
; DI int v_rd_base(int lane) { return ((lane & 3) << 3) | (((lane >> 2) & 3) << 6) | (((lane >> 4) & 1) << 5) | (((lane >> 5) & 1) << 8); }
; template <int OFF> DI s16x4 tr_read(int vb) { s16x4 r; asm volatile("ds_read_b64_tr_b16 %0, %1 offset:%2" : "=&v"(r) : "v"(vb), "i"(OFF) : "memory"); return r; }
; template <int H> DI void v_reads(s16x4* vf, int vb) {
;     vf[0] = tr_read<v_rd_off(0, 2 * H, 0)>(vb); vf[1] = tr_read<v_rd_off(0, 2 * H, 1)>(vb); vf[2] = tr_read<v_rd_off(0, 2 * H + 1, 0)>(vb); vf[3] = tr_read<v_rd_off(0, 2 * H + 1, 1)>(vb);
;     vf[4] = tr_read<v_rd_off(1, 2 * H, 0)>(vb); vf[5] = tr_read<v_rd_off(1, 2 * H, 1)>(vb); vf[6] = tr_read<v_rd_off(1, 2 * H + 1, 0)>(vb); vf[7] = tr_read<v_rd_off(1, 2 * H + 1, 1)>(vb);
;     vf[8] = tr_read<v_rd_off(2, 2 * H, 0)>(vb); vf[9] = tr_read<v_rd_off(2, 2 * H, 1)>(vb); vf[10] = tr_read<v_rd_off(2, 2 * H + 1, 0)>(vb); vf[11] = tr_read<v_rd_off(2, 2 * H + 1, 1)>(vb);
;     vf[12] = tr_read<v_rd_off(3, 2 * H, 0)>(vb); vf[13] = tr_read<v_rd_off(3, 2 * H, 1)>(vb); vf[14] = tr_read<v_rd_off(3, 2 * H + 1, 0)>(vb); vf[15] = tr_read<v_rd_off(3, 2 * H + 1, 1)>(vb);
; }
; DI void pv_mma(f32x16* o, const s16x4* vf, bf16x8 pa0, bf16x8 pa1) {
;     ...
; #pragma unroll
;     for (int d0 = 0; d0 < 4; ++d0) {
;         o[d0] = __builtin_amdgcn_mfma_f32_32x32x16_bf16(pa0, ATT_PK(vf[4 * d0], vf[4 * d0 + 1]), o[d0], 0, 0, 0);
;         o[d0] = __builtin_amdgcn_mfma_f32_32x32x16_bf16(pa1, ATT_PK(vf[4 * d0 + 2], vf[4 * d0 + 3]), o[d0], 0, 0, 0); }
;     ...
; }
; template <int DQK, int D0A, int D0B> DI void k_reads(bf16x8* kf, const LAS unsigned char* Ks, int half, int r32, int hi) {
; #pragma unroll
;     for (int d0 = D0A; d0 < D0B; ++d0) kf[d0 - D0A] = *(const LAS bf16x8*)(Ks + half * (32 * DQK * 2) + kswz<DQK>(r32, (d0 * 16 + hi * 8) * 2));
; }
; template <int D0A, int D0B> DI void qk_mma(f32x16& p, const bf16x8* kf, const bf16x8* qr) {
; #pragma unroll
;     for (int d0 = D0A; d0 < D0B; ++d0) {
.LBB0_1973:
	ds_read_b128 v[98:101], v107 offset:28672
	ds_read_b128 v[102:105], v108 offset:28672
	ds_read_b128 v[112:115], v109 offset:28672
	ds_read_b128 v[108:111], v110 offset:28672
	ds_read_b64_tr_b16 v[116:117], v106 offset:0
	ds_read_b64_tr_b16 v[118:119], v106 offset:0x800
	ds_read_b64_tr_b16 v[120:121], v106 offset:0x1000
	ds_read_b64_tr_b16 v[122:123], v106 offset:0x1800
	ds_read_b64_tr_b16 v[124:125], v106 offset:0x200
	ds_read_b64_tr_b16 v[126:127], v106 offset:0xa00
	ds_read_b64_tr_b16 v[132:133], v106 offset:0x1200
	ds_read_b64_tr_b16 v[134:135], v106 offset:0x1a00
	ds_read_b64_tr_b16 v[136:137], v106 offset:0x400
	ds_read_b64_tr_b16 v[138:139], v106 offset:0xc00
	ds_read_b64_tr_b16 v[140:141], v106 offset:0x1400
	ds_read_b64_tr_b16 v[142:143], v106 offset:0x1c00
	ds_read_b64_tr_b16 v[144:145], v106 offset:0x600
	ds_read_b64_tr_b16 v[146:147], v106 offset:0xe00
	ds_read_b64_tr_b16 v[148:149], v106 offset:0x1600
	ds_read_b64_tr_b16 v[150:151], v106 offset:0x1e00
	s_setprio 2
	v_exp_f32_e32 v64, v64
	v_exp_f32_e32 v65, v65
	v_exp_f32_e32 v66, v66
	v_exp_f32_e32 v67, v67
	v_exp_f32_e32 v68, v68
	v_exp_f32_e32 v69, v69
	v_add_f32_e32 v107, v65, v64
	v_exp_f32_e32 v70, v70
	v_add_f32_e32 v107, v66, v107
	v_exp_f32_e32 v71, v71
	v_add_f32_e32 v107, v67, v107
	v_exp_f32_e32 v72, v72
	v_add_f32_e32 v107, v68, v107
	v_exp_f32_e32 v73, v73
	v_add_f32_e32 v107, v69, v107
	v_exp_f32_e32 v74, v74
	v_add_f32_e32 v107, v70, v107
	v_exp_f32_e32 v75, v75
	v_add_f32_e32 v107, v71, v107
	v_exp_f32_e32 v76, v76
	v_add_f32_e32 v107, v72, v107
	v_exp_f32_e32 v77, v77
	v_add_f32_e32 v107, v73, v107
	v_exp_f32_e32 v78, v78
	v_add_f32_e32 v107, v74, v107
	v_exp_f32_e32 v79, v79
	v_add_f32_e32 v107, v75, v107
	v_add_f32_e32 v107, v76, v107
	v_add_f32_e32 v107, v77, v107
	v_add_f32_e32 v107, v78, v107
	v_add_f32_e32 v107, v79, v107
	v_add_f32_e32 v96, v107, v96
	v_cvt_pk_bf16_f32 v64, v64, v65
	v_cvt_pk_bf16_f32 v65, v66, v67
	v_cvt_pk_bf16_f32 v66, v68, v69
	v_cvt_pk_bf16_f32 v67, v70, v71
	v_cvt_pk_bf16_f32 v68, v72, v73
	v_cvt_pk_bf16_f32 v69, v74, v75
	v_cvt_pk_bf16_f32 v70, v76, v77
	v_cvt_pk_bf16_f32 v71, v78, v79
	s_waitcnt lgkmcnt(0)
	s_setprio 1
	v_mfma_f32_32x32x16_bf16 v[0:15], v[64:67], v[116:119], v[0:15]
	s_and_b64 vcc, exec, s[2:3]
	v_mfma_f32_32x32x16_bf16 v[48:63], v[64:67], v[124:127], v[48:63]
	v_mfma_f32_32x32x16_bf16 v[16:31], v[64:67], v[136:139], v[16:31]
	v_mfma_f32_32x32x16_bf16 v[32:47], v[64:67], v[144:147], v[32:47]
	v_mfma_f32_32x32x16_bf16 v[0:15], v[68:71], v[120:123], v[0:15]
	v_mfma_f32_32x32x16_bf16 v[48:63], v[68:71], v[132:135], v[48:63]
	v_mfma_f32_32x32x16_bf16 v[16:31], v[68:71], v[140:143], v[16:31]
	v_mfma_f32_32x32x16_bf16 v[32:47], v[68:71], v[148:151], v[32:47]
	s_waitcnt lgkmcnt(0)
	v_mfma_f32_32x32x16_bf16 v[64:79], v[98:101], v[92:95], 0
	v_mfma_f32_32x32x16_bf16 v[64:79], v[102:105], v[88:91], v[64:79]
	v_mfma_f32_32x32x16_bf16 v[64:79], v[112:115], v[84:87], v[64:79]
	v_mfma_f32_32x32x16_bf16 v[64:79], v[108:111], v[80:83], v[64:79]
	s_setprio 0
	s_cbranch_vccnz .LBB0_1975
	v_add3_u32 v80, s88, v97, v130
	v_add_u32_e32 v88, 0x400, v80
	v_add_u32_e32 v90, 0x408, v80
	v_add_u32_e32 v92, 0x420, v80
	v_add_u32_e32 v94, 0x428, v80
	v_add_u32_e32 v81, 0x440, v80
	v_add_u32_e32 v82, 0x448, v80
	v_add_u32_e32 v84, 0x460, v80
	v_add_u32_e32 v86, 0x468, v80
	ds_read2_b32 v[80:81], v81 offset1:1
	ds_read2_b32 v[82:83], v82 offset1:1
	ds_read2_b32 v[84:85], v84 offset1:1
	ds_read2_b32 v[86:87], v86 offset1:1
	ds_read2_b32 v[88:89], v88 offset1:1
	ds_read2_b32 v[90:91], v90 offset1:1
	ds_read2_b32 v[92:93], v92 offset1:1
	ds_read2_b32 v[94:95], v94 offset1:1
	s_waitcnt lgkmcnt(0)
	v_pk_add_f32 v[78:79], v[78:79], v[86:87]
	v_pk_add_f32 v[76:77], v[76:77], v[84:85]
	v_pk_add_f32 v[74:75], v[74:75], v[82:83]
	v_pk_add_f32 v[72:73], v[72:73], v[80:81]
	v_pk_add_f32 v[70:71], v[70:71], v[94:95]
	v_pk_add_f32 v[68:69], v[68:69], v[92:93]
	v_pk_add_f32 v[66:67], v[66:67], v[90:91]
	v_pk_add_f32 v[64:65], v[64:65], v[88:89]
.LBB0_1975:
	s_lshl_b32 s0, s44, 2
	s_add_i32 s0, s0, 0
	s_add_i32 s0, s0, 0x24000
	ds_read_b64_tr_b16 v[80:81], v106 offset:0x2000
	ds_read_b64_tr_b16 v[82:83], v106 offset:0x2800
	ds_read_b64_tr_b16 v[84:85], v106 offset:0x3000
	ds_read_b64_tr_b16 v[86:87], v106 offset:0x3800
	ds_read_b64_tr_b16 v[88:89], v106 offset:0x2200
	ds_read_b64_tr_b16 v[90:91], v106 offset:0x2a00
	ds_read_b64_tr_b16 v[92:93], v106 offset:0x3200
	ds_read_b64_tr_b16 v[94:95], v106 offset:0x3a00
	ds_read_b64_tr_b16 v[98:99], v106 offset:0x2400
	ds_read_b64_tr_b16 v[100:101], v106 offset:0x2c00
	ds_read_b64_tr_b16 v[102:103], v106 offset:0x3400
	ds_read_b64_tr_b16 v[104:105], v106 offset:0x3c00
	ds_read_b64_tr_b16 v[108:109], v106 offset:0x2600
	ds_read_b64_tr_b16 v[110:111], v106 offset:0x2e00
	ds_read_b64_tr_b16 v[112:113], v106 offset:0x3600
	ds_read_b64_tr_b16 v[114:115], v106 offset:0x3e00
	s_nop 7
	s_setprio 2
	v_exp_f32_e32 v97, v64
	v_exp_f32_e32 v65, v65
	v_exp_f32_e32 v106, v66
	v_exp_f32_e32 v67, v67
	v_exp_f32_e32 v68, v68
	v_exp_f32_e32 v69, v69
	v_add_f32_e32 v64, v65, v97
	v_exp_f32_e32 v70, v70
	v_add_f32_e32 v64, v106, v64
	v_exp_f32_e32 v71, v71
	v_add_f32_e32 v64, v67, v64
	v_exp_f32_e32 v72, v72
	v_add_f32_e32 v64, v68, v64
	v_exp_f32_e32 v73, v73
	v_add_f32_e32 v64, v69, v64
	v_exp_f32_e32 v74, v74
	v_add_f32_e32 v64, v70, v64
	v_exp_f32_e32 v75, v75
	v_add_f32_e32 v64, v71, v64
	v_exp_f32_e32 v76, v76
	v_add_f32_e32 v64, v72, v64
	v_exp_f32_e32 v77, v77
	v_add_f32_e32 v64, v73, v64
	v_exp_f32_e32 v78, v78
	v_add_f32_e32 v64, v74, v64
	v_exp_f32_e32 v79, v79
	v_add_f32_e32 v64, v75, v64
	v_add_f32_e32 v64, v76, v64
	v_add_f32_e32 v64, v77, v64
	v_add_f32_e32 v64, v78, v64
	v_add_f32_e32 v64, v79, v64
	v_add_f32_e32 v64, v96, v64
	v_cvt_pk_bf16_f32 v66, v97, v65
	v_cvt_pk_bf16_f32 v67, v106, v67
	v_cvt_pk_bf16_f32 v68, v68, v69
	v_cvt_pk_bf16_f32 v69, v70, v71
	v_cvt_pk_bf16_f32 v70, v72, v73
	v_cvt_pk_bf16_f32 v71, v74, v75
	v_cvt_pk_bf16_f32 v72, v76, v77
	v_cvt_pk_bf16_f32 v73, v78, v79
	s_waitcnt lgkmcnt(0)
; template <int TAG = 0> DI int fresh_tid(int wv) { int l; asm volatile("v_mbcnt_lo_u32_b32 %0, -1, 0\n\tv_mbcnt_hi_u32_b32 %0, -1, %0 ; site %1" : "=v"(l) : "n"(TAG)); return wv * 64 + l; }
; DI int crow(int r, int hi) { return (r & 3) + 8 * (r >> 2) + 4 * hi; }
; DI float swap_sum(float v) { auto rr = __builtin_amdgcn_permlane32_swap(__float_as_uint(v), __float_as_uint(v), false, false); return __uint_as_float(rr[0]) + __uint_as_float(rr[1]); }
; DI void pv_mma(f32x16* o, const s16x4* vf, bf16x8 pa0, bf16x8 pa1) {
;     ...
; #pragma unroll
;     for (int d0 = 0; d0 < 4; ++d0) {
;         o[d0] = __builtin_amdgcn_mfma_f32_32x32x16_bf16(pa0, ATT_PK(vf[4 * d0], vf[4 * d0 + 1]), o[d0], 0, 0, 0);
;         o[d0] = __builtin_amdgcn_mfma_f32_32x32x16_bf16(pa1, ATT_PK(vf[4 * d0 + 2], vf[4 * d0 + 3]), o[d0], 0, 0, 0); }
;     ...
; }
; template <int DQK, int MODE, int LDQ, int LDK, int LDV> ...
;     ...
;     l_reg = swap_sum(l_reg);
;     { const int lane2 = fresh_tid<110 + MODE>(wv) & 63, r32 = lane2 & 31, hi = lane2 >> 5;
;     if (hi == 0) li_l[r32] = l_reg;
;     asm volatile("s_waitcnt lgkmcnt(0)" ::: "memory");
;     float s0v[MODE == 2 ? 16 : 1][4];
;     if constexpr (MODE == 2) {
; #pragma unroll
;         for (int r = 0; r < 16; ++r)
; #pragma unroll
;             for (int d0 = 0; d0 < 4; ++d0) s0v[r][d0] = S0[(size_t)(wid * 32 + crow(r, hi)) * 512 + d0 * 32 + r32];
;     }
; #pragma unroll
;     for (int r = 0; r < 16; ++r) { const int orow = wid * 32 + crow(r, hi); const float rl = __builtin_amdgcn_rcpf(li_l[crow(r, hi)]);
	s_setprio 1
	v_mfma_f32_32x32x16_bf16 v[0:15], v[66:69], v[80:83], v[0:15]
	v_mfma_f32_32x32x16_bf16 v[48:63], v[66:69], v[88:91], v[48:63]
	v_mfma_f32_32x32x16_bf16 v[16:31], v[66:69], v[98:101], v[16:31]
	v_mfma_f32_32x32x16_bf16 v[32:47], v[66:69], v[108:111], v[32:47]
	v_mfma_f32_32x32x16_bf16 v[0:15], v[70:73], v[84:87], v[0:15]
	v_mfma_f32_32x32x16_bf16 v[48:63], v[70:73], v[92:95], v[48:63]
	v_mfma_f32_32x32x16_bf16 v[16:31], v[70:73], v[102:105], v[16:31]
	v_mfma_f32_32x32x16_bf16 v[32:47], v[70:73], v[112:115], v[32:47]
	s_setprio 0
	v_mov_b32_e32 v66, v64
	v_mbcnt_lo_u32_b32 v65, -1, 0
	v_mbcnt_hi_u32_b32 v65, -1, v65
	s_nop 1
	v_permlane32_swap_b32_e32 v64, v66
	v_and_b32_e32 v114, 63, v65
	v_and_b32_e32 v170, 31, v65
	v_cmp_gt_u32_e32 vcc, 32, v114
	s_and_saveexec_b64 s[2:3], vcc
	v_lshl_add_u32 v67, v170, 2, s0
	v_add_f32_e32 v64, v64, v66
	ds_write_b32 v67, v64
	s_or_b64 exec, exec, s[2:3]
	v_lshrrev_b32_e32 v64, 3, v65
	v_and_b32_e32 v69, 4, v64
	v_or_b32_e32 v102, s46, v69
	v_lshlrev_b32_e32 v130, 2, v170
	v_ashrrev_i32_e32 v103, 31, v102
	v_or_b32_e32 v66, 1, v102
	v_lshl_add_u64 v[92:93], s[54:55], 0, v[130:131]
	v_lshlrev_b64 v[156:157], 11, v[102:103]
	v_ashrrev_i32_e32 v67, 31, v66
	s_waitcnt lgkmcnt(0)
	v_lshl_add_u64 v[64:65], v[92:93], 0, v[156:157]
	v_lshlrev_b64 v[148:149], 11, v[66:67]
	v_lshl_add_u64 v[66:67], v[92:93], 0, v[148:149]
	global_load_dword v110, v[64:65], off
	global_load_dword v111, v[64:65], off offset:128
	global_load_dword v109, v[64:65], off offset:256
	global_load_dword v108, v[64:65], off offset:384
	global_load_dword v106, v[66:67], off
	global_load_dword v107, v[66:67], off offset:128
	global_load_dword v105, v[66:67], off offset:256
	global_load_dword v104, v[66:67], off offset:384
	v_or_b32_e32 v64, 2, v102
	v_or_b32_e32 v66, 3, v102
	v_ashrrev_i32_e32 v65, 31, v64
	v_ashrrev_i32_e32 v67, 31, v66
	v_lshlrev_b64 v[146:147], 11, v[64:65]
	v_lshlrev_b64 v[136:137], 11, v[66:67]
	v_lshl_add_u64 v[64:65], v[92:93], 0, v[146:147]
	v_lshl_add_u64 v[66:67], v[92:93], 0, v[136:137]
	global_load_dword v158, v[64:65], off
	global_load_dword v159, v[64:65], off offset:128
	global_load_dword v155, v[64:65], off offset:256
	global_load_dword v154, v[64:65], off offset:384
	global_load_dword v152, v[66:67], off
	global_load_dword v153, v[66:67], off offset:128
	global_load_dword v151, v[66:67], off offset:256
	global_load_dword v150, v[66:67], off offset:384
	v_or_b32_e32 v64, 8, v102
	v_or_b32_e32 v66, 9, v102
	v_ashrrev_i32_e32 v65, 31, v64
	v_ashrrev_i32_e32 v67, 31, v66
	v_lshlrev_b64 v[134:135], 11, v[64:65]
	v_lshlrev_b64 v[120:121], 11, v[66:67]
	v_lshl_add_u64 v[64:65], v[92:93], 0, v[134:135]
	v_lshl_add_u64 v[66:67], v[92:93], 0, v[120:121]
	global_load_dword v144, v[64:65], off
	global_load_dword v145, v[64:65], off offset:128
	global_load_dword v143, v[64:65], off offset:256
	global_load_dword v142, v[64:65], off offset:384
	global_load_dword v140, v[66:67], off
	global_load_dword v141, v[66:67], off offset:128
	global_load_dword v139, v[66:67], off offset:256
	global_load_dword v138, v[66:67], off offset:384
	v_or_b32_e32 v64, 10, v102
	v_or_b32_e32 v66, 11, v102
	v_ashrrev_i32_e32 v65, 31, v64
	v_ashrrev_i32_e32 v67, 31, v66
	v_lshlrev_b64 v[118:119], 11, v[64:65]
	v_lshlrev_b64 v[90:91], 11, v[66:67]
	v_lshl_add_u64 v[64:65], v[92:93], 0, v[118:119]
	v_lshl_add_u64 v[66:67], v[92:93], 0, v[90:91]
	global_load_dword v132, v[64:65], off
	global_load_dword v133, v[64:65], off offset:128
	global_load_dword v127, v[64:65], off offset:256
	global_load_dword v126, v[64:65], off offset:384
	global_load_dword v124, v[66:67], off
	global_load_dword v125, v[66:67], off offset:128
	global_load_dword v123, v[66:67], off offset:256
	global_load_dword v122, v[66:67], off offset:384
	v_or_b32_e32 v64, 16, v102
	v_or_b32_e32 v66, 17, v102
	v_ashrrev_i32_e32 v65, 31, v64
	v_ashrrev_i32_e32 v67, 31, v66
	v_lshlrev_b64 v[86:87], 11, v[64:65]
	v_lshlrev_b64 v[78:79], 11, v[66:67]
	v_lshl_add_u64 v[64:65], v[92:93], 0, v[86:87]
	v_lshl_add_u64 v[66:67], v[92:93], 0, v[78:79]
	global_load_dword v100, v[64:65], off
	global_load_dword v101, v[64:65], off offset:128
	global_load_dword v99, v[64:65], off offset:256
	global_load_dword v98, v[64:65], off offset:384
	global_load_dword v96, v[66:67], off
	global_load_dword v97, v[66:67], off offset:128
	global_load_dword v95, v[66:67], off offset:256
	global_load_dword v94, v[66:67], off offset:384
	v_or_b32_e32 v64, 18, v102
	v_or_b32_e32 v66, 19, v102
	v_ashrrev_i32_e32 v65, 31, v64
	v_ashrrev_i32_e32 v67, 31, v66
	v_lshlrev_b64 v[76:77], 11, v[64:65]
	v_lshlrev_b64 v[72:73], 11, v[66:67]
	v_lshl_add_u64 v[64:65], v[92:93], 0, v[76:77]
	v_lshl_add_u64 v[66:67], v[92:93], 0, v[72:73]
	v_lshl_add_u32 v169, v69, 2, s0
	global_load_dword v88, v[64:65], off
	global_load_dword v89, v[64:65], off offset:128
	global_load_dword v85, v[64:65], off offset:256
	global_load_dword v84, v[64:65], off offset:384
	global_load_dword v82, v[66:67], off
	global_load_dword v83, v[66:67], off offset:128
	global_load_dword v81, v[66:67], off offset:256
	global_load_dword v80, v[66:67], off offset:384
	ds_read_b128 v[64:67], v169
	v_or_b32_e32 v68, 24, v102
	v_ashrrev_i32_e32 v69, 31, v68
	v_lshlrev_b64 v[74:75], 11, v[68:69]
	ds_read_b128 v[68:71], v169 offset:32
	s_waitcnt lgkmcnt(0)
; DI unsigned short f2bf(float x) { unsigned u = __float_as_uint(x); u += 0x7fffu + ((u >> 16) & 1u); return (unsigned short)(u >> 16); }
; DI float shx(float v, int mask, int lane) { return __int_as_float(__builtin_amdgcn_ds_bpermute((lane ^ mask) << 2, __float_as_int(v))); }
; DI int crow(int r, int hi) { return (r & 3) + 8 * (r >> 2) + 4 * hi; }
; template <int DQK, int MODE, int LDQ, int LDK, int LDV> ...
;     ...
;     for (int r = 0; r < 16; ++r) { const int orow = wid * 32 + crow(r, hi); const float rl = __builtin_amdgcn_rcpf(li_l[crow(r, hi)]);
;         if constexpr (MODE == 0) {
; #pragma unroll
;             for (int d0 = 0; d0 < 4; ++d0) AOb[(size_t)orow * 1024 + d0 * 32 + r32] = f2bf(o[d0][r] * rl);
;         } else if constexpr (MODE == 1) {
; #pragma unroll
;             for (int d0 = 0; d0 < 4; ++d0) S0[(size_t)orow * 512 + d0 * 32 + r32] = o[d0][r] * rl;
;         } else {
;             float v[4]; float ss = 0.f;
; #pragma unroll
;             for (int d0 = 0; d0 < 4; ++d0) { v[d0] = s0v[r][d0] - lam * (o[d0][r] * rl); ss += v[d0] * v[d0]; }
; #pragma unroll
;             for (int mk = 1; mk <= 16; mk <<= 1) ss += shx(ss, mk, lane2);
;             const float rs = rsqrtf(ss * (1.f / 128.f) + EPS) * 0.8f;
; #pragma unroll
;             for (int d0 = 0; d0 < 4; ++d0) AOb[(size_t)orow * 1024 + d0 * 32 + r32] = f2bf(v[d0] * rs * gout[d0 * 32 + r32]);
;         } }
	v_rcp_f32_e32 v64, v64
	v_mov_b32_e32 v162, v0
	v_mov_b32_e32 v163, v48
	v_rcp_f32_e32 v0, v65
	v_pk_mul_f32 v[162:163], v[162:163], v[64:65] op_sel_hi:[1,0]
	v_mov_b32_e32 v48, v1
	v_lshlrev_b32_e32 v166, 2, v114
	v_pk_mul_f32 v[48:49], v[48:49], v[0:1] op_sel_hi:[1,0]
	v_xor_b32_e32 v164, 4, v166
	v_xor_b32_e32 v165, 8, v166
	v_xor_b32_e32 v168, 16, v166
	v_xor_b32_e32 v167, 32, v166
	v_or_b32_e32 v116, 25, v102
	v_ashrrev_i32_e32 v117, 31, v116
	v_xor_b32_e32 v166, 64, v166
	v_lshl_add_u64 v[112:113], v[92:93], 0, v[74:75]
	s_add_u32 s1, s60, s58
	s_mov_b32 s0, 0x358637bd
	s_addc_u32 s3, s61, s59
	s_lshl_b32 s2, s87, 1
	s_add_u32 s2, s1, s2
	s_addc_u32 s3, s3, 0
	s_waitcnt vmcnt(0)
	v_pk_fma_f32 v[172:173], v[128:129], v[162:163], v[110:111] neg_lo:[1,0,0] neg_hi:[1,0,0]
	v_mov_b32_e32 v162, v32
	v_mov_b32_e32 v163, v16
	v_pk_mul_f32 v[162:163], v[162:163], v[64:65] op_sel_hi:[1,0]
	v_mov_b32_e32 v16, v33
	v_pk_fma_f32 v[174:175], v[128:129], v[162:163], v[108:109] neg_lo:[1,0,0] neg_hi:[1,0,0]
	global_load_dword v163, v130, s[50:51]
	global_load_dword v162, v130, s[50:51] offset:128
	global_load_dword v161, v130, s[50:51] offset:256
	s_nop 0
	global_load_dword v130, v130, s[50:51] offset:384
	v_pk_fma_f32 v[176:177], v[128:129], v[48:49], v[106:107] neg_lo:[1,0,0] neg_hi:[1,0,0]
	v_pk_mul_f32 v[0:1], v[16:17], v[0:1] op_sel_hi:[1,0]
	v_pk_mul_f32 v[110:111], v[172:173], v[172:173]
	v_pk_mul_f32 v[48:49], v[176:177], v[176:177]
	v_pk_fma_f32 v[0:1], v[128:129], v[0:1], v[104:105] neg_lo:[1,0,0] neg_hi:[1,0,0]
	v_pk_mul_f32 v[108:109], v[174:175], v[174:175]
	v_pk_mul_f32 v[16:17], v[0:1], v[0:1]
	v_mov_b32_e32 v32, v48
	v_mov_b32_e32 v33, v110
	v_mov_b32_e32 v110, v49
	v_pk_add_f32 v[32:33], v[32:33], v[110:111]
	v_mov_b32_e32 v48, v17
	v_mov_b32_e32 v49, v109
	v_pk_add_f32 v[32:33], v[48:49], v[32:33]
	v_mov_b32_e32 v17, v108
	v_pk_add_f32 v[16:17], v[16:17], v[32:33]
	ds_bpermute_b32 v33, v164, v17
	ds_bpermute_b32 v32, v164, v16
	v_lshlrev_b64 v[64:65], 11, v[116:117]
	v_lshl_add_u64 v[48:49], v[92:93], 0, v[64:65]
	global_load_dword v116, v[112:113], off
	global_load_dword v117, v[112:113], off offset:128
	global_load_dword v115, v[112:113], off offset:256
	global_load_dword v114, v[112:113], off offset:384
	s_nop 0
	global_load_dword v112, v[48:49], off
	global_load_dword v113, v[48:49], off offset:128
	global_load_dword v111, v[48:49], off offset:256
	global_load_dword v110, v[48:49], off offset:384
	v_or_b32_e32 v48, 26, v102
	s_waitcnt lgkmcnt(0)
	v_pk_add_f32 v[16:17], v[16:17], v[32:33]
	ds_bpermute_b32 v33, v165, v17
	ds_bpermute_b32 v32, v165, v16
	v_or_b32_e32 v102, 27, v102
	v_ashrrev_i32_e32 v49, 31, v48
	v_ashrrev_i32_e32 v103, 31, v102
	v_lshlrev_b64 v[48:49], 11, v[48:49]
	s_waitcnt lgkmcnt(0)
	v_pk_add_f32 v[16:17], v[16:17], v[32:33]
	ds_bpermute_b32 v33, v168, v17
	ds_bpermute_b32 v32, v168, v16
	v_lshl_add_u64 v[104:105], v[92:93], 0, v[48:49]
	v_lshlrev_b32_e32 v170, 1, v170
	v_mov_b32_e32 v171, v131
	v_rcp_f32_e32 v66, v66
	s_waitcnt lgkmcnt(0)
	v_pk_add_f32 v[32:33], v[16:17], v[32:33]
	ds_bpermute_b32 v107, v167, v33
	ds_bpermute_b32 v106, v167, v32
	v_lshlrev_b64 v[16:17], 11, v[102:103]
	v_lshl_add_u64 v[92:93], v[92:93], 0, v[16:17]
	s_waitcnt lgkmcnt(0)
	v_pk_add_f32 v[32:33], v[32:33], v[106:107]
	ds_bpermute_b32 v179, v166, v33
	ds_bpermute_b32 v178, v166, v32
	global_load_dword v108, v[104:105], off
	global_load_dword v109, v[104:105], off offset:128
	global_load_dword v107, v[104:105], off offset:256
	global_load_dword v106, v[104:105], off offset:384
	s_nop 0
	global_load_dword v104, v[92:93], off
	global_load_dword v105, v[92:93], off offset:128
	global_load_dword v103, v[92:93], off offset:256
	global_load_dword v102, v[92:93], off offset:384
	v_mov_b64_e32 v[92:93], s[0:1]
	s_waitcnt lgkmcnt(0)
	v_pk_add_f32 v[32:33], v[32:33], v[178:179]
	s_nop 0
	v_pk_fma_f32 v[178:179], v[32:33], s[24:25], v[92:93] op_sel_hi:[1,0,0]
	s_nop 0
	v_mul_f32_e32 v32, 0x4b800000, v179
	v_cmp_gt_f32_e32 vcc, s67, v179
	s_nop 1
	v_cndmask_b32_e32 v32, v179, v32, vcc
	v_rsq_f32_e32 v179, v32
	v_lshl_add_u64 v[32:33], s[2:3], 0, v[170:171]
	v_lshl_add_u64 v[156:157], v[32:33], 0, v[156:157]
	v_lshl_add_u64 v[148:149], v[32:33], 0, v[148:149]
	v_mul_f32_e32 v170, 0x45800000, v179
	v_cndmask_b32_e32 v170, v179, v170, vcc
	v_mul_f32_e32 v170, 0x3f4ccccd, v170
	v_mul_f32_e32 v171, v172, v170
	v_cmp_gt_f32_e32 vcc, s67, v178
	s_mov_b64 s[2:3], 0
	s_waitcnt vmcnt(19)
	v_mul_f32_e32 v171, v163, v171
	v_bfe_u32 v172, v171, 16, 1
	v_add3_u32 v171, v171, v172, s68
	global_store_short_d16_hi v[156:157], v171, off offset:1024
	v_mul_f32_e32 v171, v173, v170
	s_waitcnt vmcnt(19)
	v_mul_f32_e32 v171, v162, v171
	v_bfe_u32 v172, v171, 16, 1
	v_add3_u32 v171, v171, v172, s68
	global_store_short_d16_hi v[156:157], v171, off offset:1088
	v_mul_f32_e32 v171, v175, v170
	s_waitcnt vmcnt(19)
	v_mul_f32_e32 v171, v161, v171
	v_bfe_u32 v172, v171, 16, 1
	v_add3_u32 v171, v171, v172, s68
	global_store_short_d16_hi v[156:157], v171, off offset:1152
	v_mul_f32_e32 v171, 0x4b800000, v178
	v_cndmask_b32_e32 v171, v178, v171, vcc
	v_mul_f32_e32 v170, v174, v170
	v_rsq_f32_e32 v171, v171
	s_waitcnt vmcnt(19)
; DI unsigned short f2bf(float x) { unsigned u = __float_as_uint(x); u += 0x7fffu + ((u >> 16) & 1u); return (unsigned short)(u >> 16); }
; DI float shx(float v, int mask, int lane) { return __int_as_float(__builtin_amdgcn_ds_bpermute((lane ^ mask) << 2, __float_as_int(v))); }
; template <int DQK, int MODE, int LDQ, int LDK, int LDV> ...
;     ...
;             float v[4]; float ss = 0.f;
; #pragma unroll
;             for (int d0 = 0; d0 < 4; ++d0) { v[d0] = s0v[r][d0] - lam * (o[d0][r] * rl); ss += v[d0] * v[d0]; }
; #pragma unroll
;             for (int mk = 1; mk <= 16; mk <<= 1) ss += shx(ss, mk, lane2);
;             const float rs = rsqrtf(ss * (1.f / 128.f) + EPS) * 0.8f;
; #pragma unroll
;             for (int d0 = 0; d0 < 4; ++d0) AOb[(size_t)orow * 1024 + d0 * 32 + r32] = f2bf(v[d0] * rs * gout[d0 * 32 + r32]);
;         } }
	v_mul_f32_e32 v170, v130, v170
	v_bfe_u32 v172, v170, 16, 1
	v_add3_u32 v170, v170, v172, s68
	global_store_short_d16_hi v[156:157], v170, off offset:1216
	v_mul_f32_e32 v156, 0x45800000, v171
	v_cndmask_b32_e32 v172, v171, v156, vcc
	v_mov_b32_e32 v156, v2
	v_rcp_f32_e32 v2, v67
	v_mov_b32_e32 v157, v50
	v_mov_b32_e32 v50, v3
	v_pk_mul_f32 v[156:157], v[156:157], v[66:67] op_sel_hi:[1,0]
	v_mov_b32_e32 v170, v34
	v_mov_b32_e32 v171, v18
	v_pk_mul_f32 v[50:51], v[50:51], v[2:3] op_sel_hi:[1,0]
	v_mov_b32_e32 v18, v35
	v_pk_fma_f32 v[156:157], v[128:129], v[156:157], v[158:159] neg_lo:[1,0,0] neg_hi:[1,0,0]
	v_pk_mul_f32 v[170:171], v[170:171], v[66:67] op_sel_hi:[1,0]
	v_pk_fma_f32 v[50:51], v[128:129], v[50:51], v[152:153] neg_lo:[1,0,0] neg_hi:[1,0,0]
	v_pk_mul_f32 v[2:3], v[18:19], v[2:3] op_sel_hi:[1,0]
	v_pk_mul_f32 v[158:159], v[156:157], v[156:157]
	v_pk_fma_f32 v[66:67], v[128:129], v[170:171], v[154:155] neg_lo:[1,0,0] neg_hi:[1,0,0]
	v_pk_mul_f32 v[152:153], v[50:51], v[50:51]
	v_pk_fma_f32 v[2:3], v[128:129], v[2:3], v[150:151] neg_lo:[1,0,0] neg_hi:[1,0,0]
	v_pk_mul_f32 v[154:155], v[66:67], v[66:67]
	v_pk_mul_f32 v[18:19], v[2:3], v[2:3]
	v_mov_b32_e32 v34, v152
	v_mov_b32_e32 v35, v158
	v_mov_b32_e32 v158, v153
	v_pk_add_f32 v[34:35], v[34:35], v[158:159]
	v_mov_b32_e32 v150, v19
	v_mov_b32_e32 v151, v155
	v_pk_add_f32 v[34:35], v[150:151], v[34:35]
	v_mov_b32_e32 v19, v154
	v_pk_add_f32 v[18:19], v[18:19], v[34:35]
	ds_bpermute_b32 v35, v164, v19
	ds_bpermute_b32 v34, v164, v18
	v_mul_f32_e32 v150, 0x3f4ccccd, v172
	v_mul_f32_e32 v151, v176, v150
	v_mul_f32_e32 v151, v163, v151
	v_bfe_u32 v152, v151, 16, 1
	s_waitcnt lgkmcnt(0)
	v_pk_add_f32 v[18:19], v[18:19], v[34:35]
	ds_bpermute_b32 v35, v165, v19
	ds_bpermute_b32 v34, v165, v18
	v_add3_u32 v151, v151, v152, s68
	global_store_short_d16_hi v[148:149], v151, off offset:1024
	v_mul_f32_e32 v151, v177, v150
	v_mul_f32_e32 v151, v162, v151
	s_waitcnt lgkmcnt(0)
	v_pk_add_f32 v[18:19], v[18:19], v[34:35]
	ds_bpermute_b32 v35, v168, v19
	ds_bpermute_b32 v34, v168, v18
	v_bfe_u32 v152, v151, 16, 1
	v_mul_f32_e32 v1, v1, v150
	v_add3_u32 v151, v151, v152, s68
	v_mul_f32_e32 v1, v161, v1
	s_waitcnt lgkmcnt(0)
	v_pk_add_f32 v[18:19], v[18:19], v[34:35]
	ds_bpermute_b32 v35, v167, v19
	ds_bpermute_b32 v34, v167, v18
	global_store_short_d16_hi v[148:149], v151, off offset:1088
	v_bfe_u32 v151, v1, 16, 1
	v_add3_u32 v1, v1, v151, s68
	v_mul_f32_e32 v0, v0, v150
	s_waitcnt lgkmcnt(0)
	v_pk_add_f32 v[18:19], v[18:19], v[34:35]
	ds_bpermute_b32 v35, v166, v19
	ds_bpermute_b32 v34, v166, v18
	global_store_short_d16_hi v[148:149], v1, off offset:1152
	v_mul_f32_e32 v150, v130, v0
	v_bfe_u32 v151, v150, 16, 1
	s_waitcnt lgkmcnt(0)
	v_pk_add_f32 v[0:1], v[18:19], v[34:35]
	s_nop 0
	v_pk_fma_f32 v[0:1], v[0:1], s[24:25], v[92:93] op_sel_hi:[1,0,0]
	s_nop 0
	v_mul_f32_e32 v18, 0x4b800000, v1
	v_cmp_gt_f32_e32 vcc, s67, v1
	s_nop 1
	v_cndmask_b32_e32 v1, v1, v18, vcc
	v_rsq_f32_e32 v1, v1
	v_add3_u32 v18, v150, v151, s68
	global_store_short_d16_hi v[148:149], v18, off offset:1216
	v_lshl_add_u64 v[18:19], v[32:33], 0, v[146:147]
	v_mul_f32_e32 v34, 0x45800000, v1
	v_cndmask_b32_e32 v1, v1, v34, vcc
	v_mul_f32_e32 v1, 0x3f4ccccd, v1
	v_mul_f32_e32 v34, v156, v1
	v_mul_f32_e32 v34, v163, v34
	v_bfe_u32 v35, v34, 16, 1
	v_add3_u32 v34, v34, v35, s68
	global_store_short_d16_hi v[18:19], v34, off offset:1024
	v_mul_f32_e32 v34, v157, v1
	v_mul_f32_e32 v34, v162, v34
	v_bfe_u32 v35, v34, 16, 1
	v_add3_u32 v34, v34, v35, s68
	global_store_short_d16_hi v[18:19], v34, off offset:1088
	v_mul_f32_e32 v34, v67, v1
	v_mul_f32_e32 v34, v161, v34
	v_bfe_u32 v35, v34, 16, 1
	v_add3_u32 v34, v34, v35, s68
	global_store_short_d16_hi v[18:19], v34, off offset:1152
	v_mul_f32_e32 v1, v66, v1
	v_mul_f32_e32 v34, 0x4b800000, v0
	v_cmp_gt_f32_e32 vcc, s67, v0
	v_mul_f32_e32 v1, v130, v1
	v_mov_b32_e32 v66, v36
	v_cndmask_b32_e32 v0, v0, v34, vcc
	v_rsq_f32_e32 v34, v0
	v_bfe_u32 v0, v1, 16, 1
	v_add3_u32 v0, v1, v0, s68
	global_store_short_d16_hi v[18:19], v0, off offset:1216
	v_rcp_f32_e32 v0, v68
	v_mov_b32_e32 v18, v4
	v_rcp_f32_e32 v4, v69
	v_mul_f32_e32 v1, 0x45800000, v34
	v_mov_b32_e32 v19, v52
	v_mov_b32_e32 v52, v5
	v_pk_mul_f32 v[18:19], v[18:19], v[0:1] op_sel_hi:[1,0]
	v_mov_b32_e32 v67, v20
	v_pk_mul_f32 v[52:53], v[52:53], v[4:5] op_sel_hi:[1,0]
	v_mov_b32_e32 v20, v37
	v_cndmask_b32_e32 v146, v34, v1, vcc
	v_pk_fma_f32 v[18:19], v[128:129], v[18:19], v[144:145] neg_lo:[1,0,0] neg_hi:[1,0,0]
	v_pk_mul_f32 v[0:1], v[66:67], v[0:1] op_sel_hi:[1,0]
	v_pk_fma_f32 v[52:53], v[128:129], v[52:53], v[140:141] neg_lo:[1,0,0] neg_hi:[1,0,0]
	v_pk_mul_f32 v[4:5], v[20:21], v[4:5] op_sel_hi:[1,0]
	v_pk_mul_f32 v[34:35], v[18:19], v[18:19]
	v_pk_fma_f32 v[0:1], v[128:129], v[0:1], v[142:143] neg_lo:[1,0,0] neg_hi:[1,0,0]
	v_pk_mul_f32 v[68:69], v[52:53], v[52:53]
	v_pk_fma_f32 v[4:5], v[128:129], v[4:5], v[138:139] neg_lo:[1,0,0] neg_hi:[1,0,0]
	v_pk_mul_f32 v[66:67], v[0:1], v[0:1]
	v_pk_mul_f32 v[20:21], v[4:5], v[4:5]
	v_mov_b32_e32 v36, v68
	v_mov_b32_e32 v37, v34
	v_mov_b32_e32 v34, v69
	v_pk_add_f32 v[34:35], v[36:37], v[34:35]
	v_mov_b32_e32 v36, v21
	v_mov_b32_e32 v37, v67
	v_pk_add_f32 v[34:35], v[36:37], v[34:35]
	v_mov_b32_e32 v21, v66
	v_pk_add_f32 v[20:21], v[20:21], v[34:35]
	ds_bpermute_b32 v35, v164, v21
	ds_bpermute_b32 v34, v164, v20
	v_mul_f32_e32 v66, 0x3f4ccccd, v146
	v_mul_f32_e32 v50, v50, v66
	v_mul_f32_e32 v50, v163, v50
	v_bfe_u32 v67, v50, 16, 1
	s_waitcnt lgkmcnt(0)
; DI unsigned short f2bf(float x) { unsigned u = __float_as_uint(x); u += 0x7fffu + ((u >> 16) & 1u); return (unsigned short)(u >> 16); }
; DI float shx(float v, int mask, int lane) { return __int_as_float(__builtin_amdgcn_ds_bpermute((lane ^ mask) << 2, __float_as_int(v))); }
; template <int DQK, int MODE, int LDQ, int LDK, int LDV> ...
;     ...
;             float v[4]; float ss = 0.f;
; #pragma unroll
;             for (int d0 = 0; d0 < 4; ++d0) { v[d0] = s0v[r][d0] - lam * (o[d0][r] * rl); ss += v[d0] * v[d0]; }
; #pragma unroll
;             for (int mk = 1; mk <= 16; mk <<= 1) ss += shx(ss, mk, lane2);
;             const float rs = rsqrtf(ss * (1.f / 128.f) + EPS) * 0.8f;
; #pragma unroll
;             for (int d0 = 0; d0 < 4; ++d0) AOb[(size_t)orow * 1024 + d0 * 32 + r32] = f2bf(v[d0] * rs * gout[d0 * 32 + r32]);
;         } }
	v_pk_add_f32 v[20:21], v[20:21], v[34:35]
	ds_bpermute_b32 v35, v165, v21
	ds_bpermute_b32 v34, v165, v20
	v_lshl_add_u64 v[36:37], v[32:33], 0, v[136:137]
	v_add3_u32 v50, v50, v67, s68
	global_store_short_d16_hi v[36:37], v50, off offset:1024
	v_mul_f32_e32 v50, v51, v66
	s_waitcnt lgkmcnt(0)
	v_pk_add_f32 v[20:21], v[20:21], v[34:35]
	ds_bpermute_b32 v35, v168, v21
	ds_bpermute_b32 v34, v168, v20
	v_mul_f32_e32 v50, v162, v50
	v_bfe_u32 v51, v50, 16, 1
	v_mul_f32_e32 v3, v3, v66
	v_add3_u32 v50, v50, v51, s68
	s_waitcnt lgkmcnt(0)
	v_pk_add_f32 v[20:21], v[20:21], v[34:35]
	ds_bpermute_b32 v35, v167, v21
	ds_bpermute_b32 v34, v167, v20
	v_mul_f32_e32 v3, v161, v3
	global_store_short_d16_hi v[36:37], v50, off offset:1088
	v_bfe_u32 v50, v3, 16, 1
	v_add3_u32 v3, v3, v50, s68
	s_waitcnt lgkmcnt(0)
	v_pk_add_f32 v[20:21], v[20:21], v[34:35]
	ds_bpermute_b32 v35, v166, v21
	ds_bpermute_b32 v34, v166, v20
	v_mul_f32_e32 v2, v2, v66
	global_store_short_d16_hi v[36:37], v3, off offset:1152
	v_mul_f32_e32 v50, v130, v2
	v_bfe_u32 v51, v50, 16, 1
	s_waitcnt lgkmcnt(0)
	v_pk_add_f32 v[2:3], v[20:21], v[34:35]
	s_nop 0
	v_pk_fma_f32 v[2:3], v[2:3], s[24:25], v[92:93] op_sel_hi:[1,0,0]
	s_nop 0
	v_mul_f32_e32 v20, 0x4b800000, v3
	v_cmp_gt_f32_e32 vcc, s67, v3
	s_nop 1
	v_cndmask_b32_e32 v3, v3, v20, vcc
	v_rsq_f32_e32 v3, v3
	v_add3_u32 v20, v50, v51, s68
	global_store_short_d16_hi v[36:37], v20, off offset:1216
	v_lshl_add_u64 v[20:21], v[32:33], 0, v[134:135]
	v_mul_f32_e32 v34, 0x45800000, v3
	v_cndmask_b32_e32 v3, v3, v34, vcc
	v_mul_f32_e32 v3, 0x3f4ccccd, v3
	v_mul_f32_e32 v18, v18, v3
	v_mul_f32_e32 v18, v163, v18
	v_bfe_u32 v34, v18, 16, 1
	v_add3_u32 v18, v18, v34, s68
	global_store_short_d16_hi v[20:21], v18, off offset:1024
	v_mul_f32_e32 v18, v19, v3
	v_mul_f32_e32 v18, v162, v18
	v_bfe_u32 v19, v18, 16, 1
	v_mul_f32_e32 v1, v1, v3
	v_add3_u32 v18, v18, v19, s68
	v_mul_f32_e32 v1, v161, v1
	global_store_short_d16_hi v[20:21], v18, off offset:1088
	v_bfe_u32 v18, v1, 16, 1
	v_add3_u32 v1, v1, v18, s68
	global_store_short_d16_hi v[20:21], v1, off offset:1152
	v_mul_f32_e32 v1, 0x4b800000, v2
	v_cmp_gt_f32_e32 vcc, s67, v2
	v_mul_f32_e32 v0, v0, v3
	v_mul_f32_e32 v0, v130, v0
	v_cndmask_b32_e32 v1, v2, v1, vcc
	v_rsq_f32_e32 v1, v1
	v_bfe_u32 v2, v0, 16, 1
	v_add3_u32 v0, v0, v2, s68
	global_store_short_d16_hi v[20:21], v0, off offset:1216
	v_mul_f32_e32 v2, 0x45800000, v1
	v_rcp_f32_e32 v0, v70
	v_cndmask_b32_e32 v66, v1, v2, vcc
	v_mov_b32_e32 v2, v6
	v_rcp_f32_e32 v6, v71
	v_mov_b32_e32 v3, v54
	v_mov_b32_e32 v18, v38
	v_mov_b32_e32 v19, v22
	v_mov_b32_e32 v54, v7
	v_pk_mul_f32 v[2:3], v[2:3], v[0:1] op_sel_hi:[1,0]
	v_pk_mul_f32 v[0:1], v[18:19], v[0:1] op_sel_hi:[1,0]
	v_pk_mul_f32 v[18:19], v[54:55], v[6:7] op_sel_hi:[1,0]
	v_mov_b32_e32 v22, v39
	v_pk_fma_f32 v[2:3], v[128:129], v[2:3], v[132:133] neg_lo:[1,0,0] neg_hi:[1,0,0]
	v_pk_fma_f32 v[20:21], v[128:129], v[18:19], v[124:125] neg_lo:[1,0,0] neg_hi:[1,0,0]
	v_pk_mul_f32 v[6:7], v[22:23], v[6:7] op_sel_hi:[1,0]
	v_pk_mul_f32 v[34:35], v[2:3], v[2:3]
	v_pk_fma_f32 v[0:1], v[128:129], v[0:1], v[126:127] neg_lo:[1,0,0] neg_hi:[1,0,0]
	v_pk_mul_f32 v[50:51], v[20:21], v[20:21]
	v_pk_fma_f32 v[18:19], v[128:129], v[6:7], v[122:123] neg_lo:[1,0,0] neg_hi:[1,0,0]
	v_pk_mul_f32 v[36:37], v[0:1], v[0:1]
	v_pk_mul_f32 v[6:7], v[18:19], v[18:19]
	v_mov_b32_e32 v22, v50
	v_mov_b32_e32 v23, v34
	v_mov_b32_e32 v34, v51
	v_pk_add_f32 v[22:23], v[22:23], v[34:35]
	v_mov_b32_e32 v34, v7
	v_mov_b32_e32 v35, v37
	v_pk_add_f32 v[22:23], v[34:35], v[22:23]
	v_mov_b32_e32 v7, v36
	v_pk_add_f32 v[6:7], v[6:7], v[22:23]
	ds_bpermute_b32 v23, v164, v7
	ds_bpermute_b32 v22, v164, v6
	v_mul_f32_e32 v36, 0x3f4ccccd, v66
	v_mul_f32_e32 v37, v52, v36
	v_mul_f32_e32 v37, v163, v37
	v_bfe_u32 v38, v37, 16, 1
	s_waitcnt lgkmcnt(0)
	v_pk_add_f32 v[6:7], v[6:7], v[22:23]
	ds_bpermute_b32 v23, v165, v7
	ds_bpermute_b32 v22, v165, v6
	v_lshl_add_u64 v[34:35], v[32:33], 0, v[120:121]
	v_add3_u32 v37, v37, v38, s68
	global_store_short_d16_hi v[34:35], v37, off offset:1024
	v_mul_f32_e32 v37, v53, v36
	s_waitcnt lgkmcnt(0)
	v_pk_add_f32 v[6:7], v[6:7], v[22:23]
	ds_bpermute_b32 v23, v168, v7
	ds_bpermute_b32 v22, v168, v6
	v_mul_f32_e32 v37, v162, v37
	v_bfe_u32 v38, v37, 16, 1
	v_mul_f32_e32 v5, v5, v36
	v_add3_u32 v37, v37, v38, s68
	s_waitcnt lgkmcnt(0)
	v_pk_add_f32 v[6:7], v[6:7], v[22:23]
	ds_bpermute_b32 v23, v167, v7
	ds_bpermute_b32 v22, v167, v6
	v_mul_f32_e32 v5, v161, v5
	global_store_short_d16_hi v[34:35], v37, off offset:1088
	v_bfe_u32 v37, v5, 16, 1
	v_add3_u32 v5, v5, v37, s68
	s_waitcnt lgkmcnt(0)
	v_pk_add_f32 v[6:7], v[6:7], v[22:23]
	ds_bpermute_b32 v23, v166, v7
	ds_bpermute_b32 v22, v166, v6
	v_mul_f32_e32 v4, v4, v36
	global_store_short_d16_hi v[34:35], v5, off offset:1152
	v_mul_f32_e32 v36, v130, v4
	v_bfe_u32 v37, v36, 16, 1
	s_waitcnt lgkmcnt(0)
	v_pk_add_f32 v[4:5], v[6:7], v[22:23]
	v_lshl_add_u64 v[22:23], v[32:33], 0, v[118:119]
	v_pk_fma_f32 v[4:5], v[4:5], s[24:25], v[92:93] op_sel_hi:[1,0,0]
	s_nop 0
	v_mul_f32_e32 v6, 0x4b800000, v5
	v_cmp_gt_f32_e32 vcc, s67, v5
	s_nop 1
	v_cndmask_b32_e32 v5, v5, v6, vcc
	v_rsq_f32_e32 v5, v5
	v_add3_u32 v6, v36, v37, s68
	global_store_short_d16_hi v[34:35], v6, off offset:1216
	v_mov_b32_e32 v36, v40
	v_mul_f32_e32 v6, 0x45800000, v5
	v_cndmask_b32_e32 v5, v5, v6, vcc
	v_mul_f32_e32 v5, 0x3f4ccccd, v5
	v_mul_f32_e32 v2, v2, v5
	v_mul_f32_e32 v2, v163, v2
	v_bfe_u32 v6, v2, 16, 1
	v_add3_u32 v2, v2, v6, s68
	global_store_short_d16_hi v[22:23], v2, off offset:1024
	v_mul_f32_e32 v2, v3, v5
	v_mul_f32_e32 v2, v162, v2
	v_bfe_u32 v3, v2, 16, 1
	v_mul_f32_e32 v1, v1, v5
	v_add3_u32 v2, v2, v3, s68
	v_mul_f32_e32 v1, v161, v1
	global_store_short_d16_hi v[22:23], v2, off offset:1088
	v_bfe_u32 v2, v1, 16, 1
	v_add3_u32 v1, v1, v2, s68
	v_mul_f32_e32 v2, 0x4b800000, v4
	v_cmp_gt_f32_e32 vcc, s67, v4
	v_mul_f32_e32 v0, v0, v5
	v_mul_f32_e32 v0, v130, v0
	v_cndmask_b32_e32 v2, v4, v2, vcc
	ds_read_b128 v[4:7], v169 offset:64
	global_store_short_d16_hi v[22:23], v1, off offset:1152
	v_bfe_u32 v1, v0, 16, 1
	v_rsq_f32_e32 v34, v2
	v_add3_u32 v0, v0, v1, s68
	global_store_short_d16_hi v[22:23], v0, off offset:1216
	ds_read_b128 v[0:3], v169 offset:96
	s_waitcnt lgkmcnt(1)
; DI unsigned short f2bf(float x) { unsigned u = __float_as_uint(x); u += 0x7fffu + ((u >> 16) & 1u); return (unsigned short)(u >> 16); }
; DI float shx(float v, int mask, int lane) { return __int_as_float(__builtin_amdgcn_ds_bpermute((lane ^ mask) << 2, __float_as_int(v))); }
; template <int DQK, int MODE, int LDQ, int LDK, int LDV> ...
;     ...
;             float v[4]; float ss = 0.f;
; #pragma unroll
;             for (int d0 = 0; d0 < 4; ++d0) { v[d0] = s0v[r][d0] - lam * (o[d0][r] * rl); ss += v[d0] * v[d0]; }
; #pragma unroll
;             for (int mk = 1; mk <= 16; mk <<= 1) ss += shx(ss, mk, lane2);
;             const float rs = rsqrtf(ss * (1.f / 128.f) + EPS) * 0.8f;
; #pragma unroll
;             for (int d0 = 0; d0 < 4; ++d0) AOb[(size_t)orow * 1024 + d0 * 32 + r32] = f2bf(v[d0] * rs * gout[d0 * 32 + r32]);
;         } }
	v_rcp_f32_e32 v4, v4
	v_mul_f32_e32 v22, 0x45800000, v34
	v_cndmask_b32_e32 v52, v34, v22, vcc
	v_mov_b32_e32 v22, v8
	v_mov_b32_e32 v23, v56
	v_mov_b32_e32 v37, v24
	v_pk_mul_f32 v[22:23], v[22:23], v[4:5] op_sel_hi:[1,0]
	v_pk_mul_f32 v[36:37], v[36:37], v[4:5] op_sel_hi:[1,0]
	v_rcp_f32_e32 v4, v5
	v_mov_b32_e32 v56, v9
	v_mov_b32_e32 v24, v41
	v_pk_fma_f32 v[22:23], v[128:129], v[22:23], v[100:101] neg_lo:[1,0,0] neg_hi:[1,0,0]
	v_pk_mul_f32 v[8:9], v[56:57], v[4:5] op_sel_hi:[1,0]
	v_pk_mul_f32 v[4:5], v[24:25], v[4:5] op_sel_hi:[1,0]
	v_pk_fma_f32 v[8:9], v[128:129], v[8:9], v[96:97] neg_lo:[1,0,0] neg_hi:[1,0,0]
	v_pk_mul_f32 v[34:35], v[22:23], v[22:23]
	v_pk_fma_f32 v[36:37], v[128:129], v[36:37], v[98:99] neg_lo:[1,0,0] neg_hi:[1,0,0]
	v_pk_mul_f32 v[50:51], v[8:9], v[8:9]
	v_pk_fma_f32 v[4:5], v[128:129], v[4:5], v[94:95] neg_lo:[1,0,0] neg_hi:[1,0,0]
	v_pk_mul_f32 v[38:39], v[36:37], v[36:37]
	v_pk_mul_f32 v[24:25], v[4:5], v[4:5]
	v_mov_b32_e32 v40, v50
	v_mov_b32_e32 v41, v34
	v_mov_b32_e32 v34, v51
	v_pk_add_f32 v[34:35], v[40:41], v[34:35]
	v_mov_b32_e32 v40, v25
	v_mov_b32_e32 v41, v39
	v_pk_add_f32 v[34:35], v[40:41], v[34:35]
	v_mov_b32_e32 v25, v38
	v_pk_add_f32 v[24:25], v[24:25], v[34:35]
	ds_bpermute_b32 v35, v164, v25
	ds_bpermute_b32 v34, v164, v24
	v_mul_f32_e32 v40, 0x3f4ccccd, v52
	v_mul_f32_e32 v20, v20, v40
	v_mul_f32_e32 v20, v163, v20
	v_bfe_u32 v41, v20, 16, 1
	s_waitcnt lgkmcnt(0)
	v_pk_add_f32 v[24:25], v[24:25], v[34:35]
	ds_bpermute_b32 v35, v165, v25
	ds_bpermute_b32 v34, v165, v24
	v_lshl_add_u64 v[38:39], v[32:33], 0, v[90:91]
	v_add3_u32 v20, v20, v41, s68
	global_store_short_d16_hi v[38:39], v20, off offset:1024
	v_mul_f32_e32 v41, v21, v40
	s_waitcnt lgkmcnt(0)
	v_pk_add_f32 v[20:21], v[24:25], v[34:35]
	ds_bpermute_b32 v25, v168, v21
	ds_bpermute_b32 v24, v168, v20
	v_mul_f32_e32 v34, v162, v41
	v_bfe_u32 v35, v34, 16, 1
	v_mul_f32_e32 v19, v19, v40
	v_add3_u32 v34, v34, v35, s68
	s_waitcnt lgkmcnt(0)
	v_pk_add_f32 v[20:21], v[20:21], v[24:25]
	ds_bpermute_b32 v25, v167, v21
	ds_bpermute_b32 v24, v167, v20
	v_mul_f32_e32 v19, v161, v19
	global_store_short_d16_hi v[38:39], v34, off offset:1088
	v_bfe_u32 v34, v19, 16, 1
	v_add3_u32 v19, v19, v34, s68
	s_waitcnt lgkmcnt(0)
	v_pk_add_f32 v[20:21], v[20:21], v[24:25]
	ds_bpermute_b32 v25, v166, v21
	ds_bpermute_b32 v24, v166, v20
	v_mul_f32_e32 v18, v18, v40
	global_store_short_d16_hi v[38:39], v19, off offset:1152
	v_mul_f32_e32 v34, v130, v18
	v_bfe_u32 v35, v34, 16, 1
	s_waitcnt lgkmcnt(0)
	v_pk_add_f32 v[18:19], v[20:21], v[24:25]
	v_rcp_f32_e32 v6, v6
	v_pk_fma_f32 v[18:19], v[18:19], s[24:25], v[92:93] op_sel_hi:[1,0,0]
	v_rcp_f32_e32 v0, v0
	v_mul_f32_e32 v20, 0x4b800000, v19
	v_cmp_gt_f32_e32 vcc, s67, v19
	v_rcp_f32_e32 v2, v2
	s_nop 0
	v_cndmask_b32_e32 v19, v19, v20, vcc
	v_rsq_f32_e32 v19, v19
	v_add3_u32 v20, v34, v35, s68
	global_store_short_d16_hi v[38:39], v20, off offset:1216
	v_lshl_add_u64 v[20:21], v[32:33], 0, v[86:87]
	v_mul_f32_e32 v24, 0x45800000, v19
	v_cndmask_b32_e32 v19, v19, v24, vcc
	v_mul_f32_e32 v19, 0x3f4ccccd, v19
	v_mul_f32_e32 v22, v22, v19
	v_mul_f32_e32 v22, v163, v22
	v_bfe_u32 v24, v22, 16, 1
	v_add3_u32 v22, v22, v24, s68
	global_store_short_d16_hi v[20:21], v22, off offset:1024
	v_mul_f32_e32 v22, v23, v19
	v_mul_f32_e32 v22, v162, v22
	v_bfe_u32 v23, v22, 16, 1
	v_add3_u32 v22, v22, v23, s68
	global_store_short_d16_hi v[20:21], v22, off offset:1088
	v_mul_f32_e32 v22, v37, v19
	v_mul_f32_e32 v22, v161, v22
	v_bfe_u32 v23, v22, 16, 1
	v_add3_u32 v22, v22, v23, s68
	global_store_short_d16_hi v[20:21], v22, off offset:1152
	v_mul_f32_e32 v22, 0x4b800000, v18
	v_cmp_gt_f32_e32 vcc, s67, v18
	v_mul_f32_e32 v19, v36, v19
	v_mul_f32_e32 v19, v130, v19
	v_cndmask_b32_e32 v18, v18, v22, vcc
	v_rsq_f32_e32 v18, v18
	v_bfe_u32 v22, v19, 16, 1
	v_add3_u32 v19, v19, v22, s68
	global_store_short_d16_hi v[20:21], v19, off offset:1216
	v_mul_f32_e32 v19, 0x45800000, v18
	v_cndmask_b32_e32 v38, v18, v19, vcc
	v_mov_b32_e32 v18, v10
	v_mov_b32_e32 v19, v58
	v_mov_b32_e32 v22, v42
	v_mov_b32_e32 v23, v26
	v_pk_mul_f32 v[18:19], v[18:19], v[6:7] op_sel_hi:[1,0]
	v_pk_mul_f32 v[22:23], v[22:23], v[6:7] op_sel_hi:[1,0]
	v_rcp_f32_e32 v6, v7
	v_mov_b32_e32 v58, v11
	v_mov_b32_e32 v26, v43
	v_pk_fma_f32 v[18:19], v[128:129], v[18:19], v[88:89] neg_lo:[1,0,0] neg_hi:[1,0,0]
	v_pk_mul_f32 v[10:11], v[58:59], v[6:7] op_sel_hi:[1,0]
	v_pk_mul_f32 v[6:7], v[26:27], v[6:7] op_sel_hi:[1,0]
	v_pk_fma_f32 v[10:11], v[128:129], v[10:11], v[82:83] neg_lo:[1,0,0] neg_hi:[1,0,0]
	v_pk_mul_f32 v[20:21], v[18:19], v[18:19]
	v_pk_fma_f32 v[22:23], v[128:129], v[22:23], v[84:85] neg_lo:[1,0,0] neg_hi:[1,0,0]
	v_pk_mul_f32 v[34:35], v[10:11], v[10:11]
	v_pk_fma_f32 v[6:7], v[128:129], v[6:7], v[80:81] neg_lo:[1,0,0] neg_hi:[1,0,0]
	v_pk_mul_f32 v[24:25], v[22:23], v[22:23]
	v_pk_mul_f32 v[26:27], v[6:7], v[6:7]
	v_mov_b32_e32 v36, v34
	v_mov_b32_e32 v37, v20
	v_mov_b32_e32 v20, v35
	v_pk_add_f32 v[20:21], v[36:37], v[20:21]
	v_mov_b32_e32 v34, v27
	v_mov_b32_e32 v35, v25
	v_pk_add_f32 v[20:21], v[34:35], v[20:21]
	v_mov_b32_e32 v27, v24
	v_pk_add_f32 v[20:21], v[26:27], v[20:21]
	ds_bpermute_b32 v25, v164, v21
	ds_bpermute_b32 v24, v164, v20
	v_mul_f32_e32 v34, 0x3f4ccccd, v38
	v_mul_f32_e32 v8, v8, v34
	v_mul_f32_e32 v8, v163, v8
	v_bfe_u32 v35, v8, 16, 1
	s_waitcnt lgkmcnt(0)
	v_pk_add_f32 v[20:21], v[20:21], v[24:25]
	ds_bpermute_b32 v25, v165, v21
	ds_bpermute_b32 v24, v165, v20
	v_lshl_add_u64 v[26:27], v[32:33], 0, v[78:79]
	v_add3_u32 v8, v8, v35, s68
	global_store_short_d16_hi v[26:27], v8, off offset:1024
	v_mul_f32_e32 v35, v9, v34
	s_waitcnt lgkmcnt(0)
; DI unsigned short f2bf(float x) { unsigned u = __float_as_uint(x); u += 0x7fffu + ((u >> 16) & 1u); return (unsigned short)(u >> 16); }
; DI float shx(float v, int mask, int lane) { return __int_as_float(__builtin_amdgcn_ds_bpermute((lane ^ mask) << 2, __float_as_int(v))); }
; template <int DQK, int MODE, int LDQ, int LDK, int LDV> ...
;     ...
;             float v[4]; float ss = 0.f;
; #pragma unroll
;             for (int d0 = 0; d0 < 4; ++d0) { v[d0] = s0v[r][d0] - lam * (o[d0][r] * rl); ss += v[d0] * v[d0]; }
; #pragma unroll
;             for (int mk = 1; mk <= 16; mk <<= 1) ss += shx(ss, mk, lane2);
;             const float rs = rsqrtf(ss * (1.f / 128.f) + EPS) * 0.8f;
; #pragma unroll
;             for (int d0 = 0; d0 < 4; ++d0) AOb[(size_t)orow * 1024 + d0 * 32 + r32] = f2bf(v[d0] * rs * gout[d0 * 32 + r32]);
;         } }
	v_pk_add_f32 v[8:9], v[20:21], v[24:25]
	ds_bpermute_b32 v21, v168, v9
	ds_bpermute_b32 v20, v168, v8
	v_mul_f32_e32 v24, v162, v35
	v_bfe_u32 v25, v24, 16, 1
	v_mul_f32_e32 v5, v5, v34
	v_add3_u32 v24, v24, v25, s68
	s_waitcnt lgkmcnt(0)
	v_pk_add_f32 v[8:9], v[8:9], v[20:21]
	ds_bpermute_b32 v21, v167, v9
	ds_bpermute_b32 v20, v167, v8
	v_mul_f32_e32 v5, v161, v5
	global_store_short_d16_hi v[26:27], v24, off offset:1088
	v_bfe_u32 v24, v5, 16, 1
	v_add3_u32 v5, v5, v24, s68
	s_waitcnt lgkmcnt(0)
	v_pk_add_f32 v[8:9], v[8:9], v[20:21]
	ds_bpermute_b32 v21, v166, v9
	ds_bpermute_b32 v20, v166, v8
	v_mul_f32_e32 v4, v4, v34
	global_store_short_d16_hi v[26:27], v5, off offset:1152
	v_mul_f32_e32 v24, v130, v4
	v_bfe_u32 v25, v24, 16, 1
	s_waitcnt lgkmcnt(0)
	v_pk_add_f32 v[4:5], v[8:9], v[20:21]
	s_nop 0
	v_pk_fma_f32 v[4:5], v[4:5], s[24:25], v[92:93] op_sel_hi:[1,0,0]
	s_nop 0
	v_mul_f32_e32 v8, 0x4b800000, v5
	v_cmp_gt_f32_e32 vcc, s67, v5
	s_nop 1
	v_cndmask_b32_e32 v5, v5, v8, vcc
	v_rsq_f32_e32 v5, v5
	v_add3_u32 v8, v24, v25, s68
	global_store_short_d16_hi v[26:27], v8, off offset:1216
	v_lshl_add_u64 v[8:9], v[32:33], 0, v[76:77]
	v_mul_f32_e32 v20, 0x45800000, v5
	v_cndmask_b32_e32 v5, v5, v20, vcc
	v_mul_f32_e32 v5, 0x3f4ccccd, v5
	v_mul_f32_e32 v18, v18, v5
	v_mul_f32_e32 v18, v163, v18
	v_bfe_u32 v20, v18, 16, 1
	v_add3_u32 v18, v18, v20, s68
	global_store_short_d16_hi v[8:9], v18, off offset:1024
	v_mul_f32_e32 v18, v19, v5
	v_mul_f32_e32 v18, v162, v18
	v_bfe_u32 v19, v18, 16, 1
	v_add3_u32 v18, v18, v19, s68
	global_store_short_d16_hi v[8:9], v18, off offset:1088
	v_mul_f32_e32 v18, v23, v5
	v_mul_f32_e32 v18, v161, v18
	v_bfe_u32 v19, v18, 16, 1
	v_add3_u32 v18, v18, v19, s68
	global_store_short_d16_hi v[8:9], v18, off offset:1152
	v_mul_f32_e32 v18, 0x4b800000, v4
	v_cmp_gt_f32_e32 vcc, s67, v4
	v_mul_f32_e32 v5, v22, v5
	v_mul_f32_e32 v5, v130, v5
	v_cndmask_b32_e32 v4, v4, v18, vcc
	v_rsq_f32_e32 v4, v4
	v_bfe_u32 v18, v5, 16, 1
	v_add3_u32 v5, v5, v18, s68
	global_store_short_d16_hi v[8:9], v5, off offset:1216
	v_mul_f32_e32 v5, 0x45800000, v4
	v_cndmask_b32_e32 v34, v4, v5, vcc
	v_mov_b32_e32 v4, v12
	v_mov_b32_e32 v5, v60
	v_mov_b32_e32 v18, v44
	v_mov_b32_e32 v19, v28
	v_pk_mul_f32 v[4:5], v[4:5], v[0:1] op_sel_hi:[1,0]
	v_pk_mul_f32 v[18:19], v[18:19], v[0:1] op_sel_hi:[1,0]
	v_rcp_f32_e32 v0, v1
	v_mov_b32_e32 v60, v13
	v_mov_b32_e32 v28, v45
	s_waitcnt vmcnt(58)
	v_pk_fma_f32 v[4:5], v[128:129], v[4:5], v[116:117] neg_lo:[1,0,0] neg_hi:[1,0,0]
	v_pk_mul_f32 v[12:13], v[60:61], v[0:1] op_sel_hi:[1,0]
	v_pk_mul_f32 v[0:1], v[28:29], v[0:1] op_sel_hi:[1,0]
	s_waitcnt vmcnt(54)
	v_pk_fma_f32 v[12:13], v[128:129], v[12:13], v[112:113] neg_lo:[1,0,0] neg_hi:[1,0,0]
	v_pk_mul_f32 v[8:9], v[4:5], v[4:5]
	v_pk_fma_f32 v[18:19], v[128:129], v[18:19], v[114:115] neg_lo:[1,0,0] neg_hi:[1,0,0]
	v_pk_mul_f32 v[22:23], v[12:13], v[12:13]
	s_waitcnt vmcnt(52)
	v_pk_fma_f32 v[0:1], v[128:129], v[0:1], v[110:111] neg_lo:[1,0,0] neg_hi:[1,0,0]
	v_pk_mul_f32 v[20:21], v[18:19], v[18:19]
	v_pk_mul_f32 v[24:25], v[0:1], v[0:1]
	v_mov_b32_e32 v26, v22
	v_mov_b32_e32 v27, v8
	v_mov_b32_e32 v8, v23
	v_pk_add_f32 v[8:9], v[26:27], v[8:9]
	v_mov_b32_e32 v22, v25
	v_mov_b32_e32 v23, v21
	v_pk_add_f32 v[8:9], v[22:23], v[8:9]
	v_mov_b32_e32 v25, v20
	v_pk_add_f32 v[8:9], v[24:25], v[8:9]
	ds_bpermute_b32 v21, v164, v9
	ds_bpermute_b32 v20, v164, v8
	v_mul_f32_e32 v24, 0x3f4ccccd, v34
	v_mul_f32_e32 v10, v10, v24
	v_mul_f32_e32 v10, v163, v10
	v_bfe_u32 v25, v10, 16, 1
	s_waitcnt lgkmcnt(0)
	v_pk_add_f32 v[8:9], v[8:9], v[20:21]
	ds_bpermute_b32 v21, v165, v9
	ds_bpermute_b32 v20, v165, v8
	v_lshl_add_u64 v[22:23], v[32:33], 0, v[72:73]
	v_add3_u32 v10, v10, v25, s68
	global_store_short_d16_hi v[22:23], v10, off offset:1024
	v_mul_f32_e32 v25, v11, v24
	s_waitcnt lgkmcnt(0)
	v_pk_add_f32 v[8:9], v[8:9], v[20:21]
	ds_bpermute_b32 v11, v168, v9
	ds_bpermute_b32 v10, v168, v8
	v_mul_f32_e32 v20, v162, v25
	v_bfe_u32 v21, v20, 16, 1
	v_mul_f32_e32 v7, v7, v24
	v_add3_u32 v20, v20, v21, s68
	s_waitcnt lgkmcnt(0)
	v_pk_add_f32 v[8:9], v[8:9], v[10:11]
	ds_bpermute_b32 v11, v167, v9
	ds_bpermute_b32 v10, v167, v8
	v_mul_f32_e32 v7, v161, v7
	global_store_short_d16_hi v[22:23], v20, off offset:1088
	v_bfe_u32 v20, v7, 16, 1
	v_add3_u32 v7, v7, v20, s68
	s_waitcnt lgkmcnt(0)
	v_pk_add_f32 v[8:9], v[8:9], v[10:11]
	ds_bpermute_b32 v11, v166, v9
	ds_bpermute_b32 v10, v166, v8
	v_mul_f32_e32 v6, v6, v24
	global_store_short_d16_hi v[22:23], v7, off offset:1152
	v_mul_f32_e32 v20, v130, v6
	v_bfe_u32 v21, v20, 16, 1
	s_waitcnt lgkmcnt(0)
	v_pk_add_f32 v[6:7], v[8:9], v[10:11]
	s_nop 0
	v_pk_fma_f32 v[6:7], v[6:7], s[24:25], v[92:93] op_sel_hi:[1,0,0]
	s_nop 0
	v_mul_f32_e32 v8, 0x4b800000, v7
	v_cmp_gt_f32_e32 vcc, s67, v7
	s_nop 1
	v_cndmask_b32_e32 v7, v7, v8, vcc
	v_rsq_f32_e32 v7, v7
	v_add3_u32 v8, v20, v21, s68
	global_store_short_d16_hi v[22:23], v8, off offset:1216
	v_lshl_add_u64 v[8:9], v[32:33], 0, v[74:75]
	v_mul_f32_e32 v10, 0x45800000, v7
	v_cndmask_b32_e32 v7, v7, v10, vcc
	v_mul_f32_e32 v7, 0x3f4ccccd, v7
	v_mul_f32_e32 v4, v4, v7
	v_mul_f32_e32 v4, v163, v4
	v_bfe_u32 v10, v4, 16, 1
	v_add3_u32 v4, v4, v10, s68
	global_store_short_d16_hi v[8:9], v4, off offset:1024
	v_mul_f32_e32 v4, v5, v7
	v_mul_f32_e32 v4, v162, v4
	v_bfe_u32 v5, v4, 16, 1
	v_add3_u32 v4, v4, v5, s68
	global_store_short_d16_hi v[8:9], v4, off offset:1088
	v_mul_f32_e32 v4, v19, v7
	v_mul_f32_e32 v4, v161, v4
	v_bfe_u32 v5, v4, 16, 1
	v_add3_u32 v4, v4, v5, s68
	v_mul_f32_e32 v5, 0x4b800000, v6
	v_cmp_gt_f32_e32 vcc, s67, v6
	global_store_short_d16_hi v[8:9], v4, off offset:1152
	v_mul_f32_e32 v4, v18, v7
	v_cndmask_b32_e32 v5, v6, v5, vcc
	v_rsq_f32_e32 v5, v5
	v_mul_f32_e32 v4, v130, v4
	v_bfe_u32 v6, v4, 16, 1
	v_add3_u32 v4, v4, v6, s68
	global_store_short_d16_hi v[8:9], v4, off offset:1216
	v_mul_f32_e32 v4, 0x45800000, v5
	v_cndmask_b32_e32 v24, v5, v4, vcc
	v_mov_b32_e32 v4, v14
	v_mov_b32_e32 v5, v62
	v_mov_b32_e32 v8, v46
	v_mov_b32_e32 v9, v30
	v_pk_mul_f32 v[4:5], v[4:5], v[2:3] op_sel_hi:[1,0]
	v_pk_mul_f32 v[8:9], v[8:9], v[2:3] op_sel_hi:[1,0]
	v_rcp_f32_e32 v2, v3
	v_mov_b32_e32 v62, v15
	v_mov_b32_e32 v30, v47
	s_waitcnt vmcnt(58)
; DI unsigned short f2bf(float x) { unsigned u = __float_as_uint(x); u += 0x7fffu + ((u >> 16) & 1u); return (unsigned short)(u >> 16); }
; DI float shx(float v, int mask, int lane) { return __int_as_float(__builtin_amdgcn_ds_bpermute((lane ^ mask) << 2, __float_as_int(v))); }
; template <int DQK, int MODE, int LDQ, int LDK, int LDV> ...
;     ...
;             float v[4]; float ss = 0.f;
; #pragma unroll
;             for (int d0 = 0; d0 < 4; ++d0) { v[d0] = s0v[r][d0] - lam * (o[d0][r] * rl); ss += v[d0] * v[d0]; }
; #pragma unroll
;             for (int mk = 1; mk <= 16; mk <<= 1) ss += shx(ss, mk, lane2);
;             const float rs = rsqrtf(ss * (1.f / 128.f) + EPS) * 0.8f;
; #pragma unroll
;             for (int d0 = 0; d0 < 4; ++d0) AOb[(size_t)orow * 1024 + d0 * 32 + r32] = f2bf(v[d0] * rs * gout[d0 * 32 + r32]);
;         } }
; DI void phase4(const Params& p, LAS unsigned char* lds, int wv) {
;     ...
;             att::attn_body<64, 2, 2048, 2048, 2048>(P + qrow * 2048 + 512 + h * 128 + 64, P + rowbase * 2048 + 1024 + h * 128 + 64, P + rowbase * 2048 + 1536 + h * 128, qb * 256, 0.f,
;                                                    nullptr, S0 + qrow * 512 + h * 128, AO + qrow * 1024 + 512 + h * 128, lam, p.diff_out_norm_w, lds, wv);
;             __syncthreads();
	v_pk_fma_f32 v[4:5], v[128:129], v[4:5], v[108:109] neg_lo:[1,0,0] neg_hi:[1,0,0]
	v_pk_mul_f32 v[14:15], v[62:63], v[2:3] op_sel_hi:[1,0]
	v_pk_mul_f32 v[2:3], v[30:31], v[2:3] op_sel_hi:[1,0]
	s_waitcnt vmcnt(54)
	v_pk_fma_f32 v[14:15], v[128:129], v[14:15], v[104:105] neg_lo:[1,0,0] neg_hi:[1,0,0]
	v_pk_mul_f32 v[6:7], v[4:5], v[4:5]
	v_pk_fma_f32 v[8:9], v[128:129], v[8:9], v[106:107] neg_lo:[1,0,0] neg_hi:[1,0,0]
	v_pk_mul_f32 v[18:19], v[14:15], v[14:15]
	s_waitcnt vmcnt(52)
	v_pk_fma_f32 v[2:3], v[128:129], v[2:3], v[102:103] neg_lo:[1,0,0] neg_hi:[1,0,0]
	v_pk_mul_f32 v[10:11], v[8:9], v[8:9]
	v_pk_mul_f32 v[20:21], v[2:3], v[2:3]
	v_mov_b32_e32 v22, v18
	v_mov_b32_e32 v23, v6
	v_mov_b32_e32 v6, v19
	v_pk_add_f32 v[6:7], v[22:23], v[6:7]
	v_mov_b32_e32 v18, v21
	v_mov_b32_e32 v19, v11
	v_pk_add_f32 v[6:7], v[18:19], v[6:7]
	v_mov_b32_e32 v21, v10
	v_pk_add_f32 v[6:7], v[20:21], v[6:7]
	ds_bpermute_b32 v11, v164, v7
	ds_bpermute_b32 v10, v164, v6
	v_mul_f32_e32 v20, 0x3f4ccccd, v24
	v_mul_f32_e32 v12, v12, v20
	v_mul_f32_e32 v12, v163, v12
	v_bfe_u32 v21, v12, 16, 1
	s_waitcnt lgkmcnt(0)
	v_pk_add_f32 v[6:7], v[6:7], v[10:11]
	ds_bpermute_b32 v11, v165, v7
	ds_bpermute_b32 v10, v165, v6
	v_lshl_add_u64 v[18:19], v[32:33], 0, v[64:65]
	v_add3_u32 v12, v12, v21, s68
	global_store_short_d16_hi v[18:19], v12, off offset:1024
	v_mul_f32_e32 v12, v13, v20
	s_waitcnt lgkmcnt(0)
	v_pk_add_f32 v[6:7], v[6:7], v[10:11]
	ds_bpermute_b32 v11, v168, v7
	ds_bpermute_b32 v10, v168, v6
	v_mul_f32_e32 v12, v162, v12
	v_bfe_u32 v13, v12, 16, 1
	v_mul_f32_e32 v1, v1, v20
	v_add3_u32 v12, v12, v13, s68
	s_waitcnt lgkmcnt(0)
	v_pk_add_f32 v[6:7], v[6:7], v[10:11]
	ds_bpermute_b32 v11, v167, v7
	ds_bpermute_b32 v10, v167, v6
	v_mul_f32_e32 v1, v161, v1
	global_store_short_d16_hi v[18:19], v12, off offset:1088
	v_bfe_u32 v12, v1, 16, 1
	v_add3_u32 v1, v1, v12, s68
	s_waitcnt lgkmcnt(0)
	v_pk_add_f32 v[6:7], v[6:7], v[10:11]
	ds_bpermute_b32 v11, v166, v7
	ds_bpermute_b32 v10, v166, v6
	v_mul_f32_e32 v0, v0, v20
	global_store_short_d16_hi v[18:19], v1, off offset:1152
	v_mul_f32_e32 v12, v130, v0
	v_bfe_u32 v13, v12, 16, 1
	s_waitcnt lgkmcnt(0)
	v_pk_add_f32 v[0:1], v[6:7], v[10:11]
	s_nop 0
	v_pk_fma_f32 v[0:1], v[0:1], s[24:25], v[92:93] op_sel_hi:[1,0,0]
	s_nop 0
	v_mul_f32_e32 v6, 0x4b800000, v1
	v_cmp_gt_f32_e32 vcc, s67, v1
	s_nop 1
	v_cndmask_b32_e32 v1, v1, v6, vcc
	v_rsq_f32_e32 v1, v1
	v_add3_u32 v6, v12, v13, s68
	global_store_short_d16_hi v[18:19], v6, off offset:1216
	v_lshl_add_u64 v[6:7], v[32:33], 0, v[48:49]
	v_mul_f32_e32 v10, 0x45800000, v1
	v_cndmask_b32_e32 v1, v1, v10, vcc
	v_mul_f32_e32 v1, 0x3f4ccccd, v1
	v_mul_f32_e32 v4, v4, v1
	v_mul_f32_e32 v4, v163, v4
	v_bfe_u32 v10, v4, 16, 1
	v_add3_u32 v4, v4, v10, s68
	global_store_short_d16_hi v[6:7], v4, off offset:1024
	v_mul_f32_e32 v4, v5, v1
	v_mul_f32_e32 v4, v162, v4
	v_bfe_u32 v5, v4, 16, 1
	v_add3_u32 v4, v4, v5, s68
	global_store_short_d16_hi v[6:7], v4, off offset:1088
	v_mul_f32_e32 v4, v9, v1
	v_mul_f32_e32 v4, v161, v4
	v_bfe_u32 v5, v4, 16, 1
	v_add3_u32 v4, v4, v5, s68
	global_store_short_d16_hi v[6:7], v4, off offset:1152
	v_mul_f32_e32 v4, 0x4b800000, v0
	v_cmp_gt_f32_e32 vcc, s67, v0
	v_mul_f32_e32 v1, v8, v1
	v_mul_f32_e32 v1, v130, v1
	v_cndmask_b32_e32 v0, v0, v4, vcc
	v_rsq_f32_e32 v0, v0
	v_bfe_u32 v4, v1, 16, 1
	v_add3_u32 v1, v1, v4, s68
	global_store_short_d16_hi v[6:7], v1, off offset:1216
	v_mul_f32_e32 v1, 0x45800000, v0
	v_cndmask_b32_e32 v0, v0, v1, vcc
	v_mul_f32_e32 v4, 0x3f4ccccd, v0
	v_mul_f32_e32 v5, v14, v4
	v_mul_f32_e32 v5, v163, v5
	v_bfe_u32 v6, v5, 16, 1
	v_lshl_add_u64 v[0:1], v[32:33], 0, v[16:17]
	v_add3_u32 v5, v5, v6, s68
	global_store_short_d16_hi v[0:1], v5, off offset:1024
	v_mul_f32_e32 v5, v15, v4
	v_mul_f32_e32 v5, v162, v5
	v_bfe_u32 v6, v5, 16, 1
	v_mul_f32_e32 v3, v3, v4
	v_add3_u32 v5, v5, v6, s68
	v_mul_f32_e32 v3, v161, v3
	global_store_short_d16_hi v[0:1], v5, off offset:1088
	v_bfe_u32 v5, v3, 16, 1
	v_mul_f32_e32 v2, v2, v4
	v_add3_u32 v3, v3, v5, s68
	v_mul_f32_e32 v2, v130, v2
	global_store_short_d16_hi v[0:1], v3, off offset:1152
	v_bfe_u32 v3, v2, 16, 1
	v_add3_u32 v2, v2, v3, s68
	global_store_short_d16_hi v[0:1], v2, off offset:1216
	s_waitcnt vmcnt(63) expcnt(7) lgkmcnt(15)
	s_barrier
; #define ATT_DMA_K(t) do { const bf16_t* kg_ = Kh + (size_t)(t) * 64 * LDK; LAS unsigned char* sb_ = lds + ((t) & 3) * KBUF; \
;     _Pragma("unroll") for (int i_ = 0; i_ < NKP; ++i_) __builtin_amdgcn_global_load_lds((const unsigned*)(kg_ + kgo[i_]), (LAS unsigned*)(sb_ + (wid + 8 * i_) * 1024), 16, 0, 0); } while (0)
; #define ATT_DMA_V(t, vs) do { const bf16_t* vg_ = Vh + (size_t)(t) * 64 * LDV; LAS unsigned char* sb_ = lds + V_OFF + (vs) * SHM_V; \
;     _Pragma("unroll") for (int i_ = 0; i_ < 2; ++i_) __builtin_amdgcn_global_load_lds((const unsigned*)(vg_ + vgo[i_]), (LAS unsigned*)(sb_ + (2 * wid + i_) * 1024), 16, 0, 0); } while (0)
; template <int DQK, int MODE, int LDQ, int LDK, int LDV> ...
;     ...
;     int kgo[NKP], vgo[2];
; #pragma unroll
;     for (int i = 0; i < NKP; ++i) { const int L = (wid + 8 * i) * 64 + lane, row = L / CPR, slot = L % CPR, cc = (slot & ~7) | ((slot & 7) ^ ((row >> 1) & 7)); kgo[i] = row * LDK + cc * 8; }
; #pragma unroll
;     for (int i = 0; i < 2; ++i) { const int L = (2 * wid + i) * 64 + lane, st = L >> 5, w5 = L & 31, kk = (st >> 2) * 8 + (w5 >> 2), c = (st & 3) * 32 + (w5 & 3) * 8;
;         const int k = (kk & ~0xC) | ((kk & 4) << 1) | ((kk & 8) >> 1); vgo[i] = k * LDV + c; }
;     ...
;     ATT_DMA_K(0); ATT_DMA_K(1); ATT_DMA_V(0, 0); ATT_DMA_K(2); ATT_DMA_V(1, 1);
;     bf16x8 qr[ND0];
;     { const bf16_t* Qw = Qb + (size_t)(wid * 32 + r32) * LDQ + hi * 8;
; #pragma unroll
;       for (int d0 = 0; d0 < ND0; ++d0) qr[d0] = *(const bf16x8*)(Qw + d0 * 16);
; DI void phase4(const Params& p, LAS unsigned char* lds, int wv) {
;     ...
;     for (int L = blockIdx.x; L < 2048; L += gridDim.x) {
;         const int i = L >> 8, c = L & 255, x = c & 7, j = c >> 3, g = i * 8 + x, b = g >> 2, h = g & 3, kind = ((j >> 4) + i) & 1, qb = j & 15;
;         const size_t rowbase = (size_t)b * SEQ, qrow = rowbase + qb * 256;
;         if (kind == 0) {
;             att::attn_body<192, 0, 768, 768, 512>(Q + qrow * 768 + h * 192, KM + rowbase * 768 + h * 192, V + rowbase * 512 + h * 128, qb * 256, 0.07216878364870322f * LOG2E,
.LBB0_1978:
	s_and_b64 vcc, exec, s[2:3]
	s_cbranch_vccz .LBB0_1911
	v_mbcnt_lo_u32_b32 v36, -1, 0
	v_mbcnt_hi_u32_b32 v36, -1, v36
	s_mul_i32 s0, s41, 0x600
	v_add_u32_e32 v0, s33, v36
	s_mul_hi_u32 s1, s40, 0x600
	v_readfirstlane_b32 s55, v0
	s_add_i32 s1, s1, s0
	s_mul_i32 s0, s40, 0x600
	v_mov_b32_e32 v1, s55
	v_bfi_b32 v1, s63, v1, v36
	v_mul_hi_i32 v2, v1, s69
	v_lshrrev_b32_e32 v3, 31, v2
	v_ashrrev_i32_e32 v2, 2, v2
	v_add_u32_e32 v2, v2, v3
	s_add_u32 s0, s18, s0
	v_mul_lo_u32 v3, v2, 24
	s_addc_u32 s1, s19, s1
	s_mul_i32 s2, s86, 0x180
	v_sub_u32_e32 v3, v1, v3
	v_lshrrev_b32_e32 v4, 1, v2
	s_add_u32 s46, s0, s2
	v_bitop3_b32 v3, v4, v3, 7 bitop3:0x6c
	v_mul_lo_u32 v2, v2, s70
	s_addc_u32 s47, s1, 0
	s_mul_i32 s54, s42, 0x600000
	v_lshl_add_u32 v28, v3, 3, v2
	v_add_u32_e32 v2, 0x200, v1
	s_mul_hi_i32 s53, s42, 0x600000
	s_add_u32 s0, s20, s54
	v_mul_hi_i32 v3, v2, s69
	s_addc_u32 s1, s21, s53
	v_lshrrev_b32_e32 v4, 31, v3
	v_ashrrev_i32_e32 v3, 2, v3
	s_add_u32 s44, s0, s2
	v_add_u32_e32 v3, v3, v4
	s_addc_u32 s45, s1, 0
	s_lshl_b64 s[4:5], s[42:43], 22
	v_mul_lo_u32 v4, v3, 24
	s_add_u32 s0, s12, s4
	v_sub_u32_e32 v2, v2, v4
	v_lshrrev_b32_e32 v4, 1, v3
	s_addc_u32 s1, s13, s5
	s_lshl_b32 s2, s86, 8
	v_bitop3_b32 v2, v4, v2, 7 bitop3:0x6c
	v_mul_lo_u32 v3, v3, s70
	v_add_u32_e32 v1, 0x400, v1
	s_add_u32 s2, s0, s2
	v_lshl_add_u32 v30, v2, 3, v3
	v_mul_hi_i32 v2, v1, s69
	s_addc_u32 s3, s1, 0
	s_ashr_i32 s56, s55, 6
	v_lshrrev_b32_e32 v3, 31, v2
	v_ashrrev_i32_e32 v2, 2, v2
	v_add_u32_e32 v2, v2, v3
	s_lshl_b32 s0, s56, 7
	v_mul_lo_u32 v3, v2, 24
	s_ashr_i32 s0, s0, 4
	v_bfe_u32 v39, v0, 2, 2
	v_lshrrev_b32_e32 v0, 2, v0
	v_sub_u32_e32 v1, v1, v3
	v_lshrrev_b32_e32 v3, 1, v2
	v_lshlrev_b32_e32 v42, 3, v36
	s_and_b32 s57, s0, -16
	v_and_b32_e32 v41, 4, v0
	s_lshr_b32 s0, s0, 0
	v_bitop3_b32 v1, v3, v1, 7 bitop3:0x6c
	v_mul_lo_u32 v2, v2, s70
	v_and_b32_e32 v38, 32, v36
	v_and_b32_e32 v40, 24, v42
	s_and_b32 s58, s0, 8
	v_or3_b32 v0, v41, v39, s57
	s_lshl_b32 s0, s56, 10
	v_ashrrev_i32_e32 v29, 31, v28
	v_lshl_add_u32 v32, v1, 3, v2
	v_or_b32_e32 v1, v38, v40
	v_or_b32_e32 v0, s58, v0
	s_add_i32 s49, s0, 0
	v_lshlrev_b64 v[4:5], 1, v[28:29]
	v_ashrrev_i32_e32 v31, 31, v30
	v_lshl_or_b32 v132, v0, 9, v1
	v_lshl_add_u64 v[0:1], s[44:45], 0, v[4:5]
	s_mov_b32 m0, s49
	v_lshlrev_b64 v[6:7], 1, v[30:31]
	global_load_lds_dwordx4 v[0:1], off
	v_lshl_add_u64 v[0:1], s[44:45], 0, v[6:7]
	s_add_i32 m0, s49, 0x2000
	v_ashrrev_i32_e32 v33, 31, v32
	global_load_lds_dwordx4 v[0:1], off
	s_add_i32 m0, s49, 0x4000
	v_lshlrev_b64 v[0:1], 1, v[32:33]
	s_add_u32 s0, s44, 0x18000
	v_lshl_add_u64 v[2:3], s[44:45], 0, v[0:1]
	s_addc_u32 s1, s45, 0
	global_load_lds_dwordx4 v[2:3], off
	s_add_i32 m0, s49, 0x6000
	v_lshl_add_u64 v[2:3], s[0:1], 0, v[4:5]
	global_load_lds_dwordx4 v[2:3], off
	v_lshl_add_u64 v[2:3], s[0:1], 0, v[6:7]
	s_add_i32 m0, s49, 0x8000
	v_ashrrev_i32_e32 v133, 31, v132
	global_load_lds_dwordx4 v[2:3], off
	v_lshl_add_u64 v[2:3], s[0:1], 0, v[0:1]
	s_lshl_b32 s0, s56, 11
	s_add_i32 m0, s49, 0xa000
	s_add_i32 s59, s0, 0
	global_load_lds_dwordx4 v[2:3], off
	s_add_i32 s52, s59, 0x18000
	v_lshlrev_b64 v[2:3], 1, v[132:133]
	v_lshl_add_u64 v[8:9], s[2:3], 0, v[2:3]
	s_mov_b32 m0, s52
	s_mov_b64 s[0:1], 0x80
	global_load_lds_dwordx4 v[8:9], off
	s_add_i32 m0, s59, 0x18400
	s_add_u32 s42, s44, 0x30000
	v_lshl_add_u64 v[8:9], v[8:9], 0, s[0:1]
	s_addc_u32 s43, s45, 0
	global_load_lds_dwordx4 v[8:9], off
	s_add_i32 m0, s49, 0xc000
	v_lshl_add_u64 v[4:5], s[42:43], 0, v[4:5]
	global_load_lds_dwordx4 v[4:5], off
	v_lshl_add_u64 v[4:5], s[42:43], 0, v[6:7]
	s_add_i32 m0, s49, 0xe000
	v_and_b32_e32 v37, 31, v36
	global_load_lds_dwordx4 v[4:5], off
	s_add_i32 m0, s49, 0x10000
	s_add_u32 s44, s2, 0x10000
	s_addc_u32 s45, s3, 0
	s_lshl_b32 s48, s56, 5
	v_or_b32_e32 v6, s48, v37
	v_mov_b64_e32 v[4:5], s[46:47]
	s_movk_i32 s0, 0x600
	v_lshrrev_b32_e32 v43, 1, v36
	v_mad_i64_i32 v[4:5], s[0:1], v6, s0, v[4:5]
	v_and_b32_e32 v130, 16, v43
	v_lshl_add_u64 v[24:25], v[4:5], 0, v[130:131]
	global_load_dwordx4 v[16:19], v[24:25], off
	global_load_dwordx4 v[20:23], v[24:25], off offset:32
	global_load_dwordx4 v[4:7], v[24:25], off offset:64
	global_load_dwordx4 v[12:15], v[24:25], off offset:96
	global_load_dwordx4 v[8:11], v[24:25], off offset:128
	v_lshl_add_u64 v[0:1], s[42:43], 0, v[0:1]
	global_load_lds_dwordx4 v[0:1], off
	s_add_i32 m0, s59, 0x1c000
	v_lshl_add_u64 v[0:1], s[44:45], 0, v[2:3]
	global_load_lds_dwordx4 v[0:1], off
	global_load_dwordx4 v[0:3], v[24:25], off offset:160
	v_or_b32_e32 v134, 64, v132
	v_ashrrev_i32_e32 v135, 31, v134
	v_lshl_add_u64 v[34:35], v[134:135], 1, s[44:45]
	s_add_i32 m0, s59, 0x1c400
	s_movk_i32 s0, 0x180
	s_movk_i32 s1, 0x80
	s_movk_i32 s6, 0xa0
	v_mad_u32_u24 v158, v37, s0, 0
	s_waitcnt vmcnt(0)
; DI float bf2f(unsigned short h) { return __uint_as_float((unsigned)h << 16); }
; DI unsigned cvtpk(float lo, float hi) { unsigned r; asm volatile("v_cvt_pk_bf16_f32 %0, %1, %2" : "=v"(r) : "v"(lo), "v"(hi)); return r; }
; DI float swap_sum(float v) { auto rr = __builtin_amdgcn_permlane32_swap(__float_as_uint(v), __float_as_uint(v), false, false); return __uint_as_float(rr[0]) + __uint_as_float(rr[1]); }
; template <int DQK, int MODE, int LDQ, int LDK, int LDV> ...
;     ...
;       for (int d0 = 0; d0 < ND0; ++d0) qr[d0] = *(const bf16x8*)(Qw + d0 * 16);
;       if constexpr (MODE == 0) {
;           float ss = 0.f;
; #pragma unroll
;           for (int d0 = 0; d0 < ND0; ++d0)
; #pragma unroll
;               for (int j = 0; j < 8; ++j) { const float f = bf2f((unsigned short)qr[d0][j]); ss += f * f; }
;           ss = swap_sum(ss);
;           const float rstd = rsqrtf(ss * (1.f / DQK) + EPS) * C;
; #pragma unroll
;           for (int d0 = 0; d0 < ND0; ++d0) { const float* g = gq + d0 * 16 + hi * 8;
;               { float f[8]; _Pragma("unroll") for (int j = 0; j < 8; ++j) f[j] = bf2f((unsigned short)qr[d0][j]) * rstd * g[j];
;                 u32x4 w = {cvtpk(f[0], f[1]), cvtpk(f[2], f[3]), cvtpk(f[4], f[5]), cvtpk(f[6], f[7])}; qr[d0] = __builtin_bit_cast(bf16x8, w); asm volatile("" ::: "memory"); } }
;       } }
	v_lshlrev_b32_e32 v62, 16, v16
	v_and_b32_e32 v44, 0xffff0000, v16
	v_lshlrev_b32_e32 v45, 16, v17
	v_and_b32_e32 v49, 0xffff0000, v17
	v_lshlrev_b32_e32 v50, 16, v18
	v_and_b32_e32 v51, 0xffff0000, v18
	v_lshlrev_b32_e32 v52, 16, v19
	v_and_b32_e32 v53, 0xffff0000, v19
	global_load_dwordx4 v[16:19], v[24:25], off offset:192
	v_lshlrev_b32_e32 v48, 16, v20
	v_and_b32_e32 v46, 0xffff0000, v20
	v_lshlrev_b32_e32 v47, 16, v21
	v_and_b32_e32 v57, 0xffff0000, v21
	v_lshlrev_b32_e32 v58, 16, v22
	v_and_b32_e32 v59, 0xffff0000, v22
	v_lshlrev_b32_e32 v60, 16, v23
	v_and_b32_e32 v61, 0xffff0000, v23
	global_load_dwordx4 v[20:23], v[24:25], off offset:224
	v_lshlrev_b32_e32 v56, 16, v4
	v_and_b32_e32 v54, 0xffff0000, v4
	v_lshlrev_b32_e32 v55, 16, v5
	v_and_b32_e32 v66, 0xffff0000, v5
	v_lshlrev_b32_e32 v67, 16, v6
	v_and_b32_e32 v68, 0xffff0000, v6
	v_lshlrev_b32_e32 v69, 16, v7
	v_and_b32_e32 v70, 0xffff0000, v7
	global_load_dwordx4 v[4:7], v[24:25], off offset:256
	v_lshlrev_b32_e32 v65, 16, v12
	v_and_b32_e32 v64, 0xffff0000, v12
	v_lshlrev_b32_e32 v97, 16, v13
	v_and_b32_e32 v96, 0xffff0000, v13
	v_lshlrev_b32_e32 v95, 16, v14
	v_and_b32_e32 v94, 0xffff0000, v14
	v_lshlrev_b32_e32 v93, 16, v15
	v_and_b32_e32 v92, 0xffff0000, v15
	global_load_dwordx4 v[12:15], v[24:25], off offset:288
	v_lshlrev_b32_e32 v74, 16, v8
	v_and_b32_e32 v72, 0xffff0000, v8
	v_lshlrev_b32_e32 v71, 16, v9
	v_and_b32_e32 v113, 0xffff0000, v9
	v_lshlrev_b32_e32 v103, 16, v10
	v_and_b32_e32 v102, 0xffff0000, v10
	v_lshlrev_b32_e32 v99, 16, v11
	v_and_b32_e32 v98, 0xffff0000, v11
	global_load_dwordx4 v[8:11], v[24:25], off offset:352
	s_nop 0
	global_load_dwordx4 v[24:27], v[24:25], off offset:320
	v_mul_f32_e32 v63, v44, v44
	v_fmac_f32_e32 v63, v62, v62
	v_fmac_f32_e32 v63, v45, v45
	v_fmac_f32_e32 v63, v49, v49
	v_fmac_f32_e32 v63, v50, v50
	v_fmac_f32_e32 v63, v51, v51
	v_fmac_f32_e32 v63, v52, v52
	v_fmac_f32_e32 v63, v53, v53
	v_fmac_f32_e32 v63, v48, v48
	v_fmac_f32_e32 v63, v46, v46
	v_fmac_f32_e32 v63, v47, v47
	v_fmac_f32_e32 v63, v57, v57
	v_fmac_f32_e32 v63, v58, v58
	v_fmac_f32_e32 v63, v59, v59
	v_fmac_f32_e32 v63, v60, v60
	v_fmac_f32_e32 v63, v61, v61
	v_fmac_f32_e32 v63, v56, v56
	v_fmac_f32_e32 v63, v54, v54
	v_fmac_f32_e32 v63, v55, v55
	v_fmac_f32_e32 v63, v66, v66
	v_fmac_f32_e32 v63, v67, v67
	v_fmac_f32_e32 v63, v68, v68
	v_fmac_f32_e32 v63, v69, v69
	v_fmac_f32_e32 v63, v70, v70
	v_fmac_f32_e32 v63, v65, v65
	v_fmac_f32_e32 v63, v64, v64
	v_fmac_f32_e32 v63, v97, v97
	v_fmac_f32_e32 v63, v96, v96
	v_fmac_f32_e32 v63, v95, v95
	v_fmac_f32_e32 v63, v94, v94
	v_fmac_f32_e32 v63, v93, v93
	v_fmac_f32_e32 v63, v92, v92
	v_fmac_f32_e32 v63, v74, v74
	v_lshlrev_b32_e32 v101, 16, v0
	v_and_b32_e32 v100, 0xffff0000, v0
	v_lshlrev_b32_e32 v119, 16, v1
	v_and_b32_e32 v118, 0xffff0000, v1
	v_lshlrev_b32_e32 v117, 16, v2
	v_and_b32_e32 v116, 0xffff0000, v2
	v_lshlrev_b32_e32 v115, 16, v3
	v_and_b32_e32 v114, 0xffff0000, v3
	v_fmac_f32_e32 v63, v72, v72
	v_fmac_f32_e32 v63, v71, v71
	s_waitcnt vmcnt(0)
	v_lshlrev_b32_e32 v112, 16, v16
	v_and_b32_e32 v111, 0xffff0000, v16
	v_lshlrev_b32_e32 v110, 16, v17
	v_and_b32_e32 v109, 0xffff0000, v17
	v_lshlrev_b32_e32 v107, 16, v18
	v_and_b32_e32 v106, 0xffff0000, v18
	v_lshlrev_b32_e32 v105, 16, v19
	v_and_b32_e32 v104, 0xffff0000, v19
	global_load_dwordx4 v[0:3], v38, s[26:27] offset:16
	global_load_dwordx4 v[16:19], v38, s[26:27]
	v_fmac_f32_e32 v63, v113, v113
	v_fmac_f32_e32 v63, v103, v103
	v_fmac_f32_e32 v63, v102, v102
	v_fmac_f32_e32 v63, v99, v99
	v_fmac_f32_e32 v63, v98, v98
	v_fmac_f32_e32 v63, v101, v101
	v_fmac_f32_e32 v63, v100, v100
	v_fmac_f32_e32 v63, v119, v119
	v_fmac_f32_e32 v63, v118, v118
	v_fmac_f32_e32 v63, v117, v117
	v_fmac_f32_e32 v63, v116, v116
	v_fmac_f32_e32 v63, v115, v115
	v_fmac_f32_e32 v63, v114, v114
	v_fmac_f32_e32 v63, v112, v112
	v_fmac_f32_e32 v63, v111, v111
	v_fmac_f32_e32 v63, v110, v110
	v_fmac_f32_e32 v63, v109, v109
	v_fmac_f32_e32 v63, v107, v107
	v_fmac_f32_e32 v63, v106, v106
	v_fmac_f32_e32 v63, v105, v105
	v_fmac_f32_e32 v63, v104, v104
	v_lshlrev_b32_e32 v108, 16, v20
	v_fmac_f32_e32 v63, v108, v108
	v_and_b32_e32 v79, 0xffff0000, v20
	v_fmac_f32_e32 v63, v79, v79
	v_lshlrev_b32_e32 v78, 16, v21
	v_fmac_f32_e32 v63, v78, v78
	v_and_b32_e32 v77, 0xffff0000, v21
	v_fmac_f32_e32 v63, v77, v77
	v_lshlrev_b32_e32 v76, 16, v22
	v_fmac_f32_e32 v63, v76, v76
	v_and_b32_e32 v75, 0xffff0000, v22
	v_fmac_f32_e32 v63, v75, v75
	v_lshlrev_b32_e32 v73, 16, v23
	v_fmac_f32_e32 v63, v73, v73
	v_and_b32_e32 v22, 0xffff0000, v23
	v_fmac_f32_e32 v63, v22, v22
	v_lshlrev_b32_e32 v21, 16, v4
	v_fmac_f32_e32 v63, v21, v21
	v_and_b32_e32 v20, 0xffff0000, v4
	v_fmac_f32_e32 v63, v20, v20
	v_lshlrev_b32_e32 v144, 16, v5
	v_fmac_f32_e32 v63, v144, v144
	v_and_b32_e32 v143, 0xffff0000, v5
	v_fmac_f32_e32 v63, v143, v143
	v_lshlrev_b32_e32 v142, 16, v6
	v_fmac_f32_e32 v63, v142, v142
	v_and_b32_e32 v141, 0xffff0000, v6
	v_fmac_f32_e32 v63, v141, v141
	v_lshlrev_b32_e32 v140, 16, v7
	v_fmac_f32_e32 v63, v140, v140
	v_and_b32_e32 v139, 0xffff0000, v7
	v_fmac_f32_e32 v63, v139, v139
	v_lshlrev_b32_e32 v138, 16, v12
	v_fmac_f32_e32 v63, v138, v138
	v_and_b32_e32 v137, 0xffff0000, v12
	v_fmac_f32_e32 v63, v137, v137
	v_lshlrev_b32_e32 v136, 16, v13
	v_fmac_f32_e32 v63, v136, v136
	v_and_b32_e32 v127, 0xffff0000, v13
	v_fmac_f32_e32 v63, v127, v127
	v_lshlrev_b32_e32 v126, 16, v14
	v_fmac_f32_e32 v63, v126, v126
	v_and_b32_e32 v125, 0xffff0000, v14
	v_fmac_f32_e32 v63, v125, v125
	v_lshlrev_b32_e32 v124, 16, v15
	v_fmac_f32_e32 v63, v124, v124
	v_and_b32_e32 v123, 0xffff0000, v15
	v_fmac_f32_e32 v63, v123, v123
; DI float bf2f(unsigned short h) { return __uint_as_float((unsigned)h << 16); }
; DI unsigned cvtpk(float lo, float hi) { unsigned r; asm volatile("v_cvt_pk_bf16_f32 %0, %1, %2" : "=v"(r) : "v"(lo), "v"(hi)); return r; }
; DI float swap_sum(float v) { auto rr = __builtin_amdgcn_permlane32_swap(__float_as_uint(v), __float_as_uint(v), false, false); return __uint_as_float(rr[0]) + __uint_as_float(rr[1]); }
; template <int DQK, int MODE, int LDQ, int LDK, int LDV> ...
;     ...
;       if constexpr (MODE == 0) {
;           float ss = 0.f;
; #pragma unroll
;           for (int d0 = 0; d0 < ND0; ++d0)
; #pragma unroll
;               for (int j = 0; j < 8; ++j) { const float f = bf2f((unsigned short)qr[d0][j]); ss += f * f; }
;           ss = swap_sum(ss);
;           const float rstd = rsqrtf(ss * (1.f / DQK) + EPS) * C;
; #pragma unroll
;           for (int d0 = 0; d0 < ND0; ++d0) { const float* g = gq + d0 * 16 + hi * 8;
;               { float f[8]; _Pragma("unroll") for (int j = 0; j < 8; ++j) f[j] = bf2f((unsigned short)qr[d0][j]) * rstd * g[j];
;                 u32x4 w = {cvtpk(f[0], f[1]), cvtpk(f[2], f[3]), cvtpk(f[4], f[5]), cvtpk(f[6], f[7])}; qr[d0] = __builtin_bit_cast(bf16x8, w); asm volatile("" ::: "memory"); } }
	v_lshlrev_b32_e32 v122, 16, v24
	v_fmac_f32_e32 v63, v122, v122
	v_and_b32_e32 v121, 0xffff0000, v24
	v_fmac_f32_e32 v63, v121, v121
	v_lshlrev_b32_e32 v120, 16, v25
	v_fmac_f32_e32 v63, v120, v120
	v_and_b32_e32 v25, 0xffff0000, v25
	v_fmac_f32_e32 v63, v25, v25
	v_lshlrev_b32_e32 v24, 16, v26
	v_fmac_f32_e32 v63, v24, v24
	v_and_b32_e32 v23, 0xffff0000, v26
	v_fmac_f32_e32 v63, v23, v23
	v_lshlrev_b32_e32 v15, 16, v27
	v_fmac_f32_e32 v63, v15, v15
	v_and_b32_e32 v14, 0xffff0000, v27
	v_fmac_f32_e32 v63, v14, v14
	v_lshlrev_b32_e32 v12, 16, v8
	v_fmac_f32_e32 v63, v12, v12
	v_and_b32_e32 v13, 0xffff0000, v8
	v_and_b32_e32 v5, 0xffff0000, v9
	v_lshlrev_b32_e32 v4, 16, v9
	v_fmac_f32_e32 v63, v13, v13
	v_pk_mul_f32 v[6:7], v[4:5], v[4:5]
	global_load_lds_dwordx4 v[34:35], off
	v_add_f32_e32 v6, v6, v63
	v_add_f32_e32 v26, v7, v6
	v_and_b32_e32 v7, 0xffff0000, v10
	v_lshlrev_b32_e32 v6, 16, v10
	v_pk_mul_f32 v[8:9], v[6:7], v[6:7]
	s_nop 0
	v_add_f32_e32 v8, v8, v26
	v_add_f32_e32 v26, v9, v8
	v_and_b32_e32 v9, 0xffff0000, v11
	v_lshlrev_b32_e32 v8, 16, v11
	v_pk_mul_f32 v[10:11], v[8:9], v[8:9]
	s_nop 0
	v_add_f32_e32 v10, v10, v26
	v_add_f32_e32 v10, v11, v10
	v_mov_b32_e32 v11, v10
	s_nop 1
	v_permlane32_swap_b32_e32 v10, v11
	v_add_f32_e32 v10, v10, v11
	v_fmamk_f32 v10, v10, 0x3baaaaab, v160
	v_mul_f32_e32 v11, 0x4b800000, v10
	v_cmp_gt_f32_e32 vcc, s67, v10
	s_nop 1
	v_cndmask_b32_e32 v10, v10, v11, vcc
	v_rsq_f32_e32 v10, v10
	s_nop 0
	v_mul_f32_e32 v11, 0x45800000, v10
	v_cndmask_b32_e32 v10, v10, v11, vcc
	v_mul_f32_e32 v10, 0x3dd53b94, v10
	v_mul_f32_e32 v11, v10, v62
	s_waitcnt vmcnt(0)
	v_mul_f32_e32 v11, v16, v11
	v_mul_f32_e32 v16, v10, v44
	v_mul_f32_e32 v16, v17, v16
	v_mul_f32_e32 v17, v10, v45
	v_mul_f32_e32 v17, v18, v17
	v_mul_f32_e32 v18, v10, v49
	v_mul_f32_e32 v18, v19, v18
	v_mul_f32_e32 v19, v10, v50
	v_mul_f32_e32 v0, v0, v19
	v_mul_f32_e32 v19, v10, v51
	v_mul_f32_e32 v1, v1, v19
	v_mul_f32_e32 v19, v10, v52
	v_mul_f32_e32 v2, v2, v19
	v_mul_f32_e32 v19, v10, v53
	v_mul_f32_e32 v3, v3, v19
	v_cvt_pk_bf16_f32 v80, v11, v16
	v_cvt_pk_bf16_f32 v81, v17, v18
	v_cvt_pk_bf16_f32 v82, v0, v1
	v_cvt_pk_bf16_f32 v83, v2, v3
	global_load_dwordx4 v[0:3], v38, s[26:27] offset:64
	global_load_dwordx4 v[16:19], v38, s[26:27] offset:80
	v_mul_f32_e32 v11, v10, v48
	v_mul_f32_e32 v26, v10, v64
	v_mul_f32_e32 v27, v10, v97
	v_mul_f32_e32 v34, v10, v96
	v_mul_f32_e32 v35, v10, v95
	v_mul_f32_e32 v44, v10, v94
	v_mul_f32_e32 v45, v10, v93
	v_mul_f32_e32 v22, v10, v22
	v_mul_f32_e32 v20, v10, v20
	v_mul_f32_e32 v24, v10, v24
	v_mul_f32_e32 v23, v10, v23
	v_mul_f32_e32 v15, v10, v15
	v_mul_f32_e32 v14, v10, v14
	v_mul_f32_e32 v4, v10, v4
	v_mul_f32_e32 v5, v10, v5
	v_mul_f32_e32 v6, v10, v6
	v_mul_f32_e32 v7, v10, v7
	v_mul_f32_e32 v8, v10, v8
	v_mul_f32_e32 v9, v10, v9
	s_waitcnt vmcnt(0)
	v_mul_f32_e32 v0, v11, v0
	v_mul_f32_e32 v11, v10, v46
	v_mul_f32_e32 v1, v11, v1
	v_mul_f32_e32 v11, v10, v47
	v_mul_f32_e32 v2, v11, v2
	v_mul_f32_e32 v11, v10, v57
	v_mul_f32_e32 v3, v11, v3
	v_mul_f32_e32 v11, v10, v58
	v_mul_f32_e32 v11, v11, v16
	v_mul_f32_e32 v16, v10, v59
	v_mul_f32_e32 v16, v16, v17
	v_mul_f32_e32 v17, v10, v60
	v_mul_f32_e32 v17, v17, v18
	v_mul_f32_e32 v18, v10, v61
	v_mul_f32_e32 v18, v18, v19
	v_cvt_pk_bf16_f32 v84, v0, v1
	v_cvt_pk_bf16_f32 v85, v2, v3
	v_cvt_pk_bf16_f32 v86, v11, v16
	v_cvt_pk_bf16_f32 v87, v17, v18
	global_load_dwordx4 v[0:3], v38, s[26:27] offset:128
	global_load_dwordx4 v[16:19], v38, s[26:27] offset:144
	v_mul_f32_e32 v11, v10, v56
	v_mul_f32_e32 v46, v10, v92
	s_waitcnt vmcnt(0)
	v_mul_f32_e32 v0, v11, v0
	v_mul_f32_e32 v11, v10, v54
	v_mul_f32_e32 v1, v11, v1
	v_mul_f32_e32 v11, v10, v55
	v_mul_f32_e32 v2, v11, v2
	v_mul_f32_e32 v11, v10, v66
	v_mul_f32_e32 v3, v11, v3
	v_mul_f32_e32 v11, v10, v67
	v_mul_f32_e32 v11, v11, v16
	v_mul_f32_e32 v16, v10, v68
	v_mul_f32_e32 v16, v16, v17
	v_mul_f32_e32 v17, v10, v69
	v_mul_f32_e32 v17, v17, v18
	v_mul_f32_e32 v18, v10, v70
	v_mul_f32_e32 v18, v18, v19
	v_cvt_pk_bf16_f32 v88, v0, v1
	v_cvt_pk_bf16_f32 v89, v2, v3
	v_cvt_pk_bf16_f32 v90, v11, v16
	v_cvt_pk_bf16_f32 v91, v17, v18
	global_load_dwordx4 v[0:3], v38, s[26:27] offset:192
	global_load_dwordx4 v[16:19], v38, s[26:27] offset:208
	v_mul_f32_e32 v11, v10, v65
	s_waitcnt vmcnt(0)
	v_mul_f32_e32 v0, v11, v0
	v_mul_f32_e32 v1, v26, v1
	v_mul_f32_e32 v2, v27, v2
	v_mul_f32_e32 v3, v34, v3
	v_mul_f32_e32 v11, v35, v16
	v_mul_f32_e32 v16, v44, v17
	v_mul_f32_e32 v17, v45, v18
	v_mul_f32_e32 v18, v46, v19
	v_cvt_pk_bf16_f32 v92, v0, v1
	v_cvt_pk_bf16_f32 v93, v2, v3
	v_cvt_pk_bf16_f32 v94, v11, v16
	v_cvt_pk_bf16_f32 v95, v17, v18
	global_load_dwordx4 v[0:3], v38, s[26:27] offset:256
	global_load_dwordx4 v[16:19], v38, s[26:27] offset:272
	v_mul_f32_e32 v11, v10, v74
	v_mul_f32_e32 v26, v10, v72
	v_mul_f32_e32 v27, v10, v71
	v_mul_f32_e32 v34, v10, v113
	v_mul_f32_e32 v35, v10, v103
	v_mul_f32_e32 v44, v10, v102
	v_mul_f32_e32 v45, v10, v99
	v_mul_f32_e32 v46, v10, v98
	s_waitcnt vmcnt(0)
	v_mul_f32_e32 v0, v11, v0
	v_mul_f32_e32 v1, v26, v1
	v_mul_f32_e32 v2, v27, v2
	v_mul_f32_e32 v3, v34, v3
	v_mul_f32_e32 v11, v35, v16
	v_mul_f32_e32 v16, v44, v17
	v_mul_f32_e32 v17, v45, v18
	v_mul_f32_e32 v18, v46, v19
	v_cvt_pk_bf16_f32 v96, v0, v1
	v_cvt_pk_bf16_f32 v97, v2, v3
	v_cvt_pk_bf16_f32 v98, v11, v16
	v_cvt_pk_bf16_f32 v99, v17, v18
	global_load_dwordx4 v[0:3], v38, s[26:27] offset:320
	global_load_dwordx4 v[16:19], v38, s[26:27] offset:336
	v_mul_f32_e32 v11, v10, v101
	v_mul_f32_e32 v26, v10, v100
	v_mul_f32_e32 v27, v10, v119
	v_mul_f32_e32 v34, v10, v118
	v_mul_f32_e32 v35, v10, v117
	v_mul_f32_e32 v44, v10, v116
	v_mul_f32_e32 v45, v10, v115
	v_mul_f32_e32 v46, v10, v114
	s_waitcnt vmcnt(0)
; DI float bf2f(unsigned short h) { return __uint_as_float((unsigned)h << 16); }
; DI unsigned cvtpk(float lo, float hi) { unsigned r; asm volatile("v_cvt_pk_bf16_f32 %0, %1, %2" : "=v"(r) : "v"(lo), "v"(hi)); return r; }
; DI int v_rd_base(int lane) { return ((lane & 3) << 3) | (((lane >> 2) & 3) << 6) | (((lane >> 4) & 1) << 5) | (((lane >> 5) & 1) << 8); }
; #define ATT_BIAS(P, t, half) do { if constexpr (MODE != 0) { if ((t) >= tL && (t) < tR) { const LAS float* bp_ = bt + ((t) * 64 + (half) * 32 - qpos + 224 + 4 * hi);     \
;     _Pragma("unroll") for (int r = 0; r < 16; ++r) P[r] += bp_[(r & 3) + 8 * (r >> 2)]; } } } while (0)
; #define ATT_TOP(N) do { asm volatile("s_waitcnt vmcnt(%0)" :: "n"(N) : "memory"); __builtin_amdgcn_s_barrier(); asm volatile("" ::: "memory"); } while (0)
; #define ATT_LGKM0() do { SBAR(); asm volatile("s_waitcnt lgkmcnt(0)" ::: "memory"); SBAR(); } while (0)
; template <int DQK, int MODE, int LDQ, int LDK, int LDV> ...
;     ...
;           for (int d0 = 0; d0 < ND0; ++d0) { const float* g = gq + d0 * 16 + hi * 8;
;               { float f[8]; _Pragma("unroll") for (int j = 0; j < 8; ++j) f[j] = bf2f((unsigned short)qr[d0][j]) * rstd * g[j];
;                 u32x4 w = {cvtpk(f[0], f[1]), cvtpk(f[2], f[3]), cvtpk(f[4], f[5]), cvtpk(f[6], f[7])}; qr[d0] = __builtin_bit_cast(bf16x8, w); asm volatile("" ::: "memory"); } }
;       } }
;     const int qlo = q0 + wid * 32, qpos = qlo + r32;
;     const int tL = MODE == 0 ? 0 : (qlo >= 191 ? (qlo - 127) >> 6 : 0), tR = MODE == 0 ? NT : min(NT, (qlo + 222) >> 6);
;     float fL = 1.f, fR = 1.f; if constexpr (MODE != 0) { fL = __builtin_amdgcn_exp2f(bt[0]); fR = __builtin_amdgcn_exp2f(-bt[448]); }
;     ...
;     const int vbase = (int)(unsigned)(size_t)lds + V_OFF + v_rd_base(lane);
;     ...
;     constexpr int NDA = ND0 > 6 ? 6 : ND0;
;     ...
;     f32x16 pA, pB; bf16x8 pa0, pa1;
;     int v0 = 0, v1 = 1, v2 = 2;
;     ATT_TOP(NKP + 2);
;     { bf16x8 kf[NDA]; k_reads<DQK, 0, NDA>(kf, lds, 0, r32, hi); ATT_LGKM0(); qk_mma<0, NDA>(pA, kf, qr);
;       if constexpr (ND0 > NDA) { bf16x8 kg[ND0 - NDA]; k_reads<DQK, NDA, ND0>(kg, lds, 0, r32, hi); ATT_LGKM0(); qk_mma<NDA, ND0>(pA, kg, qr); }
;       ATT_BIAS(pA, 0, 0); }
;     if (wid >= 4) __builtin_amdgcn_s_setprio(1);
	v_mul_f32_e32 v0, v11, v0
	v_mul_f32_e32 v1, v26, v1
	v_mul_f32_e32 v2, v27, v2
	v_mul_f32_e32 v3, v34, v3
	v_mul_f32_e32 v11, v35, v16
	v_mul_f32_e32 v16, v44, v17
	v_mul_f32_e32 v17, v45, v18
	v_mul_f32_e32 v18, v46, v19
	v_cvt_pk_bf16_f32 v100, v0, v1
	v_cvt_pk_bf16_f32 v101, v2, v3
	v_cvt_pk_bf16_f32 v102, v11, v16
	v_cvt_pk_bf16_f32 v103, v17, v18
	global_load_dwordx4 v[0:3], v38, s[26:27] offset:384
	global_load_dwordx4 v[16:19], v38, s[26:27] offset:400
	v_mul_f32_e32 v11, v10, v112
	v_mul_f32_e32 v26, v10, v111
	v_mul_f32_e32 v27, v10, v110
	v_mul_f32_e32 v34, v10, v109
	v_mul_f32_e32 v35, v10, v107
	v_mul_f32_e32 v44, v10, v106
	v_mul_f32_e32 v45, v10, v105
	v_mul_f32_e32 v46, v10, v104
	s_waitcnt vmcnt(0)
	v_mul_f32_e32 v0, v11, v0
	v_mul_f32_e32 v1, v26, v1
	v_mul_f32_e32 v2, v27, v2
	v_mul_f32_e32 v3, v34, v3
	v_mul_f32_e32 v11, v35, v16
	v_mul_f32_e32 v16, v44, v17
	v_mul_f32_e32 v17, v45, v18
	v_mul_f32_e32 v18, v46, v19
	v_cvt_pk_bf16_f32 v104, v0, v1
	v_cvt_pk_bf16_f32 v105, v2, v3
	v_cvt_pk_bf16_f32 v106, v11, v16
	v_cvt_pk_bf16_f32 v107, v17, v18
	global_load_dwordx4 v[0:3], v38, s[26:27] offset:448
	global_load_dwordx4 v[16:19], v38, s[26:27] offset:464
	v_mul_f32_e32 v11, v10, v108
	v_mul_f32_e32 v26, v10, v79
	v_mul_f32_e32 v27, v10, v78
	v_mul_f32_e32 v34, v10, v77
	v_mul_f32_e32 v35, v10, v76
	v_mul_f32_e32 v44, v10, v75
	v_mul_f32_e32 v45, v10, v73
	s_waitcnt vmcnt(0)
	v_mul_f32_e32 v0, v11, v0
	v_mul_f32_e32 v1, v26, v1
	v_mul_f32_e32 v2, v27, v2
	v_mul_f32_e32 v3, v34, v3
	v_mul_f32_e32 v11, v35, v16
	v_mul_f32_e32 v16, v44, v17
	v_mul_f32_e32 v17, v45, v18
	v_mul_f32_e32 v18, v22, v19
	v_cvt_pk_bf16_f32 v108, v0, v1
	v_cvt_pk_bf16_f32 v109, v2, v3
	v_cvt_pk_bf16_f32 v110, v11, v16
	v_cvt_pk_bf16_f32 v111, v17, v18
	global_load_dwordx4 v[0:3], v38, s[26:27] offset:512
	global_load_dwordx4 v[16:19], v38, s[26:27] offset:528
	v_mul_f32_e32 v11, v10, v21
	v_mul_f32_e32 v21, v10, v144
	v_mul_f32_e32 v22, v10, v143
	v_mul_f32_e32 v26, v10, v142
	v_mul_f32_e32 v27, v10, v141
	v_mul_f32_e32 v34, v10, v140
	v_mul_f32_e32 v35, v10, v139
	s_waitcnt vmcnt(0)
	v_mul_f32_e32 v0, v11, v0
	v_mul_f32_e32 v1, v20, v1
	v_mul_f32_e32 v2, v21, v2
	v_mul_f32_e32 v3, v22, v3
	v_mul_f32_e32 v11, v26, v16
	v_mul_f32_e32 v16, v27, v17
	v_mul_f32_e32 v17, v34, v18
	v_mul_f32_e32 v18, v35, v19
	v_cvt_pk_bf16_f32 v112, v0, v1
	v_cvt_pk_bf16_f32 v113, v2, v3
	v_cvt_pk_bf16_f32 v114, v11, v16
	v_cvt_pk_bf16_f32 v115, v17, v18
	global_load_dwordx4 v[0:3], v38, s[26:27] offset:576
	global_load_dwordx4 v[16:19], v38, s[26:27] offset:592
	v_mul_f32_e32 v11, v10, v138
	v_mul_f32_e32 v20, v10, v137
	v_mul_f32_e32 v21, v10, v136
	v_mul_f32_e32 v22, v10, v127
	v_mul_f32_e32 v26, v10, v126
	v_mul_f32_e32 v27, v10, v125
	v_mul_f32_e32 v34, v10, v124
	v_mul_f32_e32 v35, v10, v123
	s_waitcnt vmcnt(0)
	v_mul_f32_e32 v0, v11, v0
	v_mul_f32_e32 v1, v20, v1
	v_mul_f32_e32 v2, v21, v2
	v_mul_f32_e32 v3, v22, v3
	v_mul_f32_e32 v11, v26, v16
	v_mul_f32_e32 v16, v27, v17
	v_mul_f32_e32 v17, v34, v18
	v_mul_f32_e32 v18, v35, v19
	v_cvt_pk_bf16_f32 v116, v0, v1
	v_cvt_pk_bf16_f32 v117, v2, v3
	v_cvt_pk_bf16_f32 v118, v11, v16
	v_cvt_pk_bf16_f32 v119, v17, v18
	global_load_dwordx4 v[0:3], v38, s[26:27] offset:640
	global_load_dwordx4 v[16:19], v38, s[26:27] offset:656
	v_mul_f32_e32 v11, v10, v122
	v_mul_f32_e32 v20, v10, v121
	v_mul_f32_e32 v21, v10, v120
	v_mul_f32_e32 v22, v10, v25
	s_waitcnt vmcnt(0)
	v_mul_f32_e32 v0, v11, v0
	v_mul_f32_e32 v1, v20, v1
	v_mul_f32_e32 v2, v21, v2
	v_mul_f32_e32 v3, v22, v3
	v_mul_f32_e32 v11, v24, v16
	v_mul_f32_e32 v16, v23, v17
	v_mul_f32_e32 v15, v15, v18
	v_mul_f32_e32 v14, v14, v19
	v_cvt_pk_bf16_f32 v120, v0, v1
	v_cvt_pk_bf16_f32 v121, v2, v3
	v_cvt_pk_bf16_f32 v122, v11, v16
	v_cvt_pk_bf16_f32 v123, v15, v14
	global_load_dwordx4 v[0:3], v38, s[26:27] offset:704
	global_load_dwordx4 v[14:17], v38, s[26:27] offset:720
	v_and_b32_e32 v24, 0x70, v42
	v_mul_f32_e32 v11, v10, v12
	v_mul_f32_e32 v12, v10, v13
	v_bitop3_b32 v151, v43, v24, 16 bitop3:0x6c
	v_bitop3_b32 v149, v130, v24, 32 bitop3:0x36
	v_bitop3_b32 v148, v130, v24, 64 bitop3:0x36
	v_bitop3_b32 v147, v130, v24, s65 bitop3:0x36
	v_bitop3_b32 v146, v130, v24, s1 bitop3:0x36
	v_bitop3_b32 v150, v130, v24, s6 bitop3:0x36
	v_add_u32_e32 v161, v158, v151
	v_add_u32_e32 v162, v158, v149
	v_add_u32_e32 v163, v158, v148
	v_add_u32_e32 v164, v158, v147
	v_add_u32_e32 v165, v158, v146
	v_add_u32_e32 v166, v158, v150
	s_waitcnt vmcnt(0)
	v_mul_f32_e32 v0, v11, v0
	v_mul_f32_e32 v1, v12, v1
	v_mul_f32_e32 v2, v4, v2
	v_mul_f32_e32 v3, v5, v3
	v_mul_f32_e32 v4, v6, v14
	v_mul_f32_e32 v5, v7, v15
	v_mul_f32_e32 v6, v8, v16
	v_mul_f32_e32 v7, v9, v17
	v_cvt_pk_bf16_f32 v124, v0, v1
	v_cvt_pk_bf16_f32 v125, v2, v3
	v_cvt_pk_bf16_f32 v126, v4, v5
	v_cvt_pk_bf16_f32 v127, v6, v7
	s_waitcnt vmcnt(5)
	s_barrier
	ds_read_b128 v[0:3], v161
	ds_read_b128 v[4:7], v162
	ds_read_b128 v[8:11], v163
	ds_read_b128 v[12:15], v164
	ds_read_b128 v[16:19], v165
	ds_read_b128 v[20:23], v166
	s_waitcnt lgkmcnt(0)
	s_waitcnt lgkmcnt(0)
	v_mfma_f32_32x32x16_bf16 v[64:79], v[0:3], v[80:83], 0
	s_movk_i32 s0, 0xc0
	v_bitop3_b32 v152, v130, v24, s0 bitop3:0x36
	s_movk_i32 s0, 0x100
	v_bitop3_b32 v154, v130, v24, s0 bitop3:0x36
	s_movk_i32 s0, 0x120
	v_bitop3_b32 v155, v130, v24, s0 bitop3:0x36
	s_movk_i32 s0, 0x140
	v_mfma_f32_32x32x16_bf16 v[64:79], v[4:7], v[84:87], v[64:79]
	v_bitop3_b32 v156, v130, v24, s0 bitop3:0x36
	s_movk_i32 s0, 0x160
	v_add_u32_e32 v167, v158, v152
	v_bitop3_b32 v153, v130, v24, s72 bitop3:0x36
	v_add_u32_e32 v169, v158, v154
	v_add_u32_e32 v171, v158, v156
	v_bitop3_b32 v157, v130, v24, s0 bitop3:0x36
	v_mfma_f32_32x32x16_bf16 v[64:79], v[8:11], v[88:91], v[64:79]
	v_add_u32_e32 v168, v158, v153
	ds_read_b128 v[0:3], v167
	ds_read_b128 v[4:7], v168
	v_add_u32_e32 v170, v158, v155
	v_add_u32_e32 v172, v158, v157
	v_mfma_f32_32x32x16_bf16 v[64:79], v[12:15], v[92:95], v[64:79]
	ds_read_b128 v[8:11], v169
	ds_read_b128 v[12:15], v170
	v_mfma_f32_32x32x16_bf16 v[64:79], v[16:19], v[96:99], v[64:79]
	ds_read_b128 v[16:19], v171
	ds_read_b128 v[24:27], v172
	v_mfma_f32_32x32x16_bf16 v[64:79], v[20:23], v[100:103], v[64:79]
	s_waitcnt lgkmcnt(0)
	s_waitcnt lgkmcnt(5)
	v_mfma_f32_32x32x16_bf16 v[64:79], v[0:3], v[104:107], v[64:79]
	s_cmp_lt_i32 s56, 4
	s_waitcnt lgkmcnt(4)
	v_mfma_f32_32x32x16_bf16 v[64:79], v[4:7], v[108:111], v[64:79]
	s_waitcnt lgkmcnt(3)
	v_mfma_f32_32x32x16_bf16 v[64:79], v[8:11], v[112:115], v[64:79]
	s_waitcnt lgkmcnt(2)
	v_mfma_f32_32x32x16_bf16 v[64:79], v[12:15], v[116:119], v[64:79]
	s_waitcnt lgkmcnt(1)
	v_mfma_f32_32x32x16_bf16 v[64:79], v[16:19], v[120:123], v[64:79]
	s_waitcnt lgkmcnt(0)
	v_mfma_f32_32x32x16_bf16 v[64:79], v[24:27], v[124:127], v[64:79]
	s_cbranch_scc1 .LBB0_1981

; #define SBAR() __builtin_amdgcn_sched_barrier(0)
; #define ATT_DMA_K(t) do { const bf16_t* kg_ = Kh + (size_t)(t) * 64 * LDK; LAS unsigned char* sb_ = lds + ((t) & 3) * KBUF; \
;     _Pragma("unroll") for (int i_ = 0; i_ < NKP; ++i_) __builtin_amdgcn_global_load_lds((const unsigned*)(kg_ + kgo[i_]), (LAS unsigned*)(sb_ + (wid + 8 * i_) * 1024), 16, 0, 0); } while (0)
; #define ATT_DMA_V(t, vs) do { const bf16_t* vg_ = Vh + (size_t)(t) * 64 * LDV; LAS unsigned char* sb_ = lds + V_OFF + (vs) * SHM_V; \
;     _Pragma("unroll") for (int i_ = 0; i_ < 2; ++i_) __builtin_amdgcn_global_load_lds((const unsigned*)(vg_ + vgo[i_]), (LAS unsigned*)(sb_ + (2 * wid + i_) * 1024), 16, 0, 0); } while (0)
; #define ATT_SEG(t) do { if constexpr (MODE != 0) { if (((t) == tL && tL > 0) || (t) == tR) { const float f_ = (t) == tR ? fR : fL; l_reg *= f_; \
;     _Pragma("unroll") for (int d = 0; d < 4; ++d) _Pragma("unroll") for (int r = 0; r < 16; ++r) o[d][r] *= f_; } } } while (0)
; #define ATT_TOP(N) do { asm volatile("s_waitcnt vmcnt(%0)" :: "n"(N) : "memory"); __builtin_amdgcn_s_barrier(); asm volatile("" ::: "memory"); } while (0)
; DI void expsum(f32x16& p, float& l_reg, bf16x8& pa0, bf16x8& pa1) {
; #pragma unroll
;     for (int r = 0; r < 16; ++r) p[r] = __builtin_amdgcn_exp2f(p[r]);
;     float ps = 0.f;
; #pragma unroll
;     for (int r = 0; r < 16; ++r) ps += p[r];
;     l_reg += ps; asm volatile("" : "+v"(l_reg));
;     ...
;     ATT_PK4(p, 0, pa0); ATT_PK4(p, 8, pa1);
;     ...
; }
; template <int DQK, int MODE, int LDQ, int LDK, int LDV> ...
;     ...
;     f32x16 pA, pB; bf16x8 pa0, pa1;
;     int v0 = 0, v1 = 1, v2 = 2;
;     ATT_TOP(NKP + 2);
;     { bf16x8 kf[NDA]; k_reads<DQK, 0, NDA>(kf, lds, 0, r32, hi); ATT_LGKM0(); qk_mma<0, NDA>(pA, kf, qr);
;       if constexpr (ND0 > NDA) { bf16x8 kg[ND0 - NDA]; k_reads<DQK, NDA, ND0>(kg, lds, 0, r32, hi); ATT_LGKM0(); qk_mma<NDA, ND0>(pA, kg, qr); }
;       ATT_BIAS(pA, 0, 0); }
;     if (wid >= 4) __builtin_amdgcn_s_setprio(1);
;     for (int j = 0; j < NT; ++j) {
;         if (j + 2 < NT) ATT_TOP(NKP + 2); else ATT_TOP(0);
;         if (j + 3 < NT) ATT_DMA_K(j + 3);
;         if (j + 2 < NT) ATT_DMA_V(j + 2, v2);
;         ATT_SEG(j); SBAR();
;         ATT_STEP(pA, pB, 0, v0, true, 1, j);
;         ATT_STEP(pB, pA, 1, v0, (j + 1 < NT), 0, j + 1);
.Lhw_mla_b_n1982:
	s_and_b32 s1, s43, 3
	s_mulk_i32 s1, 0x6000
	s_add_i32 s1, s49, s1
	s_setprio 0
	s_mov_b32 m0, s1
	s_mov_b32 s0, s5
	s_mov_b32 s5, s44
	s_mov_b32 s44, s4
	s_lshl_b32 s4, s4, 14
	global_load_lds_dwordx4 v136, s[34:35]
	s_add_i32 m0, s1, 0x2000
	s_add_i32 s4, s52, s4
	global_load_lds_dwordx4 v138, s[34:35]
	s_add_i32 m0, s1, 0x4000
	s_add_i32 s6, s4, 0x400
	global_load_lds_dwordx4 v140, s[34:35]
	s_mov_b32 m0, s4
	s_add_i32 s1, s43, -3
	global_load_lds_dwordx4 v144, s[34:35]
	s_mov_b32 m0, s6
	s_nop 0
	global_load_lds_dwordx4 v142, s[34:35]
	s_and_b32 s1, s1, 3
	s_mulk_i32 s1, 0x6000
	v_add_u32_e32 v246, s1, v158
	v_add_u32_e32 v250, v246, v151
	v_add_u32_e32 v251, v246, v149
	v_add_u32_e32 v252, v246, v148
	v_add_u32_e32 v253, v246, v147
	s_lshl_b32 s1, s0, 14
	ds_read_b128 v[190:193], v250 offset:12416
	ds_read_b128 v[194:197], v251 offset:12416
	ds_read_b128 v[174:177], v250 offset:12288
	ds_read_b128 v[178:181], v251 offset:12288
	ds_read_b128 v[182:185], v252 offset:12288
	ds_read_b128 v[186:189], v253 offset:12288
	v_add_u32_e32 v254, s1, v130
	ds_read_b64_tr_b16 v[198:199], v254 offset:0
	ds_read_b64_tr_b16 v[200:201], v254 offset:0x800
	ds_read_b64_tr_b16 v[202:203], v254 offset:0x1000
	ds_read_b64_tr_b16 v[204:205], v254 offset:0x1800
	ds_read_b64_tr_b16 v[206:207], v254 offset:0x200
	ds_read_b64_tr_b16 v[208:209], v254 offset:0xa00
	ds_read_b64_tr_b16 v[210:211], v254 offset:0x1200
	ds_read_b64_tr_b16 v[212:213], v254 offset:0x1a00
	ds_read_b64_tr_b16 v[214:215], v254 offset:0x400
	ds_read_b64_tr_b16 v[216:217], v254 offset:0xc00
	ds_read_b64_tr_b16 v[218:219], v254 offset:0x1400
	ds_read_b64_tr_b16 v[220:221], v254 offset:0x1c00
	ds_read_b64_tr_b16 v[222:223], v254 offset:0x600
	ds_read_b64_tr_b16 v[224:225], v254 offset:0xe00
	ds_read_b64_tr_b16 v[226:227], v254 offset:0x1600
	ds_read_b64_tr_b16 v[228:229], v254 offset:0x1e00
	s_setprio 2
	v_exp_f32_e32 v64, v64
	v_exp_f32_e32 v65, v65
	v_exp_f32_e32 v66, v66
	v_exp_f32_e32 v67, v67
	v_exp_f32_e32 v68, v68
	v_exp_f32_e32 v69, v69
	v_add_f32_e32 v230, v65, v64
	v_exp_f32_e32 v70, v70
	v_add_f32_e32 v230, v66, v230
	v_exp_f32_e32 v71, v71
	v_add_f32_e32 v230, v67, v230
	v_exp_f32_e32 v72, v72
	v_add_f32_e32 v230, v68, v230
	v_exp_f32_e32 v73, v73
	v_add_f32_e32 v230, v69, v230
	v_exp_f32_e32 v74, v74
	v_add_f32_e32 v230, v70, v230
	v_exp_f32_e32 v75, v75
	v_add_f32_e32 v230, v71, v230
	v_exp_f32_e32 v76, v76
	v_add_f32_e32 v230, v72, v230
	v_exp_f32_e32 v77, v77
	v_add_f32_e32 v230, v73, v230
	v_exp_f32_e32 v78, v78
	v_add_f32_e32 v230, v74, v230
	v_exp_f32_e32 v79, v79
	v_add_f32_e32 v230, v75, v230
	v_add_f32_e32 v230, v76, v230
	v_add_f32_e32 v230, v77, v230
	v_add_f32_e32 v230, v78, v230
	v_add_f32_e32 v230, v79, v230
	v_add_f32_e32 v173, v173, v230
	v_cvt_pk_bf16_f32 v64, v64, v65
	v_cvt_pk_bf16_f32 v65, v66, v67
	v_cvt_pk_bf16_f32 v66, v68, v69
	v_cvt_pk_bf16_f32 v67, v70, v71
	v_cvt_pk_bf16_f32 v68, v72, v73
	v_cvt_pk_bf16_f32 v69, v74, v75
	v_cvt_pk_bf16_f32 v70, v76, v77
	v_cvt_pk_bf16_f32 v71, v78, v79
	s_waitcnt lgkmcnt(0)
	ds_read_b128 v[230:233], v252 offset:12416
	ds_read_b128 v[234:237], v253 offset:12416
	ds_read_b128 v[238:241], v250 offset:12544
	ds_read_b128 v[242:245], v251 offset:12544
	ds_read_b128 v[246:249], v252 offset:12544
	ds_read_b128 v[250:253], v253 offset:12544
	s_setprio 1
	v_mfma_f32_32x32x16_bf16 v[48:63], v[64:67], v[198:201], v[48:63]
	v_mfma_f32_32x32x16_bf16 v[32:47], v[64:67], v[206:209], v[32:47]
	v_mfma_f32_32x32x16_bf16 v[16:31], v[64:67], v[214:217], v[16:31]
	v_mfma_f32_32x32x16_bf16 v[0:15], v[64:67], v[222:225], v[0:15]
	v_mfma_f32_32x32x16_bf16 v[48:63], v[68:71], v[202:205], v[48:63]
	v_mfma_f32_32x32x16_bf16 v[32:47], v[68:71], v[210:213], v[32:47]
	v_mfma_f32_32x32x16_bf16 v[16:31], v[68:71], v[218:221], v[16:31]
	v_mfma_f32_32x32x16_bf16 v[0:15], v[68:71], v[226:229], v[0:15]
	s_waitcnt lgkmcnt(0)
	v_mfma_f32_32x32x16_bf16 v[64:79], v[174:177], v[80:83], 0
	v_mfma_f32_32x32x16_bf16 v[64:79], v[178:181], v[84:87], v[64:79]
	v_mfma_f32_32x32x16_bf16 v[64:79], v[182:185], v[88:91], v[64:79]
	v_mfma_f32_32x32x16_bf16 v[64:79], v[186:189], v[92:95], v[64:79]
	v_mfma_f32_32x32x16_bf16 v[64:79], v[190:193], v[96:99], v[64:79]
	v_mfma_f32_32x32x16_bf16 v[64:79], v[194:197], v[100:103], v[64:79]
	v_mfma_f32_32x32x16_bf16 v[64:79], v[230:233], v[104:107], v[64:79]
	v_mfma_f32_32x32x16_bf16 v[64:79], v[234:237], v[108:111], v[64:79]
	v_mfma_f32_32x32x16_bf16 v[64:79], v[238:241], v[112:115], v[64:79]
	v_mfma_f32_32x32x16_bf16 v[64:79], v[242:245], v[116:119], v[64:79]
	v_mfma_f32_32x32x16_bf16 v[64:79], v[246:249], v[120:123], v[64:79]
	v_mfma_f32_32x32x16_bf16 v[64:79], v[250:253], v[124:127], v[64:79]
	s_setprio 0
	s_add_i32 s4, s43, -2
	s_and_b32 s4, s4, 3
	s_mulk_i32 s4, 0x6000
	v_add_u32_e32 v246, s4, v158
	v_add_u32_e32 v250, v246, v151
	v_add_u32_e32 v251, v246, v149
	v_add_u32_e32 v252, v246, v148
	v_add_u32_e32 v253, v246, v147
	ds_read_b128 v[190:193], v250 offset:128
	ds_read_b128 v[194:197], v251 offset:128
	ds_read_b128 v[174:177], v250
	ds_read_b128 v[178:181], v251
	ds_read_b128 v[182:185], v252
	ds_read_b128 v[186:189], v253
	ds_read_b64_tr_b16 v[198:199], v254 offset:0x2000
	ds_read_b64_tr_b16 v[200:201], v254 offset:0x2800
	ds_read_b64_tr_b16 v[202:203], v254 offset:0x3000
	ds_read_b64_tr_b16 v[204:205], v254 offset:0x3800
	ds_read_b64_tr_b16 v[206:207], v254 offset:0x2200
	ds_read_b64_tr_b16 v[208:209], v254 offset:0x2a00
	ds_read_b64_tr_b16 v[210:211], v254 offset:0x3200
	ds_read_b64_tr_b16 v[212:213], v254 offset:0x3a00
	ds_read_b64_tr_b16 v[214:215], v254 offset:0x2400
	ds_read_b64_tr_b16 v[216:217], v254 offset:0x2c00
; #define SBAR() __builtin_amdgcn_sched_barrier(0)
; #define ATT_DMA_K(t) do { const bf16_t* kg_ = Kh + (size_t)(t) * 64 * LDK; LAS unsigned char* sb_ = lds + ((t) & 3) * KBUF; \
;     _Pragma("unroll") for (int i_ = 0; i_ < NKP; ++i_) __builtin_amdgcn_global_load_lds((const unsigned*)(kg_ + kgo[i_]), (LAS unsigned*)(sb_ + (wid + 8 * i_) * 1024), 16, 0, 0); } while (0)
; #define ATT_DMA_V(t, vs) do { const bf16_t* vg_ = Vh + (size_t)(t) * 64 * LDV; LAS unsigned char* sb_ = lds + V_OFF + (vs) * SHM_V; \
;     _Pragma("unroll") for (int i_ = 0; i_ < 2; ++i_) __builtin_amdgcn_global_load_lds((const unsigned*)(vg_ + vgo[i_]), (LAS unsigned*)(sb_ + (2 * wid + i_) * 1024), 16, 0, 0); } while (0)
; #define ATT_SEG(t) do { if constexpr (MODE != 0) { if (((t) == tL && tL > 0) || (t) == tR) { const float f_ = (t) == tR ? fR : fL; l_reg *= f_; \
;     _Pragma("unroll") for (int d = 0; d < 4; ++d) _Pragma("unroll") for (int r = 0; r < 16; ++r) o[d][r] *= f_; } } } while (0)
; #define ATT_TOP(N) do { asm volatile("s_waitcnt vmcnt(%0)" :: "n"(N) : "memory"); __builtin_amdgcn_s_barrier(); asm volatile("" ::: "memory"); } while (0)
; DI void expsum(f32x16& p, float& l_reg, bf16x8& pa0, bf16x8& pa1) {
; #pragma unroll
;     for (int r = 0; r < 16; ++r) p[r] = __builtin_amdgcn_exp2f(p[r]);
;     float ps = 0.f;
; #pragma unroll
;     for (int r = 0; r < 16; ++r) ps += p[r];
;     l_reg += ps; asm volatile("" : "+v"(l_reg));
;     ...
;     ATT_PK4(p, 0, pa0); ATT_PK4(p, 8, pa1);
;     ...
; }
; template <int DQK, int MODE, int LDQ, int LDK, int LDV> ...
;     ...
;     f32x16 pA, pB; bf16x8 pa0, pa1;
;     int v0 = 0, v1 = 1, v2 = 2;
;     ATT_TOP(NKP + 2);
;     { bf16x8 kf[NDA]; k_reads<DQK, 0, NDA>(kf, lds, 0, r32, hi); ATT_LGKM0(); qk_mma<0, NDA>(pA, kf, qr);
;       if constexpr (ND0 > NDA) { bf16x8 kg[ND0 - NDA]; k_reads<DQK, NDA, ND0>(kg, lds, 0, r32, hi); ATT_LGKM0(); qk_mma<NDA, ND0>(pA, kg, qr); }
;       ATT_BIAS(pA, 0, 0); }
;     if (wid >= 4) __builtin_amdgcn_s_setprio(1);
;     for (int j = 0; j < NT; ++j) {
;         if (j + 2 < NT) ATT_TOP(NKP + 2); else ATT_TOP(0);
;         if (j + 3 < NT) ATT_DMA_K(j + 3);
;         if (j + 2 < NT) ATT_DMA_V(j + 2, v2);
;         ATT_SEG(j); SBAR();
;         ATT_STEP(pA, pB, 0, v0, true, 1, j);
;         ATT_STEP(pB, pA, 1, v0, (j + 1 < NT), 0, j + 1);
;         { const int t_ = v0; v0 = v1; v1 = v2; v2 = t_; }
;     }
	ds_read_b64_tr_b16 v[218:219], v254 offset:0x3400
	ds_read_b64_tr_b16 v[220:221], v254 offset:0x3c00
	ds_read_b64_tr_b16 v[222:223], v254 offset:0x2600
	ds_read_b64_tr_b16 v[224:225], v254 offset:0x2e00
	ds_read_b64_tr_b16 v[226:227], v254 offset:0x3600
	ds_read_b64_tr_b16 v[228:229], v254 offset:0x3e00
	s_setprio 2
	v_exp_f32_e32 v64, v64
	v_exp_f32_e32 v65, v65
	v_exp_f32_e32 v66, v66
	v_exp_f32_e32 v67, v67
	v_exp_f32_e32 v68, v68
	v_exp_f32_e32 v69, v69
	v_add_f32_e32 v230, v65, v64
	v_exp_f32_e32 v70, v70
	v_add_f32_e32 v230, v66, v230
	v_exp_f32_e32 v71, v71
	v_add_f32_e32 v230, v67, v230
	v_exp_f32_e32 v72, v72
	v_add_f32_e32 v230, v68, v230
	v_exp_f32_e32 v73, v73
	v_add_f32_e32 v230, v69, v230
	v_exp_f32_e32 v74, v74
	v_add_f32_e32 v230, v70, v230
	v_exp_f32_e32 v75, v75
	v_add_f32_e32 v230, v71, v230
	v_exp_f32_e32 v76, v76
	v_add_f32_e32 v230, v72, v230
	v_exp_f32_e32 v77, v77
	v_add_f32_e32 v230, v73, v230
	v_exp_f32_e32 v78, v78
	v_add_f32_e32 v230, v74, v230
	v_exp_f32_e32 v79, v79
	v_add_f32_e32 v230, v75, v230
	v_add_f32_e32 v230, v76, v230
	v_add_f32_e32 v230, v77, v230
	v_add_f32_e32 v230, v78, v230
	v_add_f32_e32 v230, v79, v230
	v_add_f32_e32 v173, v173, v230
	v_cvt_pk_bf16_f32 v64, v64, v65
	v_cvt_pk_bf16_f32 v65, v66, v67
	v_cvt_pk_bf16_f32 v66, v68, v69
	v_cvt_pk_bf16_f32 v67, v70, v71
	v_cvt_pk_bf16_f32 v68, v72, v73
	v_cvt_pk_bf16_f32 v69, v74, v75
	v_cvt_pk_bf16_f32 v70, v76, v77
	v_cvt_pk_bf16_f32 v71, v78, v79
	s_waitcnt lgkmcnt(0)
	ds_read_b128 v[230:233], v252 offset:128
	ds_read_b128 v[234:237], v253 offset:128
	ds_read_b128 v[238:241], v250 offset:256
	ds_read_b128 v[242:245], v251 offset:256
	ds_read_b128 v[246:249], v252 offset:256
	ds_read_b128 v[250:253], v253 offset:256
	s_setprio 1
	s_waitcnt vmcnt(5)
	s_barrier
	v_mfma_f32_32x32x16_bf16 v[48:63], v[64:67], v[198:201], v[48:63]
	v_mfma_f32_32x32x16_bf16 v[32:47], v[64:67], v[206:209], v[32:47]
	v_mfma_f32_32x32x16_bf16 v[16:31], v[64:67], v[214:217], v[16:31]
	v_mfma_f32_32x32x16_bf16 v[0:15], v[64:67], v[222:225], v[0:15]
	v_mfma_f32_32x32x16_bf16 v[48:63], v[68:71], v[202:205], v[48:63]
	v_mfma_f32_32x32x16_bf16 v[32:47], v[68:71], v[210:213], v[32:47]
	v_mfma_f32_32x32x16_bf16 v[16:31], v[68:71], v[218:221], v[16:31]
	v_mfma_f32_32x32x16_bf16 v[0:15], v[68:71], v[226:229], v[0:15]
	s_waitcnt lgkmcnt(0)
	v_mfma_f32_32x32x16_bf16 v[64:79], v[174:177], v[80:83], 0
	v_mfma_f32_32x32x16_bf16 v[64:79], v[178:181], v[84:87], v[64:79]
	v_mfma_f32_32x32x16_bf16 v[64:79], v[182:185], v[88:91], v[64:79]
	v_mfma_f32_32x32x16_bf16 v[64:79], v[186:189], v[92:95], v[64:79]
	v_mfma_f32_32x32x16_bf16 v[64:79], v[190:193], v[96:99], v[64:79]
	v_mfma_f32_32x32x16_bf16 v[64:79], v[194:197], v[100:103], v[64:79]
	v_mfma_f32_32x32x16_bf16 v[64:79], v[230:233], v[104:107], v[64:79]
	v_mfma_f32_32x32x16_bf16 v[64:79], v[234:237], v[108:111], v[64:79]
	v_mfma_f32_32x32x16_bf16 v[64:79], v[238:241], v[112:115], v[64:79]
	v_mfma_f32_32x32x16_bf16 v[64:79], v[242:245], v[116:119], v[64:79]
	v_mfma_f32_32x32x16_bf16 v[64:79], v[246:249], v[120:123], v[64:79]
	v_mfma_f32_32x32x16_bf16 v[64:79], v[250:253], v[124:127], v[64:79]
	s_add_i32 s43, s43, 1
	v_add_u32_e32 v136, s36, v136
	v_add_u32_e32 v138, s36, v138
	v_add_u32_e32 v140, s36, v140
	v_add_u32_e32 v142, s38, v142
	v_add_u32_e32 v144, s38, v144
	s_cmp_eq_u32 s43, 64
	s_mov_b32 s4, s0
	s_cbranch_scc0 .Lhw_mla_b_n1982
	s_branch .Lhw_mla_exit
.LBB0_1982:
	s_and_b32 s1, s43, 3
	s_mulk_i32 s1, 0x6000
	s_add_i32 s1, s49, s1
	s_waitcnt vmcnt(5)
	s_barrier
	s_setprio 0
	s_mov_b32 m0, s1
	s_mov_b32 s0, s5
	s_mov_b32 s5, s44
	s_mov_b32 s44, s4
	s_lshl_b32 s4, s4, 14
	global_load_lds_dwordx4 v136, s[34:35]
	s_add_i32 m0, s1, 0x2000
	s_add_i32 s4, s52, s4
	global_load_lds_dwordx4 v138, s[34:35]
	s_add_i32 m0, s1, 0x4000
	s_add_i32 s6, s4, 0x400
	global_load_lds_dwordx4 v140, s[34:35]
	s_mov_b32 m0, s4
	s_add_i32 s1, s43, -3
	global_load_lds_dwordx4 v144, s[34:35]
	s_mov_b32 m0, s6
	s_nop 0
	global_load_lds_dwordx4 v142, s[34:35]
	s_and_b32 s1, s1, 3
	s_mulk_i32 s1, 0x6000
	v_add_u32_e32 v246, s1, v158
	v_add_u32_e32 v250, v246, v151
	v_add_u32_e32 v251, v246, v149
	v_add_u32_e32 v252, v246, v148
	v_add_u32_e32 v253, v246, v147
	s_lshl_b32 s1, s0, 14
	ds_read_b128 v[190:193], v250 offset:12416
	ds_read_b128 v[194:197], v251 offset:12416
	ds_read_b128 v[174:177], v250 offset:12288
	ds_read_b128 v[178:181], v251 offset:12288
	ds_read_b128 v[182:185], v252 offset:12288
	ds_read_b128 v[186:189], v253 offset:12288
	v_add_u32_e32 v254, s1, v130
	ds_read_b64_tr_b16 v[198:199], v254 offset:0
	ds_read_b64_tr_b16 v[200:201], v254 offset:0x800
	ds_read_b64_tr_b16 v[202:203], v254 offset:0x1000
	ds_read_b64_tr_b16 v[204:205], v254 offset:0x1800
	ds_read_b64_tr_b16 v[206:207], v254 offset:0x200
	ds_read_b64_tr_b16 v[208:209], v254 offset:0xa00
	ds_read_b64_tr_b16 v[210:211], v254 offset:0x1200
	ds_read_b64_tr_b16 v[212:213], v254 offset:0x1a00
	ds_read_b64_tr_b16 v[214:215], v254 offset:0x400
	ds_read_b64_tr_b16 v[216:217], v254 offset:0xc00
	ds_read_b64_tr_b16 v[218:219], v254 offset:0x1400
	ds_read_b64_tr_b16 v[220:221], v254 offset:0x1c00
	ds_read_b64_tr_b16 v[222:223], v254 offset:0x600
	ds_read_b64_tr_b16 v[224:225], v254 offset:0xe00
	ds_read_b64_tr_b16 v[226:227], v254 offset:0x1600
	ds_read_b64_tr_b16 v[228:229], v254 offset:0x1e00
	s_setprio 2
	v_exp_f32_e32 v64, v64
	v_exp_f32_e32 v65, v65
	v_exp_f32_e32 v66, v66
	v_exp_f32_e32 v67, v67
	v_exp_f32_e32 v68, v68
	v_exp_f32_e32 v69, v69
	v_add_f32_e32 v230, v65, v64
	v_exp_f32_e32 v70, v70
	v_add_f32_e32 v230, v66, v230
	v_exp_f32_e32 v71, v71
	v_add_f32_e32 v230, v67, v230
	v_exp_f32_e32 v72, v72
	v_add_f32_e32 v230, v68, v230
	v_exp_f32_e32 v73, v73
	v_add_f32_e32 v230, v69, v230
	v_exp_f32_e32 v74, v74
	v_add_f32_e32 v230, v70, v230
	v_exp_f32_e32 v75, v75
	v_add_f32_e32 v230, v71, v230
	v_exp_f32_e32 v76, v76
	v_add_f32_e32 v230, v72, v230
	v_exp_f32_e32 v77, v77
	v_add_f32_e32 v230, v73, v230
	v_exp_f32_e32 v78, v78
	v_add_f32_e32 v230, v74, v230
	v_exp_f32_e32 v79, v79
	v_add_f32_e32 v230, v75, v230
	v_add_f32_e32 v230, v76, v230
	v_add_f32_e32 v230, v77, v230
	v_add_f32_e32 v230, v78, v230
	v_add_f32_e32 v230, v79, v230
	v_add_f32_e32 v173, v173, v230
	v_cvt_pk_bf16_f32 v64, v64, v65
	v_cvt_pk_bf16_f32 v65, v66, v67
	v_cvt_pk_bf16_f32 v66, v68, v69
	v_cvt_pk_bf16_f32 v67, v70, v71
	v_cvt_pk_bf16_f32 v68, v72, v73
	v_cvt_pk_bf16_f32 v69, v74, v75
	v_cvt_pk_bf16_f32 v70, v76, v77
	v_cvt_pk_bf16_f32 v71, v78, v79
	s_waitcnt lgkmcnt(0)
; #define SBAR() __builtin_amdgcn_sched_barrier(0)
; #define ATT_DMA_K(t) do { const bf16_t* kg_ = Kh + (size_t)(t) * 64 * LDK; LAS unsigned char* sb_ = lds + ((t) & 3) * KBUF; \
;     _Pragma("unroll") for (int i_ = 0; i_ < NKP; ++i_) __builtin_amdgcn_global_load_lds((const unsigned*)(kg_ + kgo[i_]), (LAS unsigned*)(sb_ + (wid + 8 * i_) * 1024), 16, 0, 0); } while (0)
; #define ATT_DMA_V(t, vs) do { const bf16_t* vg_ = Vh + (size_t)(t) * 64 * LDV; LAS unsigned char* sb_ = lds + V_OFF + (vs) * SHM_V; \
;     _Pragma("unroll") for (int i_ = 0; i_ < 2; ++i_) __builtin_amdgcn_global_load_lds((const unsigned*)(vg_ + vgo[i_]), (LAS unsigned*)(sb_ + (2 * wid + i_) * 1024), 16, 0, 0); } while (0)
; #define ATT_SEG(t) do { if constexpr (MODE != 0) { if (((t) == tL && tL > 0) || (t) == tR) { const float f_ = (t) == tR ? fR : fL; l_reg *= f_; \
;     _Pragma("unroll") for (int d = 0; d < 4; ++d) _Pragma("unroll") for (int r = 0; r < 16; ++r) o[d][r] *= f_; } } } while (0)
; #define ATT_TOP(N) do { asm volatile("s_waitcnt vmcnt(%0)" :: "n"(N) : "memory"); __builtin_amdgcn_s_barrier(); asm volatile("" ::: "memory"); } while (0)
; DI void expsum(f32x16& p, float& l_reg, bf16x8& pa0, bf16x8& pa1) {
; #pragma unroll
;     for (int r = 0; r < 16; ++r) p[r] = __builtin_amdgcn_exp2f(p[r]);
;     float ps = 0.f;
; #pragma unroll
;     for (int r = 0; r < 16; ++r) ps += p[r];
;     l_reg += ps; asm volatile("" : "+v"(l_reg));
;     ...
;     ATT_PK4(p, 0, pa0); ATT_PK4(p, 8, pa1);
;     ...
; }
; template <int DQK, int MODE, int LDQ, int LDK, int LDV> ...
;     ...
;     f32x16 pA, pB; bf16x8 pa0, pa1;
;     int v0 = 0, v1 = 1, v2 = 2;
;     ATT_TOP(NKP + 2);
;     { bf16x8 kf[NDA]; k_reads<DQK, 0, NDA>(kf, lds, 0, r32, hi); ATT_LGKM0(); qk_mma<0, NDA>(pA, kf, qr);
;       if constexpr (ND0 > NDA) { bf16x8 kg[ND0 - NDA]; k_reads<DQK, NDA, ND0>(kg, lds, 0, r32, hi); ATT_LGKM0(); qk_mma<NDA, ND0>(pA, kg, qr); }
;       ATT_BIAS(pA, 0, 0); }
;     if (wid >= 4) __builtin_amdgcn_s_setprio(1);
;     for (int j = 0; j < NT; ++j) {
;         if (j + 2 < NT) ATT_TOP(NKP + 2); else ATT_TOP(0);
;         if (j + 3 < NT) ATT_DMA_K(j + 3);
;         if (j + 2 < NT) ATT_DMA_V(j + 2, v2);
;         ATT_SEG(j); SBAR();
;         ATT_STEP(pA, pB, 0, v0, true, 1, j);
;         ATT_STEP(pB, pA, 1, v0, (j + 1 < NT), 0, j + 1);
;         { const int t_ = v0; v0 = v1; v1 = v2; v2 = t_; }
;     }
	ds_read_b128 v[230:233], v252 offset:12416
	ds_read_b128 v[234:237], v253 offset:12416
	ds_read_b128 v[238:241], v250 offset:12544
	ds_read_b128 v[242:245], v251 offset:12544
	ds_read_b128 v[246:249], v252 offset:12544
	ds_read_b128 v[250:253], v253 offset:12544
	s_setprio 1
	v_mfma_f32_32x32x16_bf16 v[48:63], v[64:67], v[198:201], v[48:63]
	v_mfma_f32_32x32x16_bf16 v[32:47], v[64:67], v[206:209], v[32:47]
	v_mfma_f32_32x32x16_bf16 v[16:31], v[64:67], v[214:217], v[16:31]
	v_mfma_f32_32x32x16_bf16 v[0:15], v[64:67], v[222:225], v[0:15]
	v_mfma_f32_32x32x16_bf16 v[48:63], v[68:71], v[202:205], v[48:63]
	v_mfma_f32_32x32x16_bf16 v[32:47], v[68:71], v[210:213], v[32:47]
	v_mfma_f32_32x32x16_bf16 v[16:31], v[68:71], v[218:221], v[16:31]
	v_mfma_f32_32x32x16_bf16 v[0:15], v[68:71], v[226:229], v[0:15]
	s_waitcnt lgkmcnt(0)
	v_mfma_f32_32x32x16_bf16 v[64:79], v[174:177], v[80:83], 0
	v_mfma_f32_32x32x16_bf16 v[64:79], v[178:181], v[84:87], v[64:79]
	v_mfma_f32_32x32x16_bf16 v[64:79], v[182:185], v[88:91], v[64:79]
	v_mfma_f32_32x32x16_bf16 v[64:79], v[186:189], v[92:95], v[64:79]
	v_mfma_f32_32x32x16_bf16 v[64:79], v[190:193], v[96:99], v[64:79]
	v_mfma_f32_32x32x16_bf16 v[64:79], v[194:197], v[100:103], v[64:79]
	v_mfma_f32_32x32x16_bf16 v[64:79], v[230:233], v[104:107], v[64:79]
	v_mfma_f32_32x32x16_bf16 v[64:79], v[234:237], v[108:111], v[64:79]
	v_mfma_f32_32x32x16_bf16 v[64:79], v[238:241], v[112:115], v[64:79]
	v_mfma_f32_32x32x16_bf16 v[64:79], v[242:245], v[116:119], v[64:79]
	v_mfma_f32_32x32x16_bf16 v[64:79], v[246:249], v[120:123], v[64:79]
	v_mfma_f32_32x32x16_bf16 v[64:79], v[250:253], v[124:127], v[64:79]
	s_setprio 0
	s_add_i32 s4, s43, -2
	s_and_b32 s4, s4, 3
	s_mulk_i32 s4, 0x6000
	v_add_u32_e32 v246, s4, v158
	v_add_u32_e32 v250, v246, v151
	v_add_u32_e32 v251, v246, v149
	v_add_u32_e32 v252, v246, v148
	v_add_u32_e32 v253, v246, v147
	ds_read_b128 v[190:193], v250 offset:128
	ds_read_b128 v[194:197], v251 offset:128
	ds_read_b128 v[174:177], v250
	ds_read_b128 v[178:181], v251
	ds_read_b128 v[182:185], v252
	ds_read_b128 v[186:189], v253
	ds_read_b64_tr_b16 v[198:199], v254 offset:0x2000
	ds_read_b64_tr_b16 v[200:201], v254 offset:0x2800
	ds_read_b64_tr_b16 v[202:203], v254 offset:0x3000
	ds_read_b64_tr_b16 v[204:205], v254 offset:0x3800
	ds_read_b64_tr_b16 v[206:207], v254 offset:0x2200
	ds_read_b64_tr_b16 v[208:209], v254 offset:0x2a00
	ds_read_b64_tr_b16 v[210:211], v254 offset:0x3200
	ds_read_b64_tr_b16 v[212:213], v254 offset:0x3a00
	ds_read_b64_tr_b16 v[214:215], v254 offset:0x2400
	ds_read_b64_tr_b16 v[216:217], v254 offset:0x2c00
	ds_read_b64_tr_b16 v[218:219], v254 offset:0x3400
	ds_read_b64_tr_b16 v[220:221], v254 offset:0x3c00
	ds_read_b64_tr_b16 v[222:223], v254 offset:0x2600
	ds_read_b64_tr_b16 v[224:225], v254 offset:0x2e00
	ds_read_b64_tr_b16 v[226:227], v254 offset:0x3600
	ds_read_b64_tr_b16 v[228:229], v254 offset:0x3e00
	s_setprio 2
	v_exp_f32_e32 v64, v64
	v_exp_f32_e32 v65, v65
	v_exp_f32_e32 v66, v66
	v_exp_f32_e32 v67, v67
	v_exp_f32_e32 v68, v68
	v_exp_f32_e32 v69, v69
	v_add_f32_e32 v230, v65, v64
	v_exp_f32_e32 v70, v70
	v_add_f32_e32 v230, v66, v230
	v_exp_f32_e32 v71, v71
	v_add_f32_e32 v230, v67, v230
	v_exp_f32_e32 v72, v72
	v_add_f32_e32 v230, v68, v230
	v_exp_f32_e32 v73, v73
	v_add_f32_e32 v230, v69, v230
	v_exp_f32_e32 v74, v74
	v_add_f32_e32 v230, v70, v230
	v_exp_f32_e32 v75, v75
	v_add_f32_e32 v230, v71, v230
	v_exp_f32_e32 v76, v76
	v_add_f32_e32 v230, v72, v230
	v_exp_f32_e32 v77, v77
	v_add_f32_e32 v230, v73, v230
	v_exp_f32_e32 v78, v78
	v_add_f32_e32 v230, v74, v230
	v_exp_f32_e32 v79, v79
	v_add_f32_e32 v230, v75, v230
	v_add_f32_e32 v230, v76, v230
	v_add_f32_e32 v230, v77, v230
	v_add_f32_e32 v230, v78, v230
	v_add_f32_e32 v230, v79, v230
	v_add_f32_e32 v173, v173, v230
	v_cvt_pk_bf16_f32 v64, v64, v65
	v_cvt_pk_bf16_f32 v65, v66, v67
	v_cvt_pk_bf16_f32 v66, v68, v69
	v_cvt_pk_bf16_f32 v67, v70, v71
	v_cvt_pk_bf16_f32 v68, v72, v73
	v_cvt_pk_bf16_f32 v69, v74, v75
	v_cvt_pk_bf16_f32 v70, v76, v77
	v_cvt_pk_bf16_f32 v71, v78, v79
	s_waitcnt lgkmcnt(0)
	ds_read_b128 v[230:233], v252 offset:128
	ds_read_b128 v[234:237], v253 offset:128
	ds_read_b128 v[238:241], v250 offset:256
	ds_read_b128 v[242:245], v251 offset:256
	ds_read_b128 v[246:249], v252 offset:256
	ds_read_b128 v[250:253], v253 offset:256
	s_setprio 1
	v_mfma_f32_32x32x16_bf16 v[48:63], v[64:67], v[198:201], v[48:63]
	v_mfma_f32_32x32x16_bf16 v[32:47], v[64:67], v[206:209], v[32:47]
	v_mfma_f32_32x32x16_bf16 v[16:31], v[64:67], v[214:217], v[16:31]
	v_mfma_f32_32x32x16_bf16 v[0:15], v[64:67], v[222:225], v[0:15]
	v_mfma_f32_32x32x16_bf16 v[48:63], v[68:71], v[202:205], v[48:63]
	v_mfma_f32_32x32x16_bf16 v[32:47], v[68:71], v[210:213], v[32:47]
	v_mfma_f32_32x32x16_bf16 v[16:31], v[68:71], v[218:221], v[16:31]
	v_mfma_f32_32x32x16_bf16 v[0:15], v[68:71], v[226:229], v[0:15]
	s_waitcnt lgkmcnt(0)
	v_mfma_f32_32x32x16_bf16 v[64:79], v[174:177], v[80:83], 0
	v_mfma_f32_32x32x16_bf16 v[64:79], v[178:181], v[84:87], v[64:79]
	v_mfma_f32_32x32x16_bf16 v[64:79], v[182:185], v[88:91], v[64:79]
	v_mfma_f32_32x32x16_bf16 v[64:79], v[186:189], v[92:95], v[64:79]
	v_mfma_f32_32x32x16_bf16 v[64:79], v[190:193], v[96:99], v[64:79]
	v_mfma_f32_32x32x16_bf16 v[64:79], v[194:197], v[100:103], v[64:79]
	v_mfma_f32_32x32x16_bf16 v[64:79], v[230:233], v[104:107], v[64:79]
	v_mfma_f32_32x32x16_bf16 v[64:79], v[234:237], v[108:111], v[64:79]
	v_mfma_f32_32x32x16_bf16 v[64:79], v[238:241], v[112:115], v[64:79]
	v_mfma_f32_32x32x16_bf16 v[64:79], v[242:245], v[116:119], v[64:79]
	v_mfma_f32_32x32x16_bf16 v[64:79], v[246:249], v[120:123], v[64:79]
	v_mfma_f32_32x32x16_bf16 v[64:79], v[250:253], v[124:127], v[64:79]
	s_add_i32 s43, s43, 1
	v_add_u32_e32 v136, s36, v136
	v_add_u32_e32 v138, s36, v138
	v_add_u32_e32 v140, s36, v140
	v_add_u32_e32 v142, s38, v142
	v_add_u32_e32 v144, s38, v144
	s_cmp_eq_u32 s43, 64
	s_mov_b32 s4, s0
	s_cbranch_scc0 .LBB0_1982

; #define SBAR() __builtin_amdgcn_sched_barrier(0)
; #define ATT_DMA_K(t) do { const bf16_t* kg_ = Kh + (size_t)(t) * 64 * LDK; LAS unsigned char* sb_ = lds + ((t) & 3) * KBUF; \
;     _Pragma("unroll") for (int i_ = 0; i_ < NKP; ++i_) __builtin_amdgcn_global_load_lds((const unsigned*)(kg_ + kgo[i_]), (LAS unsigned*)(sb_ + (wid + 8 * i_) * 1024), 16, 0, 0); } while (0)
; #define ATT_DMA_V(t, vs) do { const bf16_t* vg_ = Vh + (size_t)(t) * 64 * LDV; LAS unsigned char* sb_ = lds + V_OFF + (vs) * SHM_V; \
;     _Pragma("unroll") for (int i_ = 0; i_ < 2; ++i_) __builtin_amdgcn_global_load_lds((const unsigned*)(vg_ + vgo[i_]), (LAS unsigned*)(sb_ + (2 * wid + i_) * 1024), 16, 0, 0); } while (0)
; #define ATT_SEG(t) do { if constexpr (MODE != 0) { if (((t) == tL && tL > 0) || (t) == tR) { const float f_ = (t) == tR ? fR : fL; l_reg *= f_; \
;     _Pragma("unroll") for (int d = 0; d < 4; ++d) _Pragma("unroll") for (int r = 0; r < 16; ++r) o[d][r] *= f_; } } } while (0)
; #define ATT_TOP(N) do { asm volatile("s_waitcnt vmcnt(%0)" :: "n"(N) : "memory"); __builtin_amdgcn_s_barrier(); asm volatile("" ::: "memory"); } while (0)
; DI void expsum(f32x16& p, float& l_reg, bf16x8& pa0, bf16x8& pa1) {
; #pragma unroll
;     for (int r = 0; r < 16; ++r) p[r] = __builtin_amdgcn_exp2f(p[r]);
;     float ps = 0.f;
; #pragma unroll
;     for (int r = 0; r < 16; ++r) ps += p[r];
;     l_reg += ps; asm volatile("" : "+v"(l_reg));
;     ...
;     ATT_PK4(p, 0, pa0); ATT_PK4(p, 8, pa1);
;     ...
; }
; template <int DQK, int MODE, int LDQ, int LDK, int LDV> ...
;     ...
;     f32x16 pA, pB; bf16x8 pa0, pa1;
;     int v0 = 0, v1 = 1, v2 = 2;
;     ATT_TOP(NKP + 2);
;     { bf16x8 kf[NDA]; k_reads<DQK, 0, NDA>(kf, lds, 0, r32, hi); ATT_LGKM0(); qk_mma<0, NDA>(pA, kf, qr);
;       if constexpr (ND0 > NDA) { bf16x8 kg[ND0 - NDA]; k_reads<DQK, NDA, ND0>(kg, lds, 0, r32, hi); ATT_LGKM0(); qk_mma<NDA, ND0>(pA, kg, qr); }
;       ATT_BIAS(pA, 0, 0); }
;     if (wid >= 4) __builtin_amdgcn_s_setprio(1);
;     for (int j = 0; j < NT; ++j) {
;         if (j + 2 < NT) ATT_TOP(NKP + 2); else ATT_TOP(0);
;         if (j + 3 < NT) ATT_DMA_K(j + 3);
;         if (j + 2 < NT) ATT_DMA_V(j + 2, v2);
;         ATT_SEG(j); SBAR();
;         ATT_STEP(pA, pB, 0, v0, true, 1, j);
;         ATT_STEP(pB, pA, 1, v0, (j + 1 < NT), 0, j + 1);
.Lstg_mla_t61_4:
	s_setprio 0
	v_lshl_add_u64 v[132:133], v[132:133], 1, s[0:1]
	s_mov_b32 m0, s6
	v_lshl_add_u64 v[134:135], v[134:135], 1, s[0:1]
	global_load_lds_dwordx4 v[132:133], off
	s_mov_b32 m0, s7
	s_nop 0
	global_load_lds_dwordx4 v[134:135], off
	ds_read_b128 v[132:135], v161 offset:36864
	ds_read_b128 v[136:139], v162 offset:36864
	ds_read_b128 v[140:143], v163 offset:36864
	ds_read_b128 v[174:177], v164 offset:36864
	ds_read_b128 v[178:181], v165 offset:36864
	ds_read_b128 v[182:185], v166 offset:36864
	v_lshl_add_u32 v144, s5, 14, v130
	ds_read_b64_tr_b16 v[186:187], v144 offset:0
	ds_read_b64_tr_b16 v[188:189], v144 offset:0x800
	ds_read_b64_tr_b16 v[190:191], v144 offset:0x1000
	ds_read_b64_tr_b16 v[192:193], v144 offset:0x1800
	ds_read_b64_tr_b16 v[194:195], v144 offset:0x200
	ds_read_b64_tr_b16 v[196:197], v144 offset:0xa00
	ds_read_b64_tr_b16 v[198:199], v144 offset:0x1200
	ds_read_b64_tr_b16 v[200:201], v144 offset:0x1a00
	ds_read_b64_tr_b16 v[202:203], v144 offset:0x400
	ds_read_b64_tr_b16 v[204:205], v144 offset:0xc00
	ds_read_b64_tr_b16 v[206:207], v144 offset:0x1400
	ds_read_b64_tr_b16 v[208:209], v144 offset:0x1c00
	ds_read_b64_tr_b16 v[210:211], v144 offset:0x600
	ds_read_b64_tr_b16 v[212:213], v144 offset:0xe00
	ds_read_b64_tr_b16 v[214:215], v144 offset:0x1600
	ds_read_b64_tr_b16 v[216:217], v144 offset:0x1e00
	s_setprio 2
	v_exp_f32_e32 v64, v64
	v_exp_f32_e32 v65, v65
	v_exp_f32_e32 v66, v66
	v_exp_f32_e32 v67, v67
	v_exp_f32_e32 v68, v68
	v_exp_f32_e32 v69, v69
	v_add_f32_e32 v145, v65, v64
	v_exp_f32_e32 v70, v70
	v_add_f32_e32 v145, v66, v145
	v_exp_f32_e32 v71, v71
	v_add_f32_e32 v145, v67, v145
	v_exp_f32_e32 v72, v72
	v_add_f32_e32 v145, v68, v145
	v_exp_f32_e32 v73, v73
	v_add_f32_e32 v145, v69, v145
	v_exp_f32_e32 v74, v74
	v_add_f32_e32 v145, v70, v145
	v_exp_f32_e32 v75, v75
	v_add_f32_e32 v145, v71, v145
	v_exp_f32_e32 v76, v76
	v_add_f32_e32 v145, v72, v145
	v_exp_f32_e32 v77, v77
	v_add_f32_e32 v145, v73, v145
	v_exp_f32_e32 v78, v78
	v_add_f32_e32 v145, v74, v145
	v_exp_f32_e32 v79, v79
	v_add_f32_e32 v145, v75, v145
	v_add_f32_e32 v145, v76, v145
	v_add_f32_e32 v145, v77, v145
	v_add_f32_e32 v145, v78, v145
	v_add_f32_e32 v145, v79, v145
	v_add_f32_e32 v145, v173, v145
	v_cvt_pk_bf16_f32 v64, v64, v65
	v_cvt_pk_bf16_f32 v65, v66, v67
	v_cvt_pk_bf16_f32 v66, v68, v69
	v_cvt_pk_bf16_f32 v67, v70, v71
	v_cvt_pk_bf16_f32 v68, v72, v73
	v_cvt_pk_bf16_f32 v69, v74, v75
	v_cvt_pk_bf16_f32 v70, v76, v77
	v_cvt_pk_bf16_f32 v71, v78, v79
	s_waitcnt lgkmcnt(0)
	ds_read_b128 v[218:221], v167 offset:36864
	ds_read_b128 v[222:225], v168 offset:36864
	ds_read_b128 v[226:229], v169 offset:36864
	ds_read_b128 v[230:233], v170 offset:36864
	ds_read_b128 v[234:237], v171 offset:36864
	ds_read_b128 v[238:241], v172 offset:36864
	s_setprio 1
	v_mfma_f32_32x32x16_bf16 v[48:63], v[64:67], v[186:189], v[48:63]
	v_mfma_f32_32x32x16_bf16 v[32:47], v[64:67], v[194:197], v[32:47]
	v_mfma_f32_32x32x16_bf16 v[16:31], v[64:67], v[202:205], v[16:31]
	v_mfma_f32_32x32x16_bf16 v[0:15], v[64:67], v[210:213], v[0:15]
	v_mfma_f32_32x32x16_bf16 v[48:63], v[68:71], v[190:193], v[48:63]
	v_mfma_f32_32x32x16_bf16 v[32:47], v[68:71], v[198:201], v[32:47]
	v_mfma_f32_32x32x16_bf16 v[16:31], v[68:71], v[206:209], v[16:31]
	v_mfma_f32_32x32x16_bf16 v[0:15], v[68:71], v[214:217], v[0:15]
	s_waitcnt lgkmcnt(0)
	v_mfma_f32_32x32x16_bf16 v[64:79], v[132:135], v[80:83], 0
	v_mfma_f32_32x32x16_bf16 v[64:79], v[136:139], v[84:87], v[64:79]
	v_mfma_f32_32x32x16_bf16 v[64:79], v[140:143], v[88:91], v[64:79]
	v_mfma_f32_32x32x16_bf16 v[64:79], v[174:177], v[92:95], v[64:79]
	v_mfma_f32_32x32x16_bf16 v[64:79], v[178:181], v[96:99], v[64:79]
	v_mfma_f32_32x32x16_bf16 v[64:79], v[182:185], v[100:103], v[64:79]
	s_waitcnt lgkmcnt(0)
	v_mfma_f32_32x32x16_bf16 v[64:79], v[218:221], v[104:107], v[64:79]
	v_mfma_f32_32x32x16_bf16 v[64:79], v[222:225], v[108:111], v[64:79]
	v_mfma_f32_32x32x16_bf16 v[64:79], v[226:229], v[112:115], v[64:79]
	v_mfma_f32_32x32x16_bf16 v[64:79], v[230:233], v[116:119], v[64:79]
	v_mfma_f32_32x32x16_bf16 v[64:79], v[234:237], v[120:123], v[64:79]
	v_mfma_f32_32x32x16_bf16 v[64:79], v[238:241], v[124:127], v[64:79]
	s_setprio 0
	ds_read_b128 v[132:135], v161 offset:49152
	ds_read_b128 v[136:139], v162 offset:49152
	ds_read_b128 v[140:143], v163 offset:49152
	ds_read_b128 v[174:177], v164 offset:49152
	ds_read_b128 v[178:181], v165 offset:49152
	ds_read_b128 v[182:185], v166 offset:49152
	ds_read_b64_tr_b16 v[186:187], v144 offset:0x2000
	ds_read_b64_tr_b16 v[188:189], v144 offset:0x2800
	ds_read_b64_tr_b16 v[190:191], v144 offset:0x3000
	ds_read_b64_tr_b16 v[192:193], v144 offset:0x3800
	ds_read_b64_tr_b16 v[194:195], v144 offset:0x2200
	ds_read_b64_tr_b16 v[196:197], v144 offset:0x2a00
	ds_read_b64_tr_b16 v[198:199], v144 offset:0x3200
	ds_read_b64_tr_b16 v[200:201], v144 offset:0x3a00
	ds_read_b64_tr_b16 v[202:203], v144 offset:0x2400
	ds_read_b64_tr_b16 v[204:205], v144 offset:0x2c00
	ds_read_b64_tr_b16 v[206:207], v144 offset:0x3400
	ds_read_b64_tr_b16 v[208:209], v144 offset:0x3c00
	ds_read_b64_tr_b16 v[210:211], v144 offset:0x2600
	ds_read_b64_tr_b16 v[212:213], v144 offset:0x2e00
	ds_read_b64_tr_b16 v[214:215], v144 offset:0x3600
	ds_read_b64_tr_b16 v[216:217], v144 offset:0x3e00
	s_nop 5
	s_setprio 2
	v_exp_f32_e32 v64, v64
	v_exp_f32_e32 v65, v65
	v_exp_f32_e32 v66, v66
	v_exp_f32_e32 v67, v67
	v_exp_f32_e32 v68, v68
	v_exp_f32_e32 v69, v69
	v_add_f32_e32 v144, v65, v64
	v_exp_f32_e32 v70, v70
	v_add_f32_e32 v144, v66, v144
	v_exp_f32_e32 v71, v71
	v_add_f32_e32 v144, v67, v144
	v_exp_f32_e32 v72, v72
	v_add_f32_e32 v144, v68, v144
	v_exp_f32_e32 v73, v73
	v_add_f32_e32 v144, v69, v144
	v_exp_f32_e32 v74, v74
	v_add_f32_e32 v144, v70, v144
	v_exp_f32_e32 v75, v75
	v_add_f32_e32 v144, v71, v144
	v_exp_f32_e32 v76, v76
	v_add_f32_e32 v144, v72, v144
	v_exp_f32_e32 v77, v77
	v_add_f32_e32 v144, v73, v144
	v_exp_f32_e32 v78, v78
	v_add_f32_e32 v144, v74, v144
	v_exp_f32_e32 v79, v79
	v_add_f32_e32 v144, v75, v144
	v_add_f32_e32 v144, v76, v144
	v_add_f32_e32 v144, v77, v144
	v_add_f32_e32 v144, v78, v144
	v_add_f32_e32 v144, v79, v144
	v_add_f32_e32 v144, v145, v144
	v_cvt_pk_bf16_f32 v64, v64, v65
	v_cvt_pk_bf16_f32 v65, v66, v67
	v_cvt_pk_bf16_f32 v66, v68, v69
	v_cvt_pk_bf16_f32 v67, v70, v71
	v_cvt_pk_bf16_f32 v68, v72, v73
	v_cvt_pk_bf16_f32 v69, v74, v75
	v_cvt_pk_bf16_f32 v70, v76, v77
	v_cvt_pk_bf16_f32 v71, v78, v79
	s_waitcnt lgkmcnt(0)
	ds_read_b128 v[218:221], v167 offset:49152
	ds_read_b128 v[222:225], v168 offset:49152
	ds_read_b128 v[226:229], v169 offset:49152
	ds_read_b128 v[230:233], v170 offset:49152
	ds_read_b128 v[234:237], v171 offset:49152
	ds_read_b128 v[238:241], v172 offset:49152
	s_setprio 1
	s_cmp_lt_u32 s33, 0x100
	s_cbranch_scc1 .Lstg_mla_m61_5
	s_waitcnt vmcnt(0)
	s_barrier

; template <int TAG = 0> DI int fresh_tid(int wv) { int l; asm volatile("v_mbcnt_lo_u32_b32 %0, -1, 0\n\tv_mbcnt_hi_u32_b32 %0, -1, %0 ; site %1" : "=v"(l) : "n"(TAG)); return wv * 64 + l; }
; #define SBAR() __builtin_amdgcn_sched_barrier(0)
; DI float swap_sum(float v) { auto rr = __builtin_amdgcn_permlane32_swap(__float_as_uint(v), __float_as_uint(v), false, false); return __uint_as_float(rr[0]) + __uint_as_float(rr[1]); }
; #define ATT_DMA_K(t) do { const bf16_t* kg_ = Kh + (size_t)(t) * 64 * LDK; LAS unsigned char* sb_ = lds + ((t) & 3) * KBUF; \
;     _Pragma("unroll") for (int i_ = 0; i_ < NKP; ++i_) __builtin_amdgcn_global_load_lds((const unsigned*)(kg_ + kgo[i_]), (LAS unsigned*)(sb_ + (wid + 8 * i_) * 1024), 16, 0, 0); } while (0)
; #define ATT_TOP(N) do { asm volatile("s_waitcnt vmcnt(%0)" :: "n"(N) : "memory"); __builtin_amdgcn_s_barrier(); asm volatile("" ::: "memory"); } while (0)
; DI void expsum(f32x16& p, float& l_reg, bf16x8& pa0, bf16x8& pa1) {
; #pragma unroll
;     for (int r = 0; r < 16; ++r) p[r] = __builtin_amdgcn_exp2f(p[r]);
;     float ps = 0.f;
; #pragma unroll
;     for (int r = 0; r < 16; ++r) ps += p[r];
;     l_reg += ps; asm volatile("" : "+v"(l_reg));
;     ...
;     ATT_PK4(p, 0, pa0); ATT_PK4(p, 8, pa1);
;     ...
; }
; template <int DQK, int MODE, int LDQ, int LDK, int LDV> ...
;     ...
;     f32x16 pA, pB; bf16x8 pa0, pa1;
;     int v0 = 0, v1 = 1, v2 = 2;
;     ATT_TOP(NKP + 2);
;     { bf16x8 kf[NDA]; k_reads<DQK, 0, NDA>(kf, lds, 0, r32, hi); ATT_LGKM0(); qk_mma<0, NDA>(pA, kf, qr);
;       if constexpr (ND0 > NDA) { bf16x8 kg[ND0 - NDA]; k_reads<DQK, NDA, ND0>(kg, lds, 0, r32, hi); ATT_LGKM0(); qk_mma<NDA, ND0>(pA, kg, qr); }
;       ATT_BIAS(pA, 0, 0); }
;     if (wid >= 4) __builtin_amdgcn_s_setprio(1);
;     for (int j = 0; j < NT; ++j) {
;         if (j + 2 < NT) ATT_TOP(NKP + 2); else ATT_TOP(0);
;         if (j + 3 < NT) ATT_DMA_K(j + 3);
;         if (j + 2 < NT) ATT_DMA_V(j + 2, v2);
;         ATT_SEG(j); SBAR();
;         ATT_STEP(pA, pB, 0, v0, true, 1, j);
;         ATT_STEP(pB, pA, 1, v0, (j + 1 < NT), 0, j + 1);
;         { const int t_ = v0; v0 = v1; v1 = v2; v2 = t_; }
;     }
;     __builtin_amdgcn_s_setprio(0);
;     ...
;     l_reg = swap_sum(l_reg);
;     { const int lane2 = fresh_tid<110 + MODE>(wv) & 63, r32 = lane2 & 31, hi = lane2 >> 5;
;     if (hi == 0) li_l[r32] = l_reg;
.Lstg_mla_t62_6:
	s_setprio 0
	ds_read_b128 v[132:135], v161 offset:61440
	ds_read_b128 v[136:139], v162 offset:61440
	ds_read_b128 v[140:143], v163 offset:61440
	ds_read_b128 v[174:177], v164 offset:61440
	ds_read_b128 v[162:165], v165 offset:61440
	ds_read_b128 v[178:181], v166 offset:61440
	v_add_u32_e32 v145, 0x8000, v130
	ds_read_b64_tr_b16 v[182:183], v145 offset:0
	ds_read_b64_tr_b16 v[184:185], v145 offset:0x800
	ds_read_b64_tr_b16 v[186:187], v145 offset:0x1000
	ds_read_b64_tr_b16 v[188:189], v145 offset:0x1800
	ds_read_b64_tr_b16 v[190:191], v145 offset:0x200
	ds_read_b64_tr_b16 v[192:193], v145 offset:0xa00
	ds_read_b64_tr_b16 v[194:195], v145 offset:0x1200
	ds_read_b64_tr_b16 v[196:197], v145 offset:0x1a00
	ds_read_b64_tr_b16 v[198:199], v145 offset:0x400
	ds_read_b64_tr_b16 v[200:201], v145 offset:0xc00
	ds_read_b64_tr_b16 v[202:203], v145 offset:0x1400
	ds_read_b64_tr_b16 v[204:205], v145 offset:0x1c00
	ds_read_b64_tr_b16 v[206:207], v145 offset:0x600
	ds_read_b64_tr_b16 v[208:209], v145 offset:0xe00
	ds_read_b64_tr_b16 v[210:211], v145 offset:0x1600
	ds_read_b64_tr_b16 v[212:213], v145 offset:0x1e00
	s_nop 3
	s_setprio 2
	v_exp_f32_e32 v64, v64
	v_exp_f32_e32 v65, v65
	v_exp_f32_e32 v66, v66
	v_exp_f32_e32 v67, v67
	v_exp_f32_e32 v68, v68
	v_exp_f32_e32 v69, v69
	v_add_f32_e32 v161, v65, v64
	v_exp_f32_e32 v70, v70
	v_add_f32_e32 v161, v66, v161
	v_exp_f32_e32 v71, v71
	v_add_f32_e32 v161, v67, v161
	v_exp_f32_e32 v72, v72
	v_add_f32_e32 v161, v68, v161
	v_exp_f32_e32 v73, v73
	v_add_f32_e32 v161, v69, v161
	v_exp_f32_e32 v74, v74
	v_add_f32_e32 v161, v70, v161
	v_exp_f32_e32 v75, v75
	v_add_f32_e32 v161, v71, v161
	v_exp_f32_e32 v76, v76
	v_add_f32_e32 v161, v72, v161
	v_exp_f32_e32 v77, v77
	v_add_f32_e32 v161, v73, v161
	v_exp_f32_e32 v78, v78
	v_add_f32_e32 v161, v74, v161
	v_exp_f32_e32 v79, v79
	v_add_f32_e32 v161, v75, v161
	v_add_f32_e32 v161, v76, v161
	v_add_f32_e32 v161, v77, v161
	v_add_f32_e32 v161, v78, v161
	v_add_f32_e32 v161, v79, v161
	v_add_f32_e32 v144, v144, v161
	v_cvt_pk_bf16_f32 v64, v64, v65
	v_cvt_pk_bf16_f32 v65, v66, v67
	v_cvt_pk_bf16_f32 v66, v68, v69
	v_cvt_pk_bf16_f32 v67, v70, v71
	v_cvt_pk_bf16_f32 v68, v72, v73
	v_cvt_pk_bf16_f32 v69, v74, v75
	v_cvt_pk_bf16_f32 v70, v76, v77
	v_cvt_pk_bf16_f32 v71, v78, v79
	s_waitcnt lgkmcnt(0)
	ds_read_b128 v[214:217], v167 offset:61440
	ds_read_b128 v[218:221], v168 offset:61440
	ds_read_b128 v[166:169], v169 offset:61440
	ds_read_b128 v[222:225], v170 offset:61440
	ds_read_b128 v[226:229], v171 offset:61440
	ds_read_b128 v[170:173], v172 offset:61440
	s_setprio 1
	v_mfma_f32_32x32x16_bf16 v[48:63], v[64:67], v[182:185], v[48:63]
	v_mfma_f32_32x32x16_bf16 v[32:47], v[64:67], v[190:193], v[32:47]
	v_mfma_f32_32x32x16_bf16 v[16:31], v[64:67], v[198:201], v[16:31]
	v_mfma_f32_32x32x16_bf16 v[0:15], v[64:67], v[206:209], v[0:15]
	v_mfma_f32_32x32x16_bf16 v[48:63], v[68:71], v[186:189], v[48:63]
	v_mfma_f32_32x32x16_bf16 v[32:47], v[68:71], v[194:197], v[32:47]
	v_mfma_f32_32x32x16_bf16 v[16:31], v[68:71], v[202:205], v[16:31]
	v_mfma_f32_32x32x16_bf16 v[0:15], v[68:71], v[210:213], v[0:15]
	s_waitcnt lgkmcnt(0)
	v_mfma_f32_32x32x16_bf16 v[64:79], v[132:135], v[80:83], 0
	v_mfma_f32_32x32x16_bf16 v[64:79], v[136:139], v[84:87], v[64:79]
	v_mfma_f32_32x32x16_bf16 v[64:79], v[140:143], v[88:91], v[64:79]
	v_mfma_f32_32x32x16_bf16 v[64:79], v[174:177], v[92:95], v[64:79]
	v_mfma_f32_32x32x16_bf16 v[64:79], v[162:165], v[96:99], v[64:79]
	v_mfma_f32_32x32x16_bf16 v[64:79], v[178:181], v[100:103], v[64:79]
	s_waitcnt lgkmcnt(0)
	v_mfma_f32_32x32x16_bf16 v[64:79], v[214:217], v[104:107], v[64:79]
	v_mfma_f32_32x32x16_bf16 v[64:79], v[218:221], v[108:111], v[64:79]
	v_mfma_f32_32x32x16_bf16 v[64:79], v[166:169], v[112:115], v[64:79]
	v_mfma_f32_32x32x16_bf16 v[64:79], v[222:225], v[116:119], v[64:79]
	v_mfma_f32_32x32x16_bf16 v[64:79], v[226:229], v[120:123], v[64:79]
	v_mfma_f32_32x32x16_bf16 v[64:79], v[170:173], v[124:127], v[64:79]
	s_setprio 0
	v_add_u32_e32 v158, 0x12000, v158
	v_add_u32_e32 v132, v158, v151
	v_add_u32_e32 v136, v158, v149
	v_add_u32_e32 v140, v158, v148
	v_add_u32_e32 v161, v158, v147
	ds_read_b128 v[132:135], v132
	ds_read_b128 v[136:139], v136
	ds_read_b128 v[140:143], v140
	ds_read_b128 v[162:165], v161
	v_add_u32_e32 v161, v158, v146
	v_add_u32_e32 v170, v158, v150
	ds_read_b128 v[166:169], v161
	ds_read_b128 v[170:173], v170
	ds_read_b64_tr_b16 v[174:175], v145 offset:0x2000
	ds_read_b64_tr_b16 v[176:177], v145 offset:0x2800
	ds_read_b64_tr_b16 v[178:179], v145 offset:0x3000
	ds_read_b64_tr_b16 v[180:181], v145 offset:0x3800
	ds_read_b64_tr_b16 v[182:183], v145 offset:0x2200
	ds_read_b64_tr_b16 v[184:185], v145 offset:0x2a00
	ds_read_b64_tr_b16 v[186:187], v145 offset:0x3200
	ds_read_b64_tr_b16 v[188:189], v145 offset:0x3a00
	ds_read_b64_tr_b16 v[190:191], v145 offset:0x2400
	ds_read_b64_tr_b16 v[192:193], v145 offset:0x2c00
	ds_read_b64_tr_b16 v[194:195], v145 offset:0x3400
	ds_read_b64_tr_b16 v[196:197], v145 offset:0x3c00
	ds_read_b64_tr_b16 v[198:199], v145 offset:0x2600
	ds_read_b64_tr_b16 v[200:201], v145 offset:0x2e00
	ds_read_b64_tr_b16 v[202:203], v145 offset:0x3600
	ds_read_b64_tr_b16 v[204:205], v145 offset:0x3e00
	s_setprio 2
	v_exp_f32_e32 v64, v64
	v_exp_f32_e32 v65, v65
	v_exp_f32_e32 v66, v66
	v_exp_f32_e32 v67, v67
	v_exp_f32_e32 v68, v68
	v_exp_f32_e32 v69, v69
	v_add_f32_e32 v145, v65, v64
	v_exp_f32_e32 v70, v70
	v_add_f32_e32 v145, v66, v145
	v_exp_f32_e32 v71, v71
	v_add_f32_e32 v145, v67, v145
	v_exp_f32_e32 v72, v72
	v_add_f32_e32 v145, v68, v145
	v_exp_f32_e32 v73, v73
	v_add_f32_e32 v145, v69, v145
	v_exp_f32_e32 v74, v74
	v_add_f32_e32 v145, v70, v145
	v_exp_f32_e32 v75, v75
	v_add_f32_e32 v145, v71, v145
	v_exp_f32_e32 v76, v76
	v_add_f32_e32 v145, v72, v145
	v_exp_f32_e32 v77, v77
	v_add_f32_e32 v145, v73, v145
	v_exp_f32_e32 v78, v78
	v_add_f32_e32 v145, v74, v145
	v_exp_f32_e32 v79, v79
	v_add_f32_e32 v145, v75, v145
	v_add_f32_e32 v145, v76, v145
	v_add_f32_e32 v145, v77, v145
	v_add_f32_e32 v145, v78, v145
	v_add_f32_e32 v145, v79, v145
	v_add_f32_e32 v161, v144, v145
	v_cvt_pk_bf16_f32 v64, v64, v65
	v_cvt_pk_bf16_f32 v65, v66, v67
	v_cvt_pk_bf16_f32 v66, v68, v69
	v_cvt_pk_bf16_f32 v67, v70, v71
	v_cvt_pk_bf16_f32 v68, v72, v73
	v_cvt_pk_bf16_f32 v69, v74, v75
	v_cvt_pk_bf16_f32 v70, v76, v77
	v_cvt_pk_bf16_f32 v71, v78, v79
	s_waitcnt lgkmcnt(0)
	v_add_u32_e32 v72, v158, v152
	v_add_u32_e32 v73, v158, v153
	ds_read_b128 v[206:209], v72
	ds_read_b128 v[210:213], v73
	v_add_u32_e32 v72, v158, v154
	v_add_u32_e32 v73, v158, v155
	ds_read_b128 v[214:217], v72
	ds_read_b128 v[218:221], v73
	v_add_u32_e32 v72, v158, v156
	v_add_u32_e32 v73, v158, v157
	ds_read_b128 v[222:225], v72
	ds_read_b128 v[226:229], v73
	s_setprio 1
	s_cmp_lt_u32 s33, 0x100
	s_cbranch_scc1 .Lstg_mla_m62_7
	s_waitcnt vmcnt(0)
	s_barrier

; template <int TAG = 0> DI int fresh_tid(int wv) { int l; asm volatile("v_mbcnt_lo_u32_b32 %0, -1, 0\n\tv_mbcnt_hi_u32_b32 %0, -1, %0 ; site %1" : "=v"(l) : "n"(TAG)); return wv * 64 + l; }
; #define SBAR() __builtin_amdgcn_sched_barrier(0)
; DI float swap_sum(float v) { auto rr = __builtin_amdgcn_permlane32_swap(__float_as_uint(v), __float_as_uint(v), false, false); return __uint_as_float(rr[0]) + __uint_as_float(rr[1]); }
; #define ATT_DMA_K(t) do { const bf16_t* kg_ = Kh + (size_t)(t) * 64 * LDK; LAS unsigned char* sb_ = lds + ((t) & 3) * KBUF; \
;     _Pragma("unroll") for (int i_ = 0; i_ < NKP; ++i_) __builtin_amdgcn_global_load_lds((const unsigned*)(kg_ + kgo[i_]), (LAS unsigned*)(sb_ + (wid + 8 * i_) * 1024), 16, 0, 0); } while (0)
; #define ATT_TOP(N) do { asm volatile("s_waitcnt vmcnt(%0)" :: "n"(N) : "memory"); __builtin_amdgcn_s_barrier(); asm volatile("" ::: "memory"); } while (0)
; DI void expsum(f32x16& p, float& l_reg, bf16x8& pa0, bf16x8& pa1) {
; #pragma unroll
;     for (int r = 0; r < 16; ++r) p[r] = __builtin_amdgcn_exp2f(p[r]);
;     float ps = 0.f;
; #pragma unroll
;     for (int r = 0; r < 16; ++r) ps += p[r];
;     l_reg += ps; asm volatile("" : "+v"(l_reg));
;     ...
;     ATT_PK4(p, 0, pa0); ATT_PK4(p, 8, pa1);
;     ...
; }
; template <int DQK, int MODE, int LDQ, int LDK, int LDV> ...
;     ...
;     f32x16 pA, pB; bf16x8 pa0, pa1;
;     int v0 = 0, v1 = 1, v2 = 2;
;     ATT_TOP(NKP + 2);
;     { bf16x8 kf[NDA]; k_reads<DQK, 0, NDA>(kf, lds, 0, r32, hi); ATT_LGKM0(); qk_mma<0, NDA>(pA, kf, qr);
;       if constexpr (ND0 > NDA) { bf16x8 kg[ND0 - NDA]; k_reads<DQK, NDA, ND0>(kg, lds, 0, r32, hi); ATT_LGKM0(); qk_mma<NDA, ND0>(pA, kg, qr); }
;       ATT_BIAS(pA, 0, 0); }
;     if (wid >= 4) __builtin_amdgcn_s_setprio(1);
;     for (int j = 0; j < NT; ++j) {
;         if (j + 2 < NT) ATT_TOP(NKP + 2); else ATT_TOP(0);
;         if (j + 3 < NT) ATT_DMA_K(j + 3);
;         if (j + 2 < NT) ATT_DMA_V(j + 2, v2);
;         ATT_SEG(j); SBAR();
;         ATT_STEP(pA, pB, 0, v0, true, 1, j);
;         ATT_STEP(pB, pA, 1, v0, (j + 1 < NT), 0, j + 1);
;         { const int t_ = v0; v0 = v1; v1 = v2; v2 = t_; }
;     }
;     __builtin_amdgcn_s_setprio(0);
;     ...
;     l_reg = swap_sum(l_reg);
;     { const int lane2 = fresh_tid<110 + MODE>(wv) & 63, r32 = lane2 & 31, hi = lane2 >> 5;
;     if (hi == 0) li_l[r32] = l_reg;
.Lstg_mla_t63_8:
	s_setprio 0
	v_add_u32_e32 v158, s82, v159
	v_add_u32_e32 v132, v158, v151
	v_add_u32_e32 v136, v158, v149
	v_add_u32_e32 v140, v158, v148
	v_add_u32_e32 v144, v158, v147
	ds_read_b128 v[132:135], v132
	ds_read_b128 v[136:139], v136
	ds_read_b128 v[140:143], v140
	ds_read_b128 v[162:165], v144
	v_add_u32_e32 v144, v158, v146
	v_add_u32_e32 v148, v158, v150
	ds_read_b128 v[144:147], v144
	ds_read_b128 v[148:151], v148
	ds_read_b64_tr_b16 v[166:167], v130 offset:0
	ds_read_b64_tr_b16 v[168:169], v130 offset:0x800
	ds_read_b64_tr_b16 v[170:171], v130 offset:0x1000
	ds_read_b64_tr_b16 v[172:173], v130 offset:0x1800
	ds_read_b64_tr_b16 v[174:175], v130 offset:0x200
	ds_read_b64_tr_b16 v[176:177], v130 offset:0xa00
	ds_read_b64_tr_b16 v[178:179], v130 offset:0x1200
	ds_read_b64_tr_b16 v[180:181], v130 offset:0x1a00
	ds_read_b64_tr_b16 v[182:183], v130 offset:0x400
	ds_read_b64_tr_b16 v[184:185], v130 offset:0xc00
	ds_read_b64_tr_b16 v[186:187], v130 offset:0x1400
	ds_read_b64_tr_b16 v[188:189], v130 offset:0x1c00
	ds_read_b64_tr_b16 v[190:191], v130 offset:0x600
	ds_read_b64_tr_b16 v[192:193], v130 offset:0xe00
	ds_read_b64_tr_b16 v[194:195], v130 offset:0x1600
	ds_read_b64_tr_b16 v[196:197], v130 offset:0x1e00
	s_setprio 2
	v_exp_f32_e32 v64, v64
	v_exp_f32_e32 v65, v65
	v_exp_f32_e32 v66, v66
	v_exp_f32_e32 v67, v67
	v_exp_f32_e32 v68, v68
	v_exp_f32_e32 v69, v69
	v_add_f32_e32 v159, v65, v64
	v_exp_f32_e32 v70, v70
	v_add_f32_e32 v159, v66, v159
	v_exp_f32_e32 v71, v71
	v_add_f32_e32 v159, v67, v159
	v_exp_f32_e32 v72, v72
	v_add_f32_e32 v159, v68, v159
	v_exp_f32_e32 v73, v73
	v_add_f32_e32 v159, v69, v159
	v_exp_f32_e32 v74, v74
	v_add_f32_e32 v159, v70, v159
	v_exp_f32_e32 v75, v75
	v_add_f32_e32 v159, v71, v159
	v_exp_f32_e32 v76, v76
	v_add_f32_e32 v159, v72, v159
	v_exp_f32_e32 v77, v77
	v_add_f32_e32 v159, v73, v159
	v_exp_f32_e32 v78, v78
	v_add_f32_e32 v159, v74, v159
	v_exp_f32_e32 v79, v79
	v_add_f32_e32 v159, v75, v159
	v_add_f32_e32 v159, v76, v159
	v_add_f32_e32 v159, v77, v159
	v_add_f32_e32 v159, v78, v159
	v_add_f32_e32 v159, v79, v159
	v_add_f32_e32 v161, v161, v159
	v_cvt_pk_bf16_f32 v64, v64, v65
	v_cvt_pk_bf16_f32 v65, v66, v67
	v_cvt_pk_bf16_f32 v66, v68, v69
	v_cvt_pk_bf16_f32 v67, v70, v71
	v_cvt_pk_bf16_f32 v68, v72, v73
	v_cvt_pk_bf16_f32 v69, v74, v75
	v_cvt_pk_bf16_f32 v70, v76, v77
	v_cvt_pk_bf16_f32 v71, v78, v79
	s_waitcnt lgkmcnt(0)
	v_add_u32_e32 v72, v158, v152
	v_add_u32_e32 v73, v158, v153
	ds_read_b128 v[198:201], v72
	ds_read_b128 v[202:205], v73
	v_add_u32_e32 v72, v158, v154
	v_add_u32_e32 v73, v158, v155
	ds_read_b128 v[152:155], v72
	ds_read_b128 v[206:209], v73
	v_add_u32_e32 v72, v158, v156
	v_add_u32_e32 v73, v158, v157
	ds_read_b128 v[156:159], v72
	ds_read_b128 v[210:213], v73
	s_setprio 1
	v_mfma_f32_32x32x16_bf16 v[48:63], v[64:67], v[166:169], v[48:63]
	v_mfma_f32_32x32x16_bf16 v[32:47], v[64:67], v[174:177], v[32:47]
	v_mfma_f32_32x32x16_bf16 v[16:31], v[64:67], v[182:185], v[16:31]
	v_mfma_f32_32x32x16_bf16 v[0:15], v[64:67], v[190:193], v[0:15]
	v_mfma_f32_32x32x16_bf16 v[48:63], v[68:71], v[170:173], v[48:63]
	v_mfma_f32_32x32x16_bf16 v[32:47], v[68:71], v[178:181], v[32:47]
	v_mfma_f32_32x32x16_bf16 v[16:31], v[68:71], v[186:189], v[16:31]
	v_mfma_f32_32x32x16_bf16 v[0:15], v[68:71], v[194:197], v[0:15]
	s_waitcnt lgkmcnt(0)
	v_mfma_f32_32x32x16_bf16 v[64:79], v[132:135], v[80:83], 0
	v_mfma_f32_32x32x16_bf16 v[64:79], v[136:139], v[84:87], v[64:79]
	v_mfma_f32_32x32x16_bf16 v[64:79], v[140:143], v[88:91], v[64:79]
	v_mfma_f32_32x32x16_bf16 v[64:79], v[162:165], v[92:95], v[64:79]
	v_mfma_f32_32x32x16_bf16 v[64:79], v[144:147], v[96:99], v[64:79]
	v_mfma_f32_32x32x16_bf16 v[64:79], v[148:151], v[100:103], v[64:79]
	s_waitcnt lgkmcnt(0)
	v_mfma_f32_32x32x16_bf16 v[64:79], v[198:201], v[104:107], v[64:79]
	v_mfma_f32_32x32x16_bf16 v[64:79], v[202:205], v[108:111], v[64:79]
	v_mfma_f32_32x32x16_bf16 v[64:79], v[152:155], v[112:115], v[64:79]
	v_mfma_f32_32x32x16_bf16 v[64:79], v[206:209], v[116:119], v[64:79]
	v_mfma_f32_32x32x16_bf16 v[64:79], v[156:159], v[120:123], v[64:79]
	v_mfma_f32_32x32x16_bf16 v[64:79], v[210:213], v[124:127], v[64:79]
	s_setprio 0
	ds_read_b64_tr_b16 v[80:81], v130 offset:0x2000
	ds_read_b64_tr_b16 v[82:83], v130 offset:0x2800
	ds_read_b64_tr_b16 v[84:85], v130 offset:0x3000
	ds_read_b64_tr_b16 v[86:87], v130 offset:0x3800
	ds_read_b64_tr_b16 v[88:89], v130 offset:0x2200
	ds_read_b64_tr_b16 v[90:91], v130 offset:0x2a00
	ds_read_b64_tr_b16 v[92:93], v130 offset:0x3200
	ds_read_b64_tr_b16 v[94:95], v130 offset:0x3a00
	ds_read_b64_tr_b16 v[96:97], v130 offset:0x2400
	ds_read_b64_tr_b16 v[98:99], v130 offset:0x2c00
	ds_read_b64_tr_b16 v[100:101], v130 offset:0x3400
	ds_read_b64_tr_b16 v[102:103], v130 offset:0x3c00
	ds_read_b64_tr_b16 v[104:105], v130 offset:0x2600
	ds_read_b64_tr_b16 v[106:107], v130 offset:0x2e00
	ds_read_b64_tr_b16 v[108:109], v130 offset:0x3600
	ds_read_b64_tr_b16 v[110:111], v130 offset:0x3e00
	s_nop 11
	s_setprio 2
	v_exp_f32_e32 v112, v64
	v_exp_f32_e32 v65, v65
	v_exp_f32_e32 v113, v66
	v_exp_f32_e32 v67, v67
	v_exp_f32_e32 v68, v68
	v_exp_f32_e32 v69, v69
	v_add_f32_e32 v64, v65, v112
	v_exp_f32_e32 v70, v70
	v_add_f32_e32 v64, v113, v64
	v_exp_f32_e32 v71, v71
	v_add_f32_e32 v64, v67, v64
	v_exp_f32_e32 v72, v72
	v_add_f32_e32 v64, v68, v64
	v_exp_f32_e32 v73, v73
	v_add_f32_e32 v64, v69, v64
	v_exp_f32_e32 v74, v74
	v_add_f32_e32 v64, v70, v64
	v_exp_f32_e32 v75, v75
	v_add_f32_e32 v64, v71, v64
	v_exp_f32_e32 v76, v76
	v_add_f32_e32 v64, v72, v64
	v_exp_f32_e32 v77, v77
	v_add_f32_e32 v64, v73, v64
	v_exp_f32_e32 v78, v78
	v_add_f32_e32 v64, v74, v64
	v_exp_f32_e32 v79, v79
	v_add_f32_e32 v64, v75, v64
	v_add_f32_e32 v64, v76, v64
	v_add_f32_e32 v64, v77, v64
	v_add_f32_e32 v64, v78, v64
	v_add_f32_e32 v64, v79, v64
	v_add_f32_e32 v64, v161, v64
	v_cvt_pk_bf16_f32 v66, v112, v65
	v_cvt_pk_bf16_f32 v67, v113, v67
	v_cvt_pk_bf16_f32 v68, v68, v69
	v_cvt_pk_bf16_f32 v69, v70, v71
	v_cvt_pk_bf16_f32 v70, v72, v73
	v_cvt_pk_bf16_f32 v71, v74, v75
	v_cvt_pk_bf16_f32 v72, v76, v77
	v_cvt_pk_bf16_f32 v73, v78, v79
	s_waitcnt lgkmcnt(0)
	s_setprio 1
	v_mfma_f32_32x32x16_bf16 v[48:63], v[66:69], v[80:83], v[48:63]
	v_mfma_f32_32x32x16_bf16 v[32:47], v[66:69], v[88:91], v[32:47]
	v_mfma_f32_32x32x16_bf16 v[16:31], v[66:69], v[96:99], v[16:31]
	v_mfma_f32_32x32x16_bf16 v[0:15], v[66:69], v[104:107], v[0:15]
	v_mfma_f32_32x32x16_bf16 v[48:63], v[70:73], v[84:87], v[48:63]
	v_mfma_f32_32x32x16_bf16 v[32:47], v[70:73], v[92:95], v[32:47]
	v_mfma_f32_32x32x16_bf16 v[16:31], v[70:73], v[100:103], v[16:31]
	v_mfma_f32_32x32x16_bf16 v[0:15], v[70:73], v[108:111], v[0:15]
	s_setprio 0
	v_mbcnt_lo_u32_b32 v66, -1, 0
	v_mbcnt_hi_u32_b32 v66, -1, v66
	v_mov_b32_e32 v67, v64
	v_and_b32_e32 v65, 31, v66
	v_bfe_u32 v66, v66, 5, 1
	v_permlane32_swap_b32_e32 v64, v67
	v_cmp_eq_u32_e32 vcc, 0, v66
	s_and_saveexec_b64 s[2:3], vcc
	s_cbranch_execz .LBB0_1910
; template <int TAG = 0> DI int fresh_tid(int wv) { int l; asm volatile("v_mbcnt_lo_u32_b32 %0, -1, 0\n\tv_mbcnt_hi_u32_b32 %0, -1, %0 ; site %1" : "=v"(l) : "n"(TAG)); return wv * 64 + l; }
; DI float swap_sum(float v) { auto rr = __builtin_amdgcn_permlane32_swap(__float_as_uint(v), __float_as_uint(v), false, false); return __uint_as_float(rr[0]) + __uint_as_float(rr[1]); }
; template <int DQK, int MODE, int LDQ, int LDK, int LDV> ...
;     ...
;     l_reg = swap_sum(l_reg);
;     { const int lane2 = fresh_tid<110 + MODE>(wv) & 63, r32 = lane2 & 31, hi = lane2 >> 5;
;     if (hi == 0) li_l[r32] = l_reg;
	v_lshl_add_u32 v68, v65, 2, s4
	v_add_f32_e32 v64, v64, v67
	ds_write_b32 v68, v64
	s_branch .LBB0_1910
